# v43 + the s_nop 0 hazard pads between s_mov m0 and each LDS-DMA load in all 9 main loops replaced by a moved ds_read_b128 (79 pads)
# speedup vs baseline: 1.0082x; 1.0082x over previous
; #define PG8_STAGE(bufoff, gbase, voff) do { _Pragma("unroll") for (int _i = 0; _i < 2; ++_i) \
;         __builtin_amdgcn_global_load_lds((const unsigned*)((const char*)(gbase) + (voff)[_i]), (LAS unsigned*)(lds + (bufoff) + ldsw + _i * 8192), 16, 0, 0); } while (0)
; #define PG8_LDA(dst, b, h) do { _Pragma("unroll") for (int m = 0; m < 4; ++m) _Pragma("unroll") for (int k = 0; k < 2; ++k) dst[m][k] = *(const LAS bf16x8*)(lds + PG8_SA(b, h) + aoff + m * 2048 + k * 1024); } while (0)
; #define PG8_LDB(dst, b, h) do { _Pragma("unroll") for (int n = 0; n < 2; ++n) _Pragma("unroll") for (int k = 0; k < 2; ++k) dst[n][k] = *(const LAS bf16x8*)(lds + PG8_SB(b, h) + boff + n * 2048 + k * 1024); } while (0)
; #define PG8_MMA(ai, bj, At, Bt) do { __builtin_amdgcn_s_setprio(1); _Pragma("unroll") for (int m = 0; m < 4; ++m) _Pragma("unroll") for (int n = 0; n < 2; ++n) _Pragma("unroll") for (int k = 0; k < 2; ++k) \
;         acc[ai][bj][m][n] = __builtin_amdgcn_mfma_f32_16x16x32_bf16(Bt[n][k], At[m][k], acc[ai][bj][m][n], 0, 0, 0); __builtin_amdgcn_s_setprio(0); } while (0)
; #define PG8_WAIT_V(n) asm volatile("s_waitcnt vmcnt(" #n ")" ::: "memory")
; #define PG8_WAIT_L(n) asm volatile("s_waitcnt lgkmcnt(" #n ")" ::: "memory")
; #define PG8_BAR __builtin_amdgcn_s_barrier()
; #define PG8_SCHED __builtin_amdgcn_sched_barrier(0)
; template <class Epi, class Sched>
; __device__ __forceinline__ void gemm_phase(LAS unsigned char* lds, const Gemm g, const Sched& S, const Epi& E) {
;     ...
;             PG8_LDB(B0, 0, 0); PG8_LDB(B1, 0, 1); PG8_SCHED; PG8_LDA(At, 0, 0); PG8_STAGE(PG8_SA(1, 1), a1 + hsA, voffA);
;             PG8_WAIT_V(8); PG8_WAIT_L(0); PG8_BAR; PG8_MMA(0, 0, At, B0); PG8_MMA(0, 1, At, B1); PG8_BAR; PG8_SCHED;
;             PG8_LDA(At, 0, 1); PG8_STAGE(PG8_SB(0, 0), b2, voffB); PG8_STAGE(PG8_SB(0, 1), b2 + hsB, voffB); PG8_STAGE(PG8_SA(0, 0), a2, voffA);
;             PG8_WAIT_V(8); PG8_WAIT_L(0); PG8_BAR; PG8_MMA(1, 0, At, B0); PG8_MMA(1, 1, At, B1); PG8_BAR; PG8_SCHED;
;             PG8_LDB(B0, 1, 0); PG8_LDB(B1, 1, 1); PG8_SCHED; PG8_LDA(At, 1, 0); PG8_STAGE(PG8_SA(0, 1), a2 + hsA, voffA);
;             PG8_WAIT_V(8); PG8_WAIT_L(0); PG8_BAR; PG8_MMA(0, 0, At, B0); PG8_MMA(0, 1, At, B1); PG8_BAR; PG8_SCHED;
.Lnp_222:
.LBB0_222:
	s_add_i32 s96, s9, 2
	s_add_u32 s20, s0, 0xfffc0080
	s_addc_u32 s21, s1, -1
	s_add_i32 s74, 0, 0x10000
	s_cmp_eq_u32 s82, s9
	s_cselect_b32 s85, s10, s21
	s_cselect_b32 s84, s43, s20
	s_cselect_b32 s39, s45, s8
	s_cselect_b32 s38, vcc_lo, vcc_hi
	s_add_i32 s9, 0, 0x14000
	v_add_u32_e32 v154, s74, v160
	v_add_u32_e32 v174, s9, v160
	ds_read_b128 v[142:145], v154
	ds_read_b128 v[146:149], v154 offset:1024
	ds_read_b128 v[150:153], v154 offset:2048
	ds_read_b128 v[154:157], v154 offset:3072
	ds_read_b128 v[162:165], v174
	ds_read_b128 v[166:169], v174 offset:1024
	ds_read_b128 v[170:173], v174 offset:2048
	ds_read_b128 v[174:177], v174 offset:3072
	s_add_i32 m0, s16, 0xc000
	ds_read_b128 v[178:181], v161
	ds_read_b128 v[182:185], v161 offset:1024
	ds_read_b128 v[186:189], v161 offset:2048
	ds_read_b128 v[208:211], v161 offset:3072
	ds_read_b128 v[212:215], v161 offset:4096
	ds_read_b128 v[216:219], v161 offset:5120
	ds_read_b128 v[220:223], v161 offset:6144
	global_load_lds_dwordx4 v138, s[0:1]
	s_add_i32 m0, s16, 0xe000
	ds_read_b128 v[224:227], v161 offset:7168
	global_load_lds_dwordx4 v140, s[0:1]
	s_waitcnt vmcnt(8)
	s_waitcnt lgkmcnt(0)
	s_barrier
	s_waitcnt lgkmcnt(0)
	v_mfma_f32_16x16x32_bf16 v[122:125], v[142:145], v[178:181], v[122:125]
	v_mfma_f32_16x16x32_bf16 v[114:117], v[150:153], v[178:181], v[114:117]
	v_mfma_f32_16x16x32_bf16 v[106:109], v[142:145], v[186:189], v[106:109]
	v_mfma_f32_16x16x32_bf16 v[98:101], v[150:153], v[186:189], v[98:101]
	v_mfma_f32_16x16x32_bf16 v[90:93], v[142:145], v[212:215], v[90:93]
	v_mfma_f32_16x16x32_bf16 v[82:85], v[150:153], v[212:215], v[82:85]
	v_mfma_f32_16x16x32_bf16 v[74:77], v[142:145], v[220:223], v[74:77]
	v_mfma_f32_16x16x32_bf16 v[66:69], v[150:153], v[220:223], v[66:69]
	v_mfma_f32_16x16x32_bf16 v[122:125], v[146:149], v[182:185], v[122:125]
	v_mfma_f32_16x16x32_bf16 v[114:117], v[154:157], v[182:185], v[114:117]
	v_mfma_f32_16x16x32_bf16 v[106:109], v[146:149], v[208:211], v[106:109]
	v_mfma_f32_16x16x32_bf16 v[98:101], v[154:157], v[208:211], v[98:101]
	v_mfma_f32_16x16x32_bf16 v[90:93], v[146:149], v[216:219], v[90:93]
	v_mfma_f32_16x16x32_bf16 v[82:85], v[154:157], v[216:219], v[82:85]
	v_mfma_f32_16x16x32_bf16 v[74:77], v[146:149], v[224:227], v[74:77]
	v_mfma_f32_16x16x32_bf16 v[66:69], v[154:157], v[224:227], v[66:69]
	v_mfma_f32_16x16x32_bf16 v[126:129], v[162:165], v[178:181], v[126:129]
	v_mfma_f32_16x16x32_bf16 v[118:121], v[170:173], v[178:181], v[118:121]
	v_mfma_f32_16x16x32_bf16 v[110:113], v[162:165], v[186:189], v[110:113]
	v_mfma_f32_16x16x32_bf16 v[102:105], v[170:173], v[186:189], v[102:105]
	v_mfma_f32_16x16x32_bf16 v[94:97], v[162:165], v[212:215], v[94:97]
	v_mfma_f32_16x16x32_bf16 v[86:89], v[170:173], v[212:215], v[86:89]
	v_mfma_f32_16x16x32_bf16 v[78:81], v[162:165], v[220:223], v[78:81]
	v_mfma_f32_16x16x32_bf16 v[70:73], v[170:173], v[220:223], v[70:73]
	v_mfma_f32_16x16x32_bf16 v[126:129], v[166:169], v[182:185], v[126:129]
	v_mfma_f32_16x16x32_bf16 v[118:121], v[174:177], v[182:185], v[118:121]
	v_mfma_f32_16x16x32_bf16 v[110:113], v[166:169], v[208:211], v[110:113]
	v_mfma_f32_16x16x32_bf16 v[102:105], v[174:177], v[208:211], v[102:105]
	v_mfma_f32_16x16x32_bf16 v[94:97], v[166:169], v[216:219], v[94:97]
	v_mfma_f32_16x16x32_bf16 v[86:89], v[174:177], v[216:219], v[86:89]
	v_mfma_f32_16x16x32_bf16 v[78:81], v[166:169], v[224:227], v[78:81]
	v_mfma_f32_16x16x32_bf16 v[70:73], v[174:177], v[224:227], v[70:73]
	s_barrier
	s_add_i32 s20, s74, s12
	s_mov_b32 m0, s20
	ds_read_b128 v[178:181], v161 offset:16384
	ds_read_b128 v[182:185], v161 offset:17408
	ds_read_b128 v[186:189], v161 offset:18432
	ds_read_b128 v[208:211], v161 offset:19456
	global_load_lds_dwordx4 v0, s[38:39]
	s_add_i32 m0, s20, 0x2000
	s_add_u32 s20, s38, 0x40000
	s_addc_u32 s21, s39, 0
	s_add_i32 s9, s9, s12
	global_load_lds_dwordx4 v130, s[38:39]
	s_mov_b32 m0, s9
	ds_read_b128 v[212:215], v161 offset:20480
	global_load_lds_dwordx4 v0, s[20:21]
	s_add_i32 m0, s9, 0x2000
	ds_read_b128 v[216:219], v161 offset:21504
	global_load_lds_dwordx4 v130, s[20:21]
	s_mov_b32 m0, s16
	ds_read_b128 v[220:223], v161 offset:22528
	global_load_lds_dwordx4 v134, s[84:85]
	s_mov_b32 m0, s30
	ds_read_b128 v[224:227], v161 offset:23552
	global_load_lds_dwordx4 v132, s[84:85]
	s_waitcnt vmcnt(8)
	s_waitcnt lgkmcnt(0)
	s_barrier
	s_waitcnt lgkmcnt(0)
	v_mfma_f32_16x16x32_bf16 v[58:61], v[142:145], v[178:181], v[58:61]
	v_mfma_f32_16x16x32_bf16 v[50:53], v[150:153], v[178:181], v[50:53]
	v_mfma_f32_16x16x32_bf16 v[42:45], v[142:145], v[186:189], v[42:45]
	v_mfma_f32_16x16x32_bf16 v[34:37], v[150:153], v[186:189], v[34:37]
	v_mfma_f32_16x16x32_bf16 v[26:29], v[142:145], v[212:215], v[26:29]
	v_mfma_f32_16x16x32_bf16 v[18:21], v[150:153], v[212:215], v[18:21]
	v_mfma_f32_16x16x32_bf16 v[10:13], v[142:145], v[220:223], v[10:13]
	v_mfma_f32_16x16x32_bf16 v[2:5], v[150:153], v[220:223], v[2:5]
	v_mfma_f32_16x16x32_bf16 v[58:61], v[146:149], v[182:185], v[58:61]
	v_mfma_f32_16x16x32_bf16 v[50:53], v[154:157], v[182:185], v[50:53]
	v_mfma_f32_16x16x32_bf16 v[42:45], v[146:149], v[208:211], v[42:45]
	v_mfma_f32_16x16x32_bf16 v[34:37], v[154:157], v[208:211], v[34:37]
	v_mfma_f32_16x16x32_bf16 v[26:29], v[146:149], v[216:219], v[26:29]
	v_mfma_f32_16x16x32_bf16 v[18:21], v[154:157], v[216:219], v[18:21]
	v_mfma_f32_16x16x32_bf16 v[10:13], v[146:149], v[224:227], v[10:13]
	v_mfma_f32_16x16x32_bf16 v[2:5], v[154:157], v[224:227], v[2:5]
	v_mfma_f32_16x16x32_bf16 v[62:65], v[162:165], v[178:181], v[62:65]
	v_mfma_f32_16x16x32_bf16 v[54:57], v[170:173], v[178:181], v[54:57]
	v_mfma_f32_16x16x32_bf16 v[46:49], v[162:165], v[186:189], v[46:49]
	v_mfma_f32_16x16x32_bf16 v[38:41], v[170:173], v[186:189], v[38:41]
	v_mfma_f32_16x16x32_bf16 v[30:33], v[162:165], v[212:215], v[30:33]
	v_mfma_f32_16x16x32_bf16 v[22:25], v[170:173], v[212:215], v[22:25]
	v_mfma_f32_16x16x32_bf16 v[14:17], v[162:165], v[220:223], v[14:17]
	v_mfma_f32_16x16x32_bf16 v[6:9], v[170:173], v[220:223], v[6:9]
	v_mfma_f32_16x16x32_bf16 v[62:65], v[166:169], v[182:185], v[62:65]
	v_mfma_f32_16x16x32_bf16 v[54:57], v[174:177], v[182:185], v[54:57]
	v_mfma_f32_16x16x32_bf16 v[46:49], v[166:169], v[208:211], v[46:49]
	v_mfma_f32_16x16x32_bf16 v[38:41], v[174:177], v[208:211], v[38:41]
	v_mfma_f32_16x16x32_bf16 v[30:33], v[166:169], v[216:219], v[30:33]
	v_mfma_f32_16x16x32_bf16 v[22:25], v[174:177], v[216:219], v[22:25]
	v_mfma_f32_16x16x32_bf16 v[14:17], v[166:169], v[224:227], v[14:17]
	v_mfma_f32_16x16x32_bf16 v[6:9], v[174:177], v[224:227], v[6:9]
	s_barrier
; #define PG8_STAGE(bufoff, gbase, voff) do { _Pragma("unroll") for (int _i = 0; _i < 2; ++_i) \
;         __builtin_amdgcn_global_load_lds((const unsigned*)((const char*)(gbase) + (voff)[_i]), (LAS unsigned*)(lds + (bufoff) + ldsw + _i * 8192), 16, 0, 0); } while (0)
; #define PG8_LDA(dst, b, h) do { _Pragma("unroll") for (int m = 0; m < 4; ++m) _Pragma("unroll") for (int k = 0; k < 2; ++k) dst[m][k] = *(const LAS bf16x8*)(lds + PG8_SA(b, h) + aoff + m * 2048 + k * 1024); } while (0)
; #define PG8_LDB(dst, b, h) do { _Pragma("unroll") for (int n = 0; n < 2; ++n) _Pragma("unroll") for (int k = 0; k < 2; ++k) dst[n][k] = *(const LAS bf16x8*)(lds + PG8_SB(b, h) + boff + n * 2048 + k * 1024); } while (0)
; #define PG8_MMA(ai, bj, At, Bt) do { __builtin_amdgcn_s_setprio(1); _Pragma("unroll") for (int m = 0; m < 4; ++m) _Pragma("unroll") for (int n = 0; n < 2; ++n) _Pragma("unroll") for (int k = 0; k < 2; ++k) \
;         acc[ai][bj][m][n] = __builtin_amdgcn_mfma_f32_16x16x32_bf16(Bt[n][k], At[m][k], acc[ai][bj][m][n], 0, 0, 0); __builtin_amdgcn_s_setprio(0); } while (0)
; #define PG8_WAIT_V(n) asm volatile("s_waitcnt vmcnt(" #n ")" ::: "memory")
; #define PG8_WAIT_L(n) asm volatile("s_waitcnt lgkmcnt(" #n ")" ::: "memory")
; #define PG8_BAR __builtin_amdgcn_s_barrier()
; #define PG8_SCHED __builtin_amdgcn_sched_barrier(0)
; template <class Epi, class Sched>
; __device__ __forceinline__ void gemm_phase(LAS unsigned char* lds, const Gemm g, const Sched& S, const Epi& E) {
;     ...
;             PG8_LDB(B0, 1, 0); PG8_LDB(B1, 1, 1); PG8_SCHED; PG8_LDA(At, 1, 0); PG8_STAGE(PG8_SA(0, 1), a2 + hsA, voffA);
;             PG8_WAIT_V(8); PG8_WAIT_L(0); PG8_BAR; PG8_MMA(0, 0, At, B0); PG8_MMA(0, 1, At, B1); PG8_BAR; PG8_SCHED;
;             PG8_LDA(At, 1, 1); PG8_STAGE(PG8_SB(1, 0), b3, voffB); PG8_STAGE(PG8_SB(1, 1), b3 + hsB, voffB); PG8_STAGE(PG8_SA(1, 0), a3, voffA);
;             PG8_WAIT_V(8); PG8_WAIT_L(0); PG8_BAR; PG8_MMA(1, 0, At, B0); PG8_MMA(1, 1, At, B1); PG8_BAR; PG8_SCHED;
;         }
;         if (wr == 0) PG8_BAR;
	s_add_i32 s9, 0, 0x18000
	s_add_i32 s74, 0, 0x1c000
	v_add_u32_e32 v154, s9, v160
	v_add_u32_e32 v174, s74, v160
	ds_read_b128 v[142:145], v154
	ds_read_b128 v[146:149], v154 offset:1024
	ds_read_b128 v[150:153], v154 offset:2048
	ds_read_b128 v[154:157], v154 offset:3072
	ds_read_b128 v[162:165], v174
	ds_read_b128 v[166:169], v174 offset:1024
	ds_read_b128 v[170:173], v174 offset:2048
	ds_read_b128 v[174:177], v174 offset:3072
	s_add_u32 s20, s84, 0x40000
	s_addc_u32 s21, s85, 0
	s_mov_b32 m0, s52
	ds_read_b128 v[178:181], v161 offset:32768
	ds_read_b128 v[182:185], v161 offset:33792
	ds_read_b128 v[186:189], v161 offset:34816
	ds_read_b128 v[208:211], v161 offset:35840
	ds_read_b128 v[212:215], v161 offset:36864
	ds_read_b128 v[216:219], v161 offset:37888
	ds_read_b128 v[220:223], v161 offset:38912
	global_load_lds_dwordx4 v134, s[20:21]
	s_mov_b32 m0, s56
	ds_read_b128 v[224:227], v161 offset:39936
	global_load_lds_dwordx4 v132, s[20:21]
	s_waitcnt vmcnt(8)
	s_waitcnt lgkmcnt(0)
	s_barrier
	s_waitcnt lgkmcnt(0)
	v_mfma_f32_16x16x32_bf16 v[122:125], v[142:145], v[178:181], v[122:125]
	v_mfma_f32_16x16x32_bf16 v[114:117], v[150:153], v[178:181], v[114:117]
	v_mfma_f32_16x16x32_bf16 v[106:109], v[142:145], v[186:189], v[106:109]
	v_mfma_f32_16x16x32_bf16 v[98:101], v[150:153], v[186:189], v[98:101]
	v_mfma_f32_16x16x32_bf16 v[90:93], v[142:145], v[212:215], v[90:93]
	v_mfma_f32_16x16x32_bf16 v[82:85], v[150:153], v[212:215], v[82:85]
	v_mfma_f32_16x16x32_bf16 v[74:77], v[142:145], v[220:223], v[74:77]
	v_mfma_f32_16x16x32_bf16 v[66:69], v[150:153], v[220:223], v[66:69]
	v_mfma_f32_16x16x32_bf16 v[122:125], v[146:149], v[182:185], v[122:125]
	v_mfma_f32_16x16x32_bf16 v[114:117], v[154:157], v[182:185], v[114:117]
	v_mfma_f32_16x16x32_bf16 v[106:109], v[146:149], v[208:211], v[106:109]
	v_mfma_f32_16x16x32_bf16 v[98:101], v[154:157], v[208:211], v[98:101]
	v_mfma_f32_16x16x32_bf16 v[90:93], v[146:149], v[216:219], v[90:93]
	v_mfma_f32_16x16x32_bf16 v[82:85], v[154:157], v[216:219], v[82:85]
	v_mfma_f32_16x16x32_bf16 v[74:77], v[146:149], v[224:227], v[74:77]
	v_mfma_f32_16x16x32_bf16 v[66:69], v[154:157], v[224:227], v[66:69]
	v_mfma_f32_16x16x32_bf16 v[126:129], v[162:165], v[178:181], v[126:129]
	v_mfma_f32_16x16x32_bf16 v[118:121], v[170:173], v[178:181], v[118:121]
	v_mfma_f32_16x16x32_bf16 v[110:113], v[162:165], v[186:189], v[110:113]
	v_mfma_f32_16x16x32_bf16 v[102:105], v[170:173], v[186:189], v[102:105]
	v_mfma_f32_16x16x32_bf16 v[94:97], v[162:165], v[212:215], v[94:97]
	v_mfma_f32_16x16x32_bf16 v[86:89], v[170:173], v[212:215], v[86:89]
	v_mfma_f32_16x16x32_bf16 v[78:81], v[162:165], v[220:223], v[78:81]
	v_mfma_f32_16x16x32_bf16 v[70:73], v[170:173], v[220:223], v[70:73]
	v_mfma_f32_16x16x32_bf16 v[126:129], v[166:169], v[182:185], v[126:129]
	v_mfma_f32_16x16x32_bf16 v[118:121], v[174:177], v[182:185], v[118:121]
	v_mfma_f32_16x16x32_bf16 v[110:113], v[166:169], v[208:211], v[110:113]
	v_mfma_f32_16x16x32_bf16 v[102:105], v[174:177], v[208:211], v[102:105]
	v_mfma_f32_16x16x32_bf16 v[94:97], v[166:169], v[216:219], v[94:97]
	v_mfma_f32_16x16x32_bf16 v[86:89], v[174:177], v[216:219], v[86:89]
	v_mfma_f32_16x16x32_bf16 v[78:81], v[166:169], v[224:227], v[78:81]
	v_mfma_f32_16x16x32_bf16 v[70:73], v[174:177], v[224:227], v[70:73]
	s_barrier
	s_add_i32 s9, s9, s12
	s_mov_b32 m0, s9
	s_add_u32 s20, s38, 0x80
	s_addc_u32 s21, s39, 0
	ds_read_b128 v[178:181], v161 offset:49152
	ds_read_b128 v[182:185], v161 offset:50176
	ds_read_b128 v[186:189], v161 offset:51200
	ds_read_b128 v[208:211], v161 offset:52224
	global_load_lds_dwordx4 v0, s[20:21]
	s_add_i32 m0, s9, 0x2000
	s_add_i32 s9, s74, s12
	global_load_lds_dwordx4 v130, s[20:21]
	s_add_u32 s20, s20, 0x40000
	s_addc_u32 s21, s21, 0
	s_mov_b32 m0, s9
	ds_read_b128 v[212:215], v161 offset:53248
	global_load_lds_dwordx4 v0, s[20:21]
	s_add_i32 m0, s9, 0x2000
	ds_read_b128 v[216:219], v161 offset:54272
	global_load_lds_dwordx4 v130, s[20:21]
	s_add_u32 s20, s84, 0x80
	s_addc_u32 s21, s85, 0
	s_mov_b32 m0, s78
	ds_read_b128 v[220:223], v161 offset:55296
	global_load_lds_dwordx4 v134, s[20:21]
	s_mov_b32 m0, s80
	ds_read_b128 v[224:227], v161 offset:56320
	global_load_lds_dwordx4 v132, s[20:21]
	s_waitcnt vmcnt(8)
	s_waitcnt lgkmcnt(0)
	s_barrier
	s_waitcnt lgkmcnt(0)
	v_mfma_f32_16x16x32_bf16 v[58:61], v[142:145], v[178:181], v[58:61]
	v_mfma_f32_16x16x32_bf16 v[50:53], v[150:153], v[178:181], v[50:53]
	v_mfma_f32_16x16x32_bf16 v[42:45], v[142:145], v[186:189], v[42:45]
	v_mfma_f32_16x16x32_bf16 v[34:37], v[150:153], v[186:189], v[34:37]
	v_mfma_f32_16x16x32_bf16 v[26:29], v[142:145], v[212:215], v[26:29]
	v_mfma_f32_16x16x32_bf16 v[18:21], v[150:153], v[212:215], v[18:21]
	v_mfma_f32_16x16x32_bf16 v[10:13], v[142:145], v[220:223], v[10:13]
	v_mfma_f32_16x16x32_bf16 v[2:5], v[150:153], v[220:223], v[2:5]
	v_mfma_f32_16x16x32_bf16 v[58:61], v[146:149], v[182:185], v[58:61]
	v_mfma_f32_16x16x32_bf16 v[50:53], v[154:157], v[182:185], v[50:53]
	v_mfma_f32_16x16x32_bf16 v[42:45], v[146:149], v[208:211], v[42:45]
	v_mfma_f32_16x16x32_bf16 v[34:37], v[154:157], v[208:211], v[34:37]
	v_mfma_f32_16x16x32_bf16 v[26:29], v[146:149], v[216:219], v[26:29]
	v_mfma_f32_16x16x32_bf16 v[18:21], v[154:157], v[216:219], v[18:21]
	v_mfma_f32_16x16x32_bf16 v[10:13], v[146:149], v[224:227], v[10:13]
	v_mfma_f32_16x16x32_bf16 v[2:5], v[154:157], v[224:227], v[2:5]
	v_mfma_f32_16x16x32_bf16 v[62:65], v[162:165], v[178:181], v[62:65]
	v_mfma_f32_16x16x32_bf16 v[54:57], v[170:173], v[178:181], v[54:57]
	v_mfma_f32_16x16x32_bf16 v[46:49], v[162:165], v[186:189], v[46:49]
	v_mfma_f32_16x16x32_bf16 v[38:41], v[170:173], v[186:189], v[38:41]
	v_mfma_f32_16x16x32_bf16 v[30:33], v[162:165], v[212:215], v[30:33]
	v_mfma_f32_16x16x32_bf16 v[22:25], v[170:173], v[212:215], v[22:25]
	v_mfma_f32_16x16x32_bf16 v[14:17], v[162:165], v[220:223], v[14:17]
	v_mfma_f32_16x16x32_bf16 v[6:9], v[170:173], v[220:223], v[6:9]
	v_mfma_f32_16x16x32_bf16 v[62:65], v[166:169], v[182:185], v[62:65]
	v_mfma_f32_16x16x32_bf16 v[54:57], v[174:177], v[182:185], v[54:57]
	v_mfma_f32_16x16x32_bf16 v[46:49], v[166:169], v[208:211], v[46:49]
	v_mfma_f32_16x16x32_bf16 v[38:41], v[174:177], v[208:211], v[38:41]
	v_mfma_f32_16x16x32_bf16 v[30:33], v[166:169], v[216:219], v[30:33]
	v_mfma_f32_16x16x32_bf16 v[22:25], v[174:177], v[216:219], v[22:25]
	v_mfma_f32_16x16x32_bf16 v[14:17], v[166:169], v[224:227], v[14:17]
	v_mfma_f32_16x16x32_bf16 v[6:9], v[174:177], v[224:227], v[6:9]
	s_barrier
	s_add_u32 s0, s0, 0x100
	s_addc_u32 s1, s1, 0
	s_add_u32 vcc_hi, vcc_hi, 0x100
	s_addc_u32 s8, s8, 0
	s_cmp_ge_i32 s96, s57
	s_mov_b32 s9, s96
	s_cbranch_scc0 .LBB0_222
	s_setprio 0
	v_readlane_b32 s96, v250, 43
	s_mov_b64 s[74:75], s[22:23]

; #define PG8_STAGE(bufoff, gbase, voff) do { _Pragma("unroll") for (int _i = 0; _i < 2; ++_i) \
;         __builtin_amdgcn_global_load_lds((const unsigned*)((const char*)(gbase) + (voff)[_i]), (LAS unsigned*)(lds + (bufoff) + ldsw + _i * 8192), 16, 0, 0); } while (0)
; #define PG8_LDA(dst, b, h) do { _Pragma("unroll") for (int m = 0; m < 4; ++m) _Pragma("unroll") for (int k = 0; k < 2; ++k) dst[m][k] = *(const LAS bf16x8*)(lds + PG8_SA(b, h) + aoff + m * 2048 + k * 1024); } while (0)
; #define PG8_LDB(dst, b, h) do { _Pragma("unroll") for (int n = 0; n < 2; ++n) _Pragma("unroll") for (int k = 0; k < 2; ++k) dst[n][k] = *(const LAS bf16x8*)(lds + PG8_SB(b, h) + boff + n * 2048 + k * 1024); } while (0)
; #define PG8_MMA(ai, bj, At, Bt) do { __builtin_amdgcn_s_setprio(1); _Pragma("unroll") for (int m = 0; m < 4; ++m) _Pragma("unroll") for (int n = 0; n < 2; ++n) _Pragma("unroll") for (int k = 0; k < 2; ++k) \
;         acc[ai][bj][m][n] = __builtin_amdgcn_mfma_f32_16x16x32_bf16(Bt[n][k], At[m][k], acc[ai][bj][m][n], 0, 0, 0); __builtin_amdgcn_s_setprio(0); } while (0)
; #define PG8_WAIT_V(n) asm volatile("s_waitcnt vmcnt(" #n ")" ::: "memory")
; #define PG8_WAIT_L(n) asm volatile("s_waitcnt lgkmcnt(" #n ")" ::: "memory")
; #define PG8_BAR __builtin_amdgcn_s_barrier()
; #define PG8_SCHED __builtin_amdgcn_sched_barrier(0)
; template <class Epi, class Sched>
; __device__ __forceinline__ void gemm_phase(LAS unsigned char* lds, const Gemm g, const Sched& S, const Epi& E) {
;     ...
;             PG8_LDB(B0, 0, 0); PG8_LDB(B1, 0, 1); PG8_SCHED; PG8_LDA(At, 0, 0); PG8_STAGE(PG8_SA(1, 1), a1 + hsA, voffA);
;             PG8_WAIT_V(8); PG8_WAIT_L(0); PG8_BAR; PG8_MMA(0, 0, At, B0); PG8_MMA(0, 1, At, B1); PG8_BAR; PG8_SCHED;
;             PG8_LDA(At, 0, 1); PG8_STAGE(PG8_SB(0, 0), b2, voffB); PG8_STAGE(PG8_SB(0, 1), b2 + hsB, voffB); PG8_STAGE(PG8_SA(0, 0), a2, voffA);
;             PG8_WAIT_V(8); PG8_WAIT_L(0); PG8_BAR; PG8_MMA(1, 0, At, B0); PG8_MMA(1, 1, At, B1); PG8_BAR; PG8_SCHED;
.Lnp_298:
.LBB0_298:
	s_add_i32 s96, s38, 2
	s_add_u32 s20, s8, 0x100
	s_addc_u32 s21, s9, 0
	s_add_i32 s74, 0, 0x10000
	s_cmp_eq_u32 s26, s38
	s_cselect_b32 s41, s43, s21
	s_cselect_b32 s40, s73, s20
	s_cselect_b32 s39, s82, s85
	s_cselect_b32 s38, s83, s84
	s_add_i32 s75, 0, 0x14000
	v_add_u32_e32 v152, s74, v206
	v_add_u32_e32 v168, s75, v206
	ds_read_b128 v[140:143], v152
	ds_read_b128 v[144:147], v152 offset:1024
	ds_read_b128 v[148:151], v152 offset:2048
	ds_read_b128 v[152:155], v152 offset:3072
	ds_read_b128 v[156:159], v168
	ds_read_b128 v[160:163], v168 offset:1024
	ds_read_b128 v[164:167], v168 offset:2048
	ds_read_b128 v[168:171], v168 offset:3072
	v_lshl_add_u64 v[208:209], s[8:9], 0, v[136:137]
	s_add_i32 m0, s30, 0xc000
	ds_read_b128 v[172:175], v210
	ds_read_b128 v[176:179], v210 offset:1024
	ds_read_b128 v[180:183], v210 offset:2048
	ds_read_b128 v[184:187], v210 offset:3072
	ds_read_b128 v[188:191], v210 offset:4096
	ds_read_b128 v[212:215], v210 offset:5120
	ds_read_b128 v[216:219], v210 offset:6144
	global_load_lds_dwordx4 v[208:209], off
	v_lshl_add_u64 v[208:209], s[8:9], 0, v[138:139]
	s_add_i32 m0, s30, 0xe000
	ds_read_b128 v[220:223], v210 offset:7168
	global_load_lds_dwordx4 v[208:209], off
	s_waitcnt vmcnt(8)
	s_waitcnt lgkmcnt(0)
	s_barrier
	s_waitcnt lgkmcnt(0)
	v_mfma_f32_16x16x32_bf16 v[126:129], v[140:143], v[172:175], v[126:129]
	v_mfma_f32_16x16x32_bf16 v[122:125], v[148:151], v[172:175], v[122:125]
	v_mfma_f32_16x16x32_bf16 v[118:121], v[140:143], v[180:183], v[118:121]
	v_mfma_f32_16x16x32_bf16 v[114:117], v[148:151], v[180:183], v[114:117]
	v_mfma_f32_16x16x32_bf16 v[106:109], v[140:143], v[188:191], v[106:109]
	v_mfma_f32_16x16x32_bf16 v[98:101], v[148:151], v[188:191], v[98:101]
	v_mfma_f32_16x16x32_bf16 v[90:93], v[140:143], v[216:219], v[90:93]
	v_mfma_f32_16x16x32_bf16 v[82:85], v[148:151], v[216:219], v[82:85]
	v_mfma_f32_16x16x32_bf16 v[126:129], v[144:147], v[176:179], v[126:129]
	v_mfma_f32_16x16x32_bf16 v[122:125], v[152:155], v[176:179], v[122:125]
	v_mfma_f32_16x16x32_bf16 v[118:121], v[144:147], v[184:187], v[118:121]
	v_mfma_f32_16x16x32_bf16 v[114:117], v[152:155], v[184:187], v[114:117]
	v_mfma_f32_16x16x32_bf16 v[106:109], v[144:147], v[212:215], v[106:109]
	v_mfma_f32_16x16x32_bf16 v[98:101], v[152:155], v[212:215], v[98:101]
	v_mfma_f32_16x16x32_bf16 v[90:93], v[144:147], v[220:223], v[90:93]
	v_mfma_f32_16x16x32_bf16 v[82:85], v[152:155], v[220:223], v[82:85]
	v_mfma_f32_16x16x32_bf16 v[110:113], v[156:159], v[172:175], v[110:113]
	v_mfma_f32_16x16x32_bf16 v[102:105], v[164:167], v[172:175], v[102:105]
	v_mfma_f32_16x16x32_bf16 v[94:97], v[156:159], v[180:183], v[94:97]
	v_mfma_f32_16x16x32_bf16 v[86:89], v[164:167], v[180:183], v[86:89]
	v_mfma_f32_16x16x32_bf16 v[78:81], v[156:159], v[188:191], v[78:81]
	v_mfma_f32_16x16x32_bf16 v[74:77], v[164:167], v[188:191], v[74:77]
	v_mfma_f32_16x16x32_bf16 v[70:73], v[156:159], v[216:219], v[70:73]
	v_mfma_f32_16x16x32_bf16 v[66:69], v[164:167], v[216:219], v[66:69]
	v_mfma_f32_16x16x32_bf16 v[110:113], v[160:163], v[176:179], v[110:113]
	v_mfma_f32_16x16x32_bf16 v[102:105], v[168:171], v[176:179], v[102:105]
	v_mfma_f32_16x16x32_bf16 v[94:97], v[160:163], v[184:187], v[94:97]
	v_mfma_f32_16x16x32_bf16 v[86:89], v[168:171], v[184:187], v[86:89]
	v_mfma_f32_16x16x32_bf16 v[78:81], v[160:163], v[212:215], v[78:81]
	v_mfma_f32_16x16x32_bf16 v[74:77], v[168:171], v[212:215], v[74:77]
	v_mfma_f32_16x16x32_bf16 v[70:73], v[160:163], v[220:223], v[70:73]
	v_mfma_f32_16x16x32_bf16 v[66:69], v[168:171], v[220:223], v[66:69]
	s_barrier
	s_add_i32 s8, s74, s24
	v_lshl_add_u64 v[208:209], s[38:39], 0, v[0:1]
	s_mov_b32 m0, s8
	ds_read_b128 v[172:175], v210 offset:16384
	ds_read_b128 v[176:179], v210 offset:17408
	ds_read_b128 v[180:183], v210 offset:18432
	ds_read_b128 v[184:187], v210 offset:19456
	ds_read_b128 v[188:191], v210 offset:20480
	global_load_lds_dwordx4 v[208:209], off
	s_add_i32 m0, s8, 0x2000
	s_add_u32 s8, s38, 0xb0000
	v_lshl_add_u64 v[224:225], s[38:39], 0, v[130:131]
	s_addc_u32 s9, s39, 0
	s_add_i32 s74, s75, s24
	global_load_lds_dwordx4 v[224:225], off
	v_lshl_add_u64 v[226:227], s[8:9], 0, v[0:1]
	s_mov_b32 m0, s74
	v_lshl_add_u64 v[228:229], s[40:41], 0, v[132:133]
	global_load_lds_dwordx4 v[226:227], off
	v_lshl_add_u64 v[226:227], s[8:9], 0, v[130:131]
	s_add_i32 m0, s74, 0x2000
	ds_read_b128 v[212:215], v210 offset:21504
	global_load_lds_dwordx4 v[226:227], off
	v_lshl_add_u64 v[226:227], s[40:41], 0, v[134:135]
	s_mov_b32 m0, s30
	ds_read_b128 v[216:219], v210 offset:22528
	global_load_lds_dwordx4 v[226:227], off
	s_mov_b32 m0, s52
	ds_read_b128 v[220:223], v210 offset:23552
	global_load_lds_dwordx4 v[228:229], off
	s_waitcnt vmcnt(8)
	s_waitcnt lgkmcnt(0)
	s_barrier
; #define PG8_STAGE(bufoff, gbase, voff) do { _Pragma("unroll") for (int _i = 0; _i < 2; ++_i) \
;         __builtin_amdgcn_global_load_lds((const unsigned*)((const char*)(gbase) + (voff)[_i]), (LAS unsigned*)(lds + (bufoff) + ldsw + _i * 8192), 16, 0, 0); } while (0)
; #define PG8_LDA(dst, b, h) do { _Pragma("unroll") for (int m = 0; m < 4; ++m) _Pragma("unroll") for (int k = 0; k < 2; ++k) dst[m][k] = *(const LAS bf16x8*)(lds + PG8_SA(b, h) + aoff + m * 2048 + k * 1024); } while (0)
; #define PG8_LDB(dst, b, h) do { _Pragma("unroll") for (int n = 0; n < 2; ++n) _Pragma("unroll") for (int k = 0; k < 2; ++k) dst[n][k] = *(const LAS bf16x8*)(lds + PG8_SB(b, h) + boff + n * 2048 + k * 1024); } while (0)
; #define PG8_MMA(ai, bj, At, Bt) do { __builtin_amdgcn_s_setprio(1); _Pragma("unroll") for (int m = 0; m < 4; ++m) _Pragma("unroll") for (int n = 0; n < 2; ++n) _Pragma("unroll") for (int k = 0; k < 2; ++k) \
;         acc[ai][bj][m][n] = __builtin_amdgcn_mfma_f32_16x16x32_bf16(Bt[n][k], At[m][k], acc[ai][bj][m][n], 0, 0, 0); __builtin_amdgcn_s_setprio(0); } while (0)
; #define PG8_WAIT_V(n) asm volatile("s_waitcnt vmcnt(" #n ")" ::: "memory")
; #define PG8_WAIT_L(n) asm volatile("s_waitcnt lgkmcnt(" #n ")" ::: "memory")
; #define PG8_BAR __builtin_amdgcn_s_barrier()
; #define PG8_SCHED __builtin_amdgcn_sched_barrier(0)
; template <class Epi, class Sched>
; __device__ __forceinline__ void gemm_phase(LAS unsigned char* lds, const Gemm g, const Sched& S, const Epi& E) {
;     ...
;             PG8_WAIT_V(8); PG8_WAIT_L(0); PG8_BAR; PG8_MMA(1, 0, At, B0); PG8_MMA(1, 1, At, B1); PG8_BAR; PG8_SCHED;
;             PG8_LDB(B0, 1, 0); PG8_LDB(B1, 1, 1); PG8_SCHED; PG8_LDA(At, 1, 0); PG8_STAGE(PG8_SA(0, 1), a2 + hsA, voffA);
;             PG8_WAIT_V(8); PG8_WAIT_L(0); PG8_BAR; PG8_MMA(0, 0, At, B0); PG8_MMA(0, 1, At, B1); PG8_BAR; PG8_SCHED;
	s_waitcnt lgkmcnt(0)
	v_mfma_f32_16x16x32_bf16 v[62:65], v[140:143], v[172:175], v[62:65]
	v_mfma_f32_16x16x32_bf16 v[58:61], v[148:151], v[172:175], v[58:61]
	v_mfma_f32_16x16x32_bf16 v[54:57], v[140:143], v[180:183], v[54:57]
	v_mfma_f32_16x16x32_bf16 v[50:53], v[148:151], v[180:183], v[50:53]
	v_mfma_f32_16x16x32_bf16 v[42:45], v[140:143], v[188:191], v[42:45]
	v_mfma_f32_16x16x32_bf16 v[34:37], v[148:151], v[188:191], v[34:37]
	v_mfma_f32_16x16x32_bf16 v[26:29], v[140:143], v[216:219], v[26:29]
	v_mfma_f32_16x16x32_bf16 v[18:21], v[148:151], v[216:219], v[18:21]
	v_mfma_f32_16x16x32_bf16 v[62:65], v[144:147], v[176:179], v[62:65]
	v_mfma_f32_16x16x32_bf16 v[58:61], v[152:155], v[176:179], v[58:61]
	v_mfma_f32_16x16x32_bf16 v[54:57], v[144:147], v[184:187], v[54:57]
	v_mfma_f32_16x16x32_bf16 v[50:53], v[152:155], v[184:187], v[50:53]
	v_mfma_f32_16x16x32_bf16 v[42:45], v[144:147], v[212:215], v[42:45]
	v_mfma_f32_16x16x32_bf16 v[34:37], v[152:155], v[212:215], v[34:37]
	v_mfma_f32_16x16x32_bf16 v[26:29], v[144:147], v[220:223], v[26:29]
	v_mfma_f32_16x16x32_bf16 v[18:21], v[152:155], v[220:223], v[18:21]
	v_mfma_f32_16x16x32_bf16 v[46:49], v[156:159], v[172:175], v[46:49]
	v_mfma_f32_16x16x32_bf16 v[38:41], v[164:167], v[172:175], v[38:41]
	v_mfma_f32_16x16x32_bf16 v[30:33], v[156:159], v[180:183], v[30:33]
	v_mfma_f32_16x16x32_bf16 v[22:25], v[164:167], v[180:183], v[22:25]
	v_mfma_f32_16x16x32_bf16 v[14:17], v[156:159], v[188:191], v[14:17]
	v_mfma_f32_16x16x32_bf16 v[10:13], v[164:167], v[188:191], v[10:13]
	v_mfma_f32_16x16x32_bf16 v[6:9], v[156:159], v[216:219], v[6:9]
	v_mfma_f32_16x16x32_bf16 v[2:5], v[164:167], v[216:219], v[2:5]
	v_mfma_f32_16x16x32_bf16 v[46:49], v[160:163], v[176:179], v[46:49]
	v_mfma_f32_16x16x32_bf16 v[38:41], v[168:171], v[176:179], v[38:41]
	v_mfma_f32_16x16x32_bf16 v[30:33], v[160:163], v[184:187], v[30:33]
	v_mfma_f32_16x16x32_bf16 v[22:25], v[168:171], v[184:187], v[22:25]
	v_mfma_f32_16x16x32_bf16 v[14:17], v[160:163], v[212:215], v[14:17]
	v_mfma_f32_16x16x32_bf16 v[10:13], v[168:171], v[212:215], v[10:13]
	v_mfma_f32_16x16x32_bf16 v[6:9], v[160:163], v[220:223], v[6:9]
	v_mfma_f32_16x16x32_bf16 v[2:5], v[168:171], v[220:223], v[2:5]
	s_barrier
	s_add_i32 s74, 0, 0x18000
	s_add_i32 s75, 0, 0x1c000
	v_add_u32_e32 v152, s74, v206
	v_add_u32_e32 v168, s75, v206
	ds_read_b128 v[140:143], v152
	ds_read_b128 v[144:147], v152 offset:1024
	ds_read_b128 v[148:151], v152 offset:2048
	ds_read_b128 v[152:155], v152 offset:3072
	ds_read_b128 v[156:159], v168
	ds_read_b128 v[160:163], v168 offset:1024
	ds_read_b128 v[164:167], v168 offset:2048
	ds_read_b128 v[168:171], v168 offset:3072
	s_add_u32 s8, s40, 0xb0000
	s_addc_u32 s9, s41, 0
	s_mov_b32 m0, s64
	v_lshl_add_u64 v[230:231], s[8:9], 0, v[134:135]
	ds_read_b128 v[172:175], v210 offset:32768
	ds_read_b128 v[176:179], v210 offset:33792
	ds_read_b128 v[180:183], v210 offset:34816
	ds_read_b128 v[184:187], v210 offset:35840
	ds_read_b128 v[188:191], v210 offset:36864
	ds_read_b128 v[212:215], v210 offset:37888
	ds_read_b128 v[216:219], v210 offset:38912
	global_load_lds_dwordx4 v[230:231], off
	v_lshl_add_u64 v[230:231], s[8:9], 0, v[132:133]
	s_mov_b32 m0, s78
	ds_read_b128 v[220:223], v210 offset:39936
	global_load_lds_dwordx4 v[230:231], off
	s_waitcnt vmcnt(8)
	s_waitcnt lgkmcnt(0)
	s_barrier
	s_waitcnt lgkmcnt(0)
	v_mfma_f32_16x16x32_bf16 v[126:129], v[140:143], v[172:175], v[126:129]
	v_mfma_f32_16x16x32_bf16 v[122:125], v[148:151], v[172:175], v[122:125]
	v_mfma_f32_16x16x32_bf16 v[118:121], v[140:143], v[180:183], v[118:121]
	v_mfma_f32_16x16x32_bf16 v[114:117], v[148:151], v[180:183], v[114:117]
	v_mfma_f32_16x16x32_bf16 v[106:109], v[140:143], v[188:191], v[106:109]
	v_mfma_f32_16x16x32_bf16 v[98:101], v[148:151], v[188:191], v[98:101]
	v_mfma_f32_16x16x32_bf16 v[90:93], v[140:143], v[216:219], v[90:93]
	v_mfma_f32_16x16x32_bf16 v[82:85], v[148:151], v[216:219], v[82:85]
	v_mfma_f32_16x16x32_bf16 v[126:129], v[144:147], v[176:179], v[126:129]
	v_mfma_f32_16x16x32_bf16 v[122:125], v[152:155], v[176:179], v[122:125]
	v_mfma_f32_16x16x32_bf16 v[118:121], v[144:147], v[184:187], v[118:121]
	v_mfma_f32_16x16x32_bf16 v[114:117], v[152:155], v[184:187], v[114:117]
	v_mfma_f32_16x16x32_bf16 v[106:109], v[144:147], v[212:215], v[106:109]
	v_mfma_f32_16x16x32_bf16 v[98:101], v[152:155], v[212:215], v[98:101]
	v_mfma_f32_16x16x32_bf16 v[90:93], v[144:147], v[220:223], v[90:93]
	v_mfma_f32_16x16x32_bf16 v[82:85], v[152:155], v[220:223], v[82:85]
	v_mfma_f32_16x16x32_bf16 v[110:113], v[156:159], v[172:175], v[110:113]
	v_mfma_f32_16x16x32_bf16 v[102:105], v[164:167], v[172:175], v[102:105]
	v_mfma_f32_16x16x32_bf16 v[94:97], v[156:159], v[180:183], v[94:97]
	v_mfma_f32_16x16x32_bf16 v[86:89], v[164:167], v[180:183], v[86:89]
	v_mfma_f32_16x16x32_bf16 v[78:81], v[156:159], v[188:191], v[78:81]
	v_mfma_f32_16x16x32_bf16 v[74:77], v[164:167], v[188:191], v[74:77]
	v_mfma_f32_16x16x32_bf16 v[70:73], v[156:159], v[216:219], v[70:73]
	v_mfma_f32_16x16x32_bf16 v[66:69], v[164:167], v[216:219], v[66:69]
	v_mfma_f32_16x16x32_bf16 v[110:113], v[160:163], v[176:179], v[110:113]
	v_mfma_f32_16x16x32_bf16 v[102:105], v[168:171], v[176:179], v[102:105]
	v_mfma_f32_16x16x32_bf16 v[94:97], v[160:163], v[184:187], v[94:97]
	v_mfma_f32_16x16x32_bf16 v[86:89], v[168:171], v[184:187], v[86:89]
	v_mfma_f32_16x16x32_bf16 v[78:81], v[160:163], v[212:215], v[78:81]
	v_mfma_f32_16x16x32_bf16 v[74:77], v[168:171], v[212:215], v[74:77]
	v_mfma_f32_16x16x32_bf16 v[70:73], v[160:163], v[220:223], v[70:73]
	v_mfma_f32_16x16x32_bf16 v[66:69], v[168:171], v[220:223], v[66:69]
	s_barrier
; #define PG8_STAGE(bufoff, gbase, voff) do { _Pragma("unroll") for (int _i = 0; _i < 2; ++_i) \
;         __builtin_amdgcn_global_load_lds((const unsigned*)((const char*)(gbase) + (voff)[_i]), (LAS unsigned*)(lds + (bufoff) + ldsw + _i * 8192), 16, 0, 0); } while (0)
; #define PG8_LDA(dst, b, h) do { _Pragma("unroll") for (int m = 0; m < 4; ++m) _Pragma("unroll") for (int k = 0; k < 2; ++k) dst[m][k] = *(const LAS bf16x8*)(lds + PG8_SA(b, h) + aoff + m * 2048 + k * 1024); } while (0)
; #define PG8_MMA(ai, bj, At, Bt) do { __builtin_amdgcn_s_setprio(1); _Pragma("unroll") for (int m = 0; m < 4; ++m) _Pragma("unroll") for (int n = 0; n < 2; ++n) _Pragma("unroll") for (int k = 0; k < 2; ++k) \
;         acc[ai][bj][m][n] = __builtin_amdgcn_mfma_f32_16x16x32_bf16(Bt[n][k], At[m][k], acc[ai][bj][m][n], 0, 0, 0); __builtin_amdgcn_s_setprio(0); } while (0)
; #define PG8_WAIT_V(n) asm volatile("s_waitcnt vmcnt(" #n ")" ::: "memory")
; #define PG8_WAIT_L(n) asm volatile("s_waitcnt lgkmcnt(" #n ")" ::: "memory")
; #define PG8_BAR __builtin_amdgcn_s_barrier()
; #define PG8_SCHED __builtin_amdgcn_sched_barrier(0)
; template <class Epi, class Sched>
; __device__ __forceinline__ void gemm_phase(LAS unsigned char* lds, const Gemm g, const Sched& S, const Epi& E) {
;     ...
;             PG8_LDA(At, 1, 1); PG8_STAGE(PG8_SB(1, 0), b3, voffB); PG8_STAGE(PG8_SB(1, 1), b3 + hsB, voffB); PG8_STAGE(PG8_SA(1, 0), a3, voffA);
;             PG8_WAIT_V(8); PG8_WAIT_L(0); PG8_BAR; PG8_MMA(1, 0, At, B0); PG8_MMA(1, 1, At, B1); PG8_BAR; PG8_SCHED;
;         }
	s_add_i32 s8, s74, s24
	v_lshl_add_u64 v[208:209], v[208:209], 0, s[18:19]
	s_mov_b32 m0, s8
	ds_read_b128 v[172:175], v210 offset:49152
	ds_read_b128 v[176:179], v210 offset:50176
	ds_read_b128 v[180:183], v210 offset:51200
	ds_read_b128 v[184:187], v210 offset:52224
	global_load_lds_dwordx4 v[208:209], off
	s_add_i32 m0, s8, 0x2000
	s_add_u32 s8, s38, 0xb0080
	v_lshl_add_u64 v[208:209], v[224:225], 0, s[18:19]
	s_addc_u32 s9, s39, 0
	s_add_i32 s38, s75, s24
	global_load_lds_dwordx4 v[208:209], off
	v_lshl_add_u64 v[208:209], s[8:9], 0, v[0:1]
	s_mov_b32 m0, s38
	ds_read_b128 v[188:191], v210 offset:53248
	global_load_lds_dwordx4 v[208:209], off
	v_lshl_add_u64 v[208:209], s[8:9], 0, v[130:131]
	s_add_i32 m0, s38, 0x2000
	ds_read_b128 v[212:215], v210 offset:54272
	global_load_lds_dwordx4 v[208:209], off
	v_lshl_add_u64 v[208:209], v[226:227], 0, s[18:19]
	s_mov_b32 m0, s16
	ds_read_b128 v[216:219], v210 offset:55296
	global_load_lds_dwordx4 v[208:209], off
	v_lshl_add_u64 v[208:209], v[228:229], 0, s[18:19]
	s_mov_b32 m0, s7
	ds_read_b128 v[220:223], v210 offset:56320
	global_load_lds_dwordx4 v[208:209], off
	s_waitcnt vmcnt(8)
	s_waitcnt lgkmcnt(0)
	s_barrier
	s_waitcnt lgkmcnt(0)
	v_mfma_f32_16x16x32_bf16 v[62:65], v[140:143], v[172:175], v[62:65]
	v_mfma_f32_16x16x32_bf16 v[58:61], v[148:151], v[172:175], v[58:61]
	v_mfma_f32_16x16x32_bf16 v[54:57], v[140:143], v[180:183], v[54:57]
	v_mfma_f32_16x16x32_bf16 v[50:53], v[148:151], v[180:183], v[50:53]
	v_mfma_f32_16x16x32_bf16 v[42:45], v[140:143], v[188:191], v[42:45]
	v_mfma_f32_16x16x32_bf16 v[34:37], v[148:151], v[188:191], v[34:37]
	v_mfma_f32_16x16x32_bf16 v[26:29], v[140:143], v[216:219], v[26:29]
	v_mfma_f32_16x16x32_bf16 v[18:21], v[148:151], v[216:219], v[18:21]
	v_mfma_f32_16x16x32_bf16 v[62:65], v[144:147], v[176:179], v[62:65]
	v_mfma_f32_16x16x32_bf16 v[58:61], v[152:155], v[176:179], v[58:61]
	v_mfma_f32_16x16x32_bf16 v[54:57], v[144:147], v[184:187], v[54:57]
	v_mfma_f32_16x16x32_bf16 v[50:53], v[152:155], v[184:187], v[50:53]
	v_mfma_f32_16x16x32_bf16 v[42:45], v[144:147], v[212:215], v[42:45]
	v_mfma_f32_16x16x32_bf16 v[34:37], v[152:155], v[212:215], v[34:37]
	v_mfma_f32_16x16x32_bf16 v[26:29], v[144:147], v[220:223], v[26:29]
	v_mfma_f32_16x16x32_bf16 v[18:21], v[152:155], v[220:223], v[18:21]
	v_mfma_f32_16x16x32_bf16 v[46:49], v[156:159], v[172:175], v[46:49]
	v_mfma_f32_16x16x32_bf16 v[38:41], v[164:167], v[172:175], v[38:41]
	v_mfma_f32_16x16x32_bf16 v[30:33], v[156:159], v[180:183], v[30:33]
	v_mfma_f32_16x16x32_bf16 v[22:25], v[164:167], v[180:183], v[22:25]
	v_mfma_f32_16x16x32_bf16 v[14:17], v[156:159], v[188:191], v[14:17]
	v_mfma_f32_16x16x32_bf16 v[10:13], v[164:167], v[188:191], v[10:13]
	v_mfma_f32_16x16x32_bf16 v[6:9], v[156:159], v[216:219], v[6:9]
	v_mfma_f32_16x16x32_bf16 v[2:5], v[164:167], v[216:219], v[2:5]
	v_mfma_f32_16x16x32_bf16 v[46:49], v[160:163], v[176:179], v[46:49]
	v_mfma_f32_16x16x32_bf16 v[38:41], v[168:171], v[176:179], v[38:41]
	v_mfma_f32_16x16x32_bf16 v[30:33], v[160:163], v[184:187], v[30:33]
	v_mfma_f32_16x16x32_bf16 v[22:25], v[168:171], v[184:187], v[22:25]
	v_mfma_f32_16x16x32_bf16 v[14:17], v[160:163], v[212:215], v[14:17]
	v_mfma_f32_16x16x32_bf16 v[10:13], v[168:171], v[212:215], v[10:13]
	v_mfma_f32_16x16x32_bf16 v[6:9], v[160:163], v[220:223], v[6:9]
	v_mfma_f32_16x16x32_bf16 v[2:5], v[168:171], v[220:223], v[2:5]
	s_barrier
	s_add_u32 s84, s84, 0x100
	s_addc_u32 s85, s85, 0
	s_cmp_ge_i32 s96, s12
	s_mov_b64 s[8:9], s[20:21]
	s_mov_b32 s38, s96
	s_cbranch_scc0 .LBB0_298
; __device__ __forceinline__ u32x4 pack8(f32x4 a, f32x4 b) { u32x4 w; w.x = cvt_pk_bf16(a[0], a[1]); w.y = cvt_pk_bf16(a[2], a[3]); w.z = cvt_pk_bf16(b[0], b[1]); w.w = cvt_pk_bf16(b[2], b[3]); return w; }
;     __device__ __forceinline__ void operator()(const Acc& acc, const Unit& u, int wr, int wc, int fr, int fq) const {
;     ...
;             for (int m = 0; m < 4; ++m) { const size_t row = (size_t)(row0 + ai * 128 + m * 16); float s = 0.f;
; #pragma unroll
;                 for (int bj = 0; bj < 2; ++bj) { const size_t off = row * DM + c8 + bj * 128; f32x4 b0, b1; unpack8(bv[m][bj], b0, b1);
;                     const f32x4 o0 = b0 + acc[ai][bj][m][0] * scale, o1 = b1 + acc[ai][bj][m][1] * scale;
;                     if (outf) { *(f32x4*)(outf + off) = o0; *(f32x4*)(outf + off + 4) = o1; }
;                     if (!outf) *(u32x4*)(xb + off) = pack8(o0, o1);
;                     s += ((o0[0] * o0[0] + o0[1] * o0[1]) + (o0[2] * o0[2] + o0[3] * o0[3])) + ((o1[0] * o1[0] + o1[1] * o1[1]) + (o1[2] * o1[2] + o1[3] * o1[3])); }
	s_setprio 0
	v_pk_mul_f32 v[182:183], v[128:129], 0.5 op_sel_hi:[1,0]
	v_pk_mul_f32 v[184:185], v[126:127], 0.5 op_sel_hi:[1,0]
	v_pk_mul_f32 v[186:187], v[124:125], 0.5 op_sel_hi:[1,0]
	v_pk_mul_f32 v[188:189], v[122:123], 0.5 op_sel_hi:[1,0]
	v_pk_mul_f32 v[180:181], v[112:113], 0.5 op_sel_hi:[1,0]
	v_pk_mul_f32 v[178:179], v[110:111], 0.5 op_sel_hi:[1,0]
	v_pk_mul_f32 v[176:177], v[104:105], 0.5 op_sel_hi:[1,0]
	v_pk_mul_f32 v[174:175], v[102:103], 0.5 op_sel_hi:[1,0]
	v_pk_mul_f32 v[170:171], v[120:121], 0.5 op_sel_hi:[1,0]
	v_pk_mul_f32 v[168:169], v[118:119], 0.5 op_sel_hi:[1,0]
	v_pk_mul_f32 v[166:167], v[116:117], 0.5 op_sel_hi:[1,0]
	v_pk_mul_f32 v[164:165], v[114:115], 0.5 op_sel_hi:[1,0]
	v_pk_mul_f32 v[162:163], v[96:97], 0.5 op_sel_hi:[1,0]
	v_pk_mul_f32 v[160:161], v[94:95], 0.5 op_sel_hi:[1,0]
	v_pk_mul_f32 v[158:159], v[88:89], 0.5 op_sel_hi:[1,0]
	v_pk_mul_f32 v[156:157], v[86:87], 0.5 op_sel_hi:[1,0]
	v_pk_mul_f32 v[150:151], v[108:109], 0.5 op_sel_hi:[1,0]
	v_pk_mul_f32 v[148:149], v[106:107], 0.5 op_sel_hi:[1,0]
	v_pk_mul_f32 v[146:147], v[100:101], 0.5 op_sel_hi:[1,0]
	v_pk_mul_f32 v[144:145], v[98:99], 0.5 op_sel_hi:[1,0]
	v_pk_mul_f32 v[142:143], v[80:81], 0.5 op_sel_hi:[1,0]
	v_pk_mul_f32 v[140:141], v[78:79], 0.5 op_sel_hi:[1,0]
	v_pk_mul_f32 v[128:129], v[76:77], 0.5 op_sel_hi:[1,0]
	v_pk_mul_f32 v[126:127], v[74:75], 0.5 op_sel_hi:[1,0]
	v_pk_mul_f32 v[124:125], v[92:93], 0.5 op_sel_hi:[1,0]
	v_pk_mul_f32 v[122:123], v[90:91], 0.5 op_sel_hi:[1,0]
	v_pk_mul_f32 v[120:121], v[84:85], 0.5 op_sel_hi:[1,0]
	v_pk_mul_f32 v[118:119], v[82:83], 0.5 op_sel_hi:[1,0]
	v_pk_mul_f32 v[116:117], v[72:73], 0.5 op_sel_hi:[1,0]
	v_pk_mul_f32 v[114:115], v[70:71], 0.5 op_sel_hi:[1,0]
	v_pk_mul_f32 v[112:113], v[68:69], 0.5 op_sel_hi:[1,0]
	v_pk_mul_f32 v[110:111], v[66:67], 0.5 op_sel_hi:[1,0]
	v_pk_mul_f32 v[102:103], v[64:65], 0.5 op_sel_hi:[1,0]
	v_pk_mul_f32 v[104:105], v[62:63], 0.5 op_sel_hi:[1,0]
	v_pk_mul_f32 v[106:107], v[60:61], 0.5 op_sel_hi:[1,0]
	v_pk_mul_f32 v[108:109], v[58:59], 0.5 op_sel_hi:[1,0]
	v_pk_mul_f32 v[100:101], v[48:49], 0.5 op_sel_hi:[1,0]
	v_pk_mul_f32 v[98:99], v[46:47], 0.5 op_sel_hi:[1,0]
	v_pk_mul_f32 v[96:97], v[40:41], 0.5 op_sel_hi:[1,0]
	v_pk_mul_f32 v[94:95], v[38:39], 0.5 op_sel_hi:[1,0]
	v_pk_mul_f32 v[92:93], v[56:57], 0.5 op_sel_hi:[1,0]
	v_pk_mul_f32 v[90:91], v[54:55], 0.5 op_sel_hi:[1,0]
	v_pk_mul_f32 v[88:89], v[52:53], 0.5 op_sel_hi:[1,0]
	v_pk_mul_f32 v[86:87], v[50:51], 0.5 op_sel_hi:[1,0]
	v_pk_mul_f32 v[82:83], v[32:33], 0.5 op_sel_hi:[1,0]
	v_pk_mul_f32 v[80:81], v[30:31], 0.5 op_sel_hi:[1,0]
	v_pk_mul_f32 v[78:79], v[24:25], 0.5 op_sel_hi:[1,0]
	v_pk_mul_f32 v[76:77], v[22:23], 0.5 op_sel_hi:[1,0]
	v_pk_mul_f32 v[72:73], v[44:45], 0.5 op_sel_hi:[1,0]
	v_pk_mul_f32 v[70:71], v[42:43], 0.5 op_sel_hi:[1,0]
	v_pk_mul_f32 v[68:69], v[36:37], 0.5 op_sel_hi:[1,0]
	v_pk_mul_f32 v[66:67], v[34:35], 0.5 op_sel_hi:[1,0]
	v_pk_mul_f32 v[64:65], v[16:17], 0.5 op_sel_hi:[1,0]
	v_pk_mul_f32 v[62:63], v[14:15], 0.5 op_sel_hi:[1,0]
	v_pk_mul_f32 v[60:61], v[12:13], 0.5 op_sel_hi:[1,0]
	v_pk_mul_f32 v[58:59], v[10:11], 0.5 op_sel_hi:[1,0]
	v_pk_mul_f32 v[56:57], v[28:29], 0.5 op_sel_hi:[1,0]
	v_pk_mul_f32 v[54:55], v[26:27], 0.5 op_sel_hi:[1,0]
	v_pk_mul_f32 v[52:53], v[20:21], 0.5 op_sel_hi:[1,0]
	v_pk_mul_f32 v[50:51], v[18:19], 0.5 op_sel_hi:[1,0]
	v_pk_mul_f32 v[48:49], v[8:9], 0.5 op_sel_hi:[1,0]
	v_pk_mul_f32 v[46:47], v[6:7], 0.5 op_sel_hi:[1,0]
	v_pk_mul_f32 v[44:45], v[4:5], 0.5 op_sel_hi:[1,0]
	v_pk_mul_f32 v[42:43], v[2:3], 0.5 op_sel_hi:[1,0]
	v_readlane_b32 s96, v250, 43
	s_mov_b32 s73, s22
	s_mov_b32 s74, s23
	s_mov_b32 s75, vcc_lo

; #define PG8_STAGE(bufoff, gbase, voff) do { _Pragma("unroll") for (int _i = 0; _i < 2; ++_i) \
;         __builtin_amdgcn_global_load_lds((const unsigned*)((const char*)(gbase) + (voff)[_i]), (LAS unsigned*)(lds + (bufoff) + ldsw + _i * 8192), 16, 0, 0); } while (0)
; #define PG8_LDA(dst, b, h) do { _Pragma("unroll") for (int m = 0; m < 4; ++m) _Pragma("unroll") for (int k = 0; k < 2; ++k) dst[m][k] = *(const LAS bf16x8*)(lds + PG8_SA(b, h) + aoff + m * 2048 + k * 1024); } while (0)
; #define PG8_LDB(dst, b, h) do { _Pragma("unroll") for (int n = 0; n < 2; ++n) _Pragma("unroll") for (int k = 0; k < 2; ++k) dst[n][k] = *(const LAS bf16x8*)(lds + PG8_SB(b, h) + boff + n * 2048 + k * 1024); } while (0)
; #define PG8_MMA(ai, bj, At, Bt) do { __builtin_amdgcn_s_setprio(1); _Pragma("unroll") for (int m = 0; m < 4; ++m) _Pragma("unroll") for (int n = 0; n < 2; ++n) _Pragma("unroll") for (int k = 0; k < 2; ++k) \
;         acc[ai][bj][m][n] = __builtin_amdgcn_mfma_f32_16x16x32_bf16(Bt[n][k], At[m][k], acc[ai][bj][m][n], 0, 0, 0); __builtin_amdgcn_s_setprio(0); } while (0)
; #define PG8_WAIT_V(n) asm volatile("s_waitcnt vmcnt(" #n ")" ::: "memory")
; #define PG8_WAIT_L(n) asm volatile("s_waitcnt lgkmcnt(" #n ")" ::: "memory")
; template <class Epi, class Sched>
; __device__ __forceinline__ void gemm_phase(LAS unsigned char* lds, const Gemm g, const Sched& S, const Epi& E) {
;     ...
;             const bool last = (t == nt - 2);
;             const char* a1 = cA + (size_t)(t + 1) * kstep;
;             const char* a2 = last ? nA : cA + (size_t)(t + 2) * kstep; const char* b2 = last ? nB : cB + (size_t)(t + 2) * kstep;
;             const char* a3 = a2 + kstep; const char* b3 = b2 + kstep;
;             if constexpr (Epi::MIDK) { if (t == (nt >> 1)) { int fr_ = fr, fq_ = fq; asm volatile("" : "+v"(fr_), "+v"(fq_)); E.mid(acc, cur, wr, wc, fr_, fq_); } }
;             PG8_LDB(B0, 0, 0); PG8_LDB(B1, 0, 1); PG8_SCHED; PG8_LDA(At, 0, 0); PG8_STAGE(PG8_SA(1, 1), a1 + hsA, voffA);
;             PG8_WAIT_V(8); PG8_WAIT_L(0); PG8_BAR; PG8_MMA(0, 0, At, B0); PG8_MMA(0, 1, At, B1); PG8_BAR; PG8_SCHED;
;             PG8_LDA(At, 0, 1); PG8_STAGE(PG8_SB(0, 0), b2, voffB); PG8_STAGE(PG8_SB(0, 1), b2 + hsB, voffB); PG8_STAGE(PG8_SA(0, 0), a2, voffA);
;             PG8_WAIT_V(8); PG8_WAIT_L(0); PG8_BAR; PG8_MMA(1, 0, At, B0); PG8_MMA(1, 1, At, B1); PG8_BAR; PG8_SCHED;
.Lnp_485:
.LBB0_485:
	s_add_i32 s85, s40, 2
	s_add_u32 s41, s38, 0xfffc0080
	s_addc_u32 s42, s39, -1
	s_add_i32 s74, 0, 0x10000
	s_cmp_eq_u32 s26, s40
	s_cselect_b32 s43, s47, s42
	s_cselect_b32 s42, s49, s41
	s_cselect_b32 s41, s73, s84
	s_cselect_b32 s40, s82, s83
	s_add_i32 s75, 0, 0x14000
	v_add_u32_e32 v154, s74, v165
	v_add_u32_e32 v162, s75, v165
	ds_read_b128 v[142:145], v154
	ds_read_b128 v[146:149], v154 offset:1024
	ds_read_b128 v[150:153], v154 offset:2048
	ds_read_b128 v[154:157], v154 offset:3072
	ds_read_b128 v[158:161], v162
	ds_read_b128 v[168:171], v162 offset:1024
	ds_read_b128 v[172:175], v162 offset:2048
	ds_read_b128 v[176:179], v162 offset:3072
	v_lshl_add_u64 v[228:229], s[38:39], 0, v[138:139]
	s_add_i32 m0, s16, 0xc000
	ds_read_b128 v[180:183], v166
	ds_read_b128 v[184:187], v166 offset:1024
	ds_read_b128 v[188:191], v166 offset:2048
	ds_read_b128 v[208:211], v166 offset:3072
	ds_read_b128 v[212:215], v166 offset:4096
	ds_read_b128 v[216:219], v166 offset:5120
	ds_read_b128 v[220:223], v166 offset:6144
	global_load_lds_dwordx4 v[228:229], off
	v_lshl_add_u64 v[228:229], s[38:39], 0, v[140:141]
	s_add_i32 m0, s16, 0xe000
	ds_read_b128 v[224:227], v166 offset:7168
	global_load_lds_dwordx4 v[228:229], off
	s_waitcnt vmcnt(8)
	s_waitcnt lgkmcnt(0)
	s_barrier
	s_waitcnt lgkmcnt(0)
	v_mfma_f32_16x16x32_bf16 v[122:125], v[142:145], v[180:183], v[122:125]
	v_mfma_f32_16x16x32_bf16 v[114:117], v[150:153], v[180:183], v[114:117]
	v_mfma_f32_16x16x32_bf16 v[110:113], v[142:145], v[188:191], v[110:113]
	v_mfma_f32_16x16x32_bf16 v[98:101], v[150:153], v[188:191], v[98:101]
	v_mfma_f32_16x16x32_bf16 v[94:97], v[142:145], v[212:215], v[94:97]
	v_mfma_f32_16x16x32_bf16 v[82:85], v[150:153], v[212:215], v[82:85]
	v_mfma_f32_16x16x32_bf16 v[78:81], v[142:145], v[220:223], v[78:81]
	v_mfma_f32_16x16x32_bf16 v[66:69], v[150:153], v[220:223], v[66:69]
	v_mfma_f32_16x16x32_bf16 v[122:125], v[146:149], v[184:187], v[122:125]
	v_mfma_f32_16x16x32_bf16 v[114:117], v[154:157], v[184:187], v[114:117]
	v_mfma_f32_16x16x32_bf16 v[110:113], v[146:149], v[208:211], v[110:113]
	v_mfma_f32_16x16x32_bf16 v[98:101], v[154:157], v[208:211], v[98:101]
	v_mfma_f32_16x16x32_bf16 v[94:97], v[146:149], v[216:219], v[94:97]
	v_mfma_f32_16x16x32_bf16 v[82:85], v[154:157], v[216:219], v[82:85]
	v_mfma_f32_16x16x32_bf16 v[78:81], v[146:149], v[224:227], v[78:81]
	v_mfma_f32_16x16x32_bf16 v[66:69], v[154:157], v[224:227], v[66:69]
	v_mfma_f32_16x16x32_bf16 v[126:129], v[158:161], v[180:183], v[126:129]
	v_mfma_f32_16x16x32_bf16 v[118:121], v[172:175], v[180:183], v[118:121]
	v_mfma_f32_16x16x32_bf16 v[106:109], v[158:161], v[188:191], v[106:109]
	v_mfma_f32_16x16x32_bf16 v[102:105], v[172:175], v[188:191], v[102:105]
	v_mfma_f32_16x16x32_bf16 v[90:93], v[158:161], v[212:215], v[90:93]
	v_mfma_f32_16x16x32_bf16 v[86:89], v[172:175], v[212:215], v[86:89]
	v_mfma_f32_16x16x32_bf16 v[74:77], v[158:161], v[220:223], v[74:77]
	v_mfma_f32_16x16x32_bf16 v[70:73], v[172:175], v[220:223], v[70:73]
	v_mfma_f32_16x16x32_bf16 v[126:129], v[168:171], v[184:187], v[126:129]
	v_mfma_f32_16x16x32_bf16 v[118:121], v[176:179], v[184:187], v[118:121]
	v_mfma_f32_16x16x32_bf16 v[106:109], v[168:171], v[208:211], v[106:109]
	v_mfma_f32_16x16x32_bf16 v[102:105], v[176:179], v[208:211], v[102:105]
	v_mfma_f32_16x16x32_bf16 v[90:93], v[168:171], v[216:219], v[90:93]
	v_mfma_f32_16x16x32_bf16 v[86:89], v[176:179], v[216:219], v[86:89]
	v_mfma_f32_16x16x32_bf16 v[74:77], v[168:171], v[224:227], v[74:77]
	v_mfma_f32_16x16x32_bf16 v[70:73], v[176:179], v[224:227], v[70:73]
	s_barrier
	s_add_i32 s74, s74, s12
	v_lshl_add_u64 v[228:229], s[40:41], 0, v[0:1]
	s_mov_b32 m0, s74
	ds_read_b128 v[180:183], v166 offset:16384
	ds_read_b128 v[184:187], v166 offset:17408
	ds_read_b128 v[188:191], v166 offset:18432
	ds_read_b128 v[208:211], v166 offset:19456
	ds_read_b128 v[212:215], v166 offset:20480
	global_load_lds_dwordx4 v[228:229], off
	s_add_i32 m0, s74, 0x2000
	s_add_u32 vcc_lo, s40, 0x40000
	v_lshl_add_u64 v[230:231], s[40:41], 0, v[130:131]
	s_addc_u32 vcc_hi, s41, 0
	s_add_i32 s74, s75, s12
	global_load_lds_dwordx4 v[230:231], off
	v_lshl_add_u64 v[232:233], vcc, 0, v[0:1]
	s_mov_b32 m0, s74
	v_lshl_add_u64 v[238:239], s[42:43], 0, v[132:133]
	global_load_lds_dwordx4 v[232:233], off
	v_lshl_add_u64 v[232:233], vcc, 0, v[130:131]
	s_add_i32 m0, s74, 0x2000
	ds_read_b128 v[216:219], v166 offset:21504
	global_load_lds_dwordx4 v[232:233], off
	v_lshl_add_u64 v[232:233], s[42:43], 0, v[134:135]
	s_mov_b32 m0, s16
	ds_read_b128 v[220:223], v166 offset:22528
	global_load_lds_dwordx4 v[232:233], off
	s_mov_b32 m0, s52
	ds_read_b128 v[224:227], v166 offset:23552
	global_load_lds_dwordx4 v[238:239], off
	s_waitcnt vmcnt(8)
	s_waitcnt lgkmcnt(0)
	s_barrier
; #define PG8_STAGE(bufoff, gbase, voff) do { _Pragma("unroll") for (int _i = 0; _i < 2; ++_i) \
;         __builtin_amdgcn_global_load_lds((const unsigned*)((const char*)(gbase) + (voff)[_i]), (LAS unsigned*)(lds + (bufoff) + ldsw + _i * 8192), 16, 0, 0); } while (0)
; #define PG8_LDA(dst, b, h) do { _Pragma("unroll") for (int m = 0; m < 4; ++m) _Pragma("unroll") for (int k = 0; k < 2; ++k) dst[m][k] = *(const LAS bf16x8*)(lds + PG8_SA(b, h) + aoff + m * 2048 + k * 1024); } while (0)
; #define PG8_LDB(dst, b, h) do { _Pragma("unroll") for (int n = 0; n < 2; ++n) _Pragma("unroll") for (int k = 0; k < 2; ++k) dst[n][k] = *(const LAS bf16x8*)(lds + PG8_SB(b, h) + boff + n * 2048 + k * 1024); } while (0)
; #define PG8_MMA(ai, bj, At, Bt) do { __builtin_amdgcn_s_setprio(1); _Pragma("unroll") for (int m = 0; m < 4; ++m) _Pragma("unroll") for (int n = 0; n < 2; ++n) _Pragma("unroll") for (int k = 0; k < 2; ++k) \
;         acc[ai][bj][m][n] = __builtin_amdgcn_mfma_f32_16x16x32_bf16(Bt[n][k], At[m][k], acc[ai][bj][m][n], 0, 0, 0); __builtin_amdgcn_s_setprio(0); } while (0)
; #define PG8_WAIT_V(n) asm volatile("s_waitcnt vmcnt(" #n ")" ::: "memory")
; #define PG8_WAIT_L(n) asm volatile("s_waitcnt lgkmcnt(" #n ")" ::: "memory")
; #define PG8_BAR __builtin_amdgcn_s_barrier()
; #define PG8_SCHED __builtin_amdgcn_sched_barrier(0)
; template <class Epi, class Sched>
; __device__ __forceinline__ void gemm_phase(LAS unsigned char* lds, const Gemm g, const Sched& S, const Epi& E) {
;     ...
;             PG8_WAIT_V(8); PG8_WAIT_L(0); PG8_BAR; PG8_MMA(1, 0, At, B0); PG8_MMA(1, 1, At, B1); PG8_BAR; PG8_SCHED;
;             PG8_LDB(B0, 1, 0); PG8_LDB(B1, 1, 1); PG8_SCHED; PG8_LDA(At, 1, 0); PG8_STAGE(PG8_SA(0, 1), a2 + hsA, voffA);
;             PG8_WAIT_V(8); PG8_WAIT_L(0); PG8_BAR; PG8_MMA(0, 0, At, B0); PG8_MMA(0, 1, At, B1); PG8_BAR; PG8_SCHED;
	s_waitcnt lgkmcnt(0)
	v_mfma_f32_16x16x32_bf16 v[62:65], v[142:145], v[180:183], v[62:65]
	v_mfma_f32_16x16x32_bf16 v[50:53], v[150:153], v[180:183], v[50:53]
	v_mfma_f32_16x16x32_bf16 v[46:49], v[142:145], v[188:191], v[46:49]
	v_mfma_f32_16x16x32_bf16 v[34:37], v[150:153], v[188:191], v[34:37]
	v_mfma_f32_16x16x32_bf16 v[30:33], v[142:145], v[212:215], v[30:33]
	v_mfma_f32_16x16x32_bf16 v[18:21], v[150:153], v[212:215], v[18:21]
	v_mfma_f32_16x16x32_bf16 v[10:13], v[142:145], v[220:223], v[10:13]
	v_mfma_f32_16x16x32_bf16 v[2:5], v[150:153], v[220:223], v[2:5]
	v_mfma_f32_16x16x32_bf16 v[62:65], v[146:149], v[184:187], v[62:65]
	v_mfma_f32_16x16x32_bf16 v[50:53], v[154:157], v[184:187], v[50:53]
	v_mfma_f32_16x16x32_bf16 v[46:49], v[146:149], v[208:211], v[46:49]
	v_mfma_f32_16x16x32_bf16 v[34:37], v[154:157], v[208:211], v[34:37]
	v_mfma_f32_16x16x32_bf16 v[30:33], v[146:149], v[216:219], v[30:33]
	v_mfma_f32_16x16x32_bf16 v[18:21], v[154:157], v[216:219], v[18:21]
	v_mfma_f32_16x16x32_bf16 v[10:13], v[146:149], v[224:227], v[10:13]
	v_mfma_f32_16x16x32_bf16 v[2:5], v[154:157], v[224:227], v[2:5]
	v_mfma_f32_16x16x32_bf16 v[58:61], v[158:161], v[180:183], v[58:61]
	v_mfma_f32_16x16x32_bf16 v[54:57], v[172:175], v[180:183], v[54:57]
	v_mfma_f32_16x16x32_bf16 v[42:45], v[158:161], v[188:191], v[42:45]
	v_mfma_f32_16x16x32_bf16 v[38:41], v[172:175], v[188:191], v[38:41]
	v_mfma_f32_16x16x32_bf16 v[26:29], v[158:161], v[212:215], v[26:29]
	v_mfma_f32_16x16x32_bf16 v[22:25], v[172:175], v[212:215], v[22:25]
	v_mfma_f32_16x16x32_bf16 v[14:17], v[158:161], v[220:223], v[14:17]
	v_mfma_f32_16x16x32_bf16 v[6:9], v[172:175], v[220:223], v[6:9]
	v_mfma_f32_16x16x32_bf16 v[58:61], v[168:171], v[184:187], v[58:61]
	v_mfma_f32_16x16x32_bf16 v[54:57], v[176:179], v[184:187], v[54:57]
	v_mfma_f32_16x16x32_bf16 v[42:45], v[168:171], v[208:211], v[42:45]
	v_mfma_f32_16x16x32_bf16 v[38:41], v[176:179], v[208:211], v[38:41]
	v_mfma_f32_16x16x32_bf16 v[26:29], v[168:171], v[216:219], v[26:29]
	v_mfma_f32_16x16x32_bf16 v[22:25], v[176:179], v[216:219], v[22:25]
	v_mfma_f32_16x16x32_bf16 v[14:17], v[168:171], v[224:227], v[14:17]
	v_mfma_f32_16x16x32_bf16 v[6:9], v[176:179], v[224:227], v[6:9]
	s_barrier
	s_add_i32 s74, 0, 0x18000
	s_add_i32 s75, 0, 0x1c000
	v_add_u32_e32 v154, s74, v165
	v_add_u32_e32 v162, s75, v165
	ds_read_b128 v[142:145], v154
	ds_read_b128 v[146:149], v154 offset:1024
	ds_read_b128 v[150:153], v154 offset:2048
	ds_read_b128 v[154:157], v154 offset:3072
	ds_read_b128 v[158:161], v162
	ds_read_b128 v[168:171], v162 offset:1024
	ds_read_b128 v[172:175], v162 offset:2048
	ds_read_b128 v[176:179], v162 offset:3072
	s_add_u32 s42, s42, 0x40000
	s_addc_u32 s43, s43, 0
	s_mov_b32 m0, s64
	v_lshl_add_u64 v[240:241], s[42:43], 0, v[134:135]
	ds_read_b128 v[180:183], v166 offset:32768
	ds_read_b128 v[184:187], v166 offset:33792
	ds_read_b128 v[188:191], v166 offset:34816
	ds_read_b128 v[208:211], v166 offset:35840
	ds_read_b128 v[212:215], v166 offset:36864
	ds_read_b128 v[216:219], v166 offset:37888
	ds_read_b128 v[220:223], v166 offset:38912
	global_load_lds_dwordx4 v[240:241], off
	v_lshl_add_u64 v[240:241], s[42:43], 0, v[132:133]
	s_mov_b32 m0, s78
	ds_read_b128 v[224:227], v166 offset:39936
	global_load_lds_dwordx4 v[240:241], off
	s_waitcnt vmcnt(8)
	s_waitcnt lgkmcnt(0)
	s_barrier
	s_waitcnt lgkmcnt(0)
	v_mfma_f32_16x16x32_bf16 v[122:125], v[142:145], v[180:183], v[122:125]
	v_mfma_f32_16x16x32_bf16 v[114:117], v[150:153], v[180:183], v[114:117]
	v_mfma_f32_16x16x32_bf16 v[110:113], v[142:145], v[188:191], v[110:113]
	v_mfma_f32_16x16x32_bf16 v[98:101], v[150:153], v[188:191], v[98:101]
	v_mfma_f32_16x16x32_bf16 v[94:97], v[142:145], v[212:215], v[94:97]
	v_mfma_f32_16x16x32_bf16 v[82:85], v[150:153], v[212:215], v[82:85]
	v_mfma_f32_16x16x32_bf16 v[78:81], v[142:145], v[220:223], v[78:81]
	v_mfma_f32_16x16x32_bf16 v[66:69], v[150:153], v[220:223], v[66:69]
	v_mfma_f32_16x16x32_bf16 v[122:125], v[146:149], v[184:187], v[122:125]
	v_mfma_f32_16x16x32_bf16 v[114:117], v[154:157], v[184:187], v[114:117]
	v_mfma_f32_16x16x32_bf16 v[110:113], v[146:149], v[208:211], v[110:113]
	v_mfma_f32_16x16x32_bf16 v[98:101], v[154:157], v[208:211], v[98:101]
	v_mfma_f32_16x16x32_bf16 v[94:97], v[146:149], v[216:219], v[94:97]
	v_mfma_f32_16x16x32_bf16 v[82:85], v[154:157], v[216:219], v[82:85]
	v_mfma_f32_16x16x32_bf16 v[78:81], v[146:149], v[224:227], v[78:81]
	v_mfma_f32_16x16x32_bf16 v[66:69], v[154:157], v[224:227], v[66:69]
	v_mfma_f32_16x16x32_bf16 v[126:129], v[158:161], v[180:183], v[126:129]
	v_mfma_f32_16x16x32_bf16 v[118:121], v[172:175], v[180:183], v[118:121]
	v_mfma_f32_16x16x32_bf16 v[106:109], v[158:161], v[188:191], v[106:109]
	v_mfma_f32_16x16x32_bf16 v[102:105], v[172:175], v[188:191], v[102:105]
	v_mfma_f32_16x16x32_bf16 v[90:93], v[158:161], v[212:215], v[90:93]
	v_mfma_f32_16x16x32_bf16 v[86:89], v[172:175], v[212:215], v[86:89]
	v_mfma_f32_16x16x32_bf16 v[74:77], v[158:161], v[220:223], v[74:77]
	v_mfma_f32_16x16x32_bf16 v[70:73], v[172:175], v[220:223], v[70:73]
	v_mfma_f32_16x16x32_bf16 v[126:129], v[168:171], v[184:187], v[126:129]
	v_mfma_f32_16x16x32_bf16 v[118:121], v[176:179], v[184:187], v[118:121]
	v_mfma_f32_16x16x32_bf16 v[106:109], v[168:171], v[208:211], v[106:109]
	v_mfma_f32_16x16x32_bf16 v[102:105], v[176:179], v[208:211], v[102:105]
	v_mfma_f32_16x16x32_bf16 v[90:93], v[168:171], v[216:219], v[90:93]
	v_mfma_f32_16x16x32_bf16 v[86:89], v[176:179], v[216:219], v[86:89]
	v_mfma_f32_16x16x32_bf16 v[74:77], v[168:171], v[224:227], v[74:77]
	v_mfma_f32_16x16x32_bf16 v[70:73], v[176:179], v[224:227], v[70:73]
	s_barrier
; #define PG8_STAGE(bufoff, gbase, voff) do { _Pragma("unroll") for (int _i = 0; _i < 2; ++_i) \
;         __builtin_amdgcn_global_load_lds((const unsigned*)((const char*)(gbase) + (voff)[_i]), (LAS unsigned*)(lds + (bufoff) + ldsw + _i * 8192), 16, 0, 0); } while (0)
; #define PG8_LDA(dst, b, h) do { _Pragma("unroll") for (int m = 0; m < 4; ++m) _Pragma("unroll") for (int k = 0; k < 2; ++k) dst[m][k] = *(const LAS bf16x8*)(lds + PG8_SA(b, h) + aoff + m * 2048 + k * 1024); } while (0)
; #define PG8_MMA(ai, bj, At, Bt) do { __builtin_amdgcn_s_setprio(1); _Pragma("unroll") for (int m = 0; m < 4; ++m) _Pragma("unroll") for (int n = 0; n < 2; ++n) _Pragma("unroll") for (int k = 0; k < 2; ++k) \
;         acc[ai][bj][m][n] = __builtin_amdgcn_mfma_f32_16x16x32_bf16(Bt[n][k], At[m][k], acc[ai][bj][m][n], 0, 0, 0); __builtin_amdgcn_s_setprio(0); } while (0)
; #define PG8_WAIT_V(n) asm volatile("s_waitcnt vmcnt(" #n ")" ::: "memory")
; #define PG8_WAIT_L(n) asm volatile("s_waitcnt lgkmcnt(" #n ")" ::: "memory")
; #define PG8_BAR __builtin_amdgcn_s_barrier()
; #define PG8_SCHED __builtin_amdgcn_sched_barrier(0)
; template <class Epi, class Sched>
; __device__ __forceinline__ void gemm_phase(LAS unsigned char* lds, const Gemm g, const Sched& S, const Epi& E) {
;     ...
;             PG8_LDA(At, 1, 1); PG8_STAGE(PG8_SB(1, 0), b3, voffB); PG8_STAGE(PG8_SB(1, 1), b3 + hsB, voffB); PG8_STAGE(PG8_SA(1, 0), a3, voffA);
;             PG8_WAIT_V(8); PG8_WAIT_L(0); PG8_BAR; PG8_MMA(1, 0, At, B0); PG8_MMA(1, 1, At, B1); PG8_BAR; PG8_SCHED;
;         }
	s_add_i32 s42, s74, s12
	v_lshl_add_u64 v[228:229], v[228:229], 0, s[18:19]
	s_mov_b32 m0, s42
	ds_read_b128 v[180:183], v166 offset:49152
	ds_read_b128 v[184:187], v166 offset:50176
	ds_read_b128 v[188:191], v166 offset:51200
	ds_read_b128 v[208:211], v166 offset:52224
	global_load_lds_dwordx4 v[228:229], off
	s_add_i32 m0, s42, 0x2000
	s_add_u32 s40, s40, 0x40080
	v_lshl_add_u64 v[228:229], v[230:231], 0, s[18:19]
	s_addc_u32 s41, s41, 0
	s_add_i32 s42, s75, s12
	global_load_lds_dwordx4 v[228:229], off
	v_lshl_add_u64 v[228:229], s[40:41], 0, v[0:1]
	s_mov_b32 m0, s42
	ds_read_b128 v[212:215], v166 offset:53248
	global_load_lds_dwordx4 v[228:229], off
	v_lshl_add_u64 v[228:229], s[40:41], 0, v[130:131]
	s_add_i32 m0, s42, 0x2000
	ds_read_b128 v[216:219], v166 offset:54272
	global_load_lds_dwordx4 v[228:229], off
	v_lshl_add_u64 v[228:229], v[232:233], 0, s[18:19]
	s_mov_b32 m0, s1
	ds_read_b128 v[220:223], v166 offset:55296
	global_load_lds_dwordx4 v[228:229], off
	v_lshl_add_u64 v[228:229], v[238:239], 0, s[18:19]
	s_mov_b32 m0, s7
	ds_read_b128 v[224:227], v166 offset:56320
	global_load_lds_dwordx4 v[228:229], off
	s_waitcnt vmcnt(8)
	s_waitcnt lgkmcnt(0)
	s_barrier
	s_waitcnt lgkmcnt(0)
	v_mfma_f32_16x16x32_bf16 v[62:65], v[142:145], v[180:183], v[62:65]
	v_mfma_f32_16x16x32_bf16 v[50:53], v[150:153], v[180:183], v[50:53]
	v_mfma_f32_16x16x32_bf16 v[46:49], v[142:145], v[188:191], v[46:49]
	v_mfma_f32_16x16x32_bf16 v[34:37], v[150:153], v[188:191], v[34:37]
	v_mfma_f32_16x16x32_bf16 v[30:33], v[142:145], v[212:215], v[30:33]
	v_mfma_f32_16x16x32_bf16 v[18:21], v[150:153], v[212:215], v[18:21]
	v_mfma_f32_16x16x32_bf16 v[10:13], v[142:145], v[220:223], v[10:13]
	v_mfma_f32_16x16x32_bf16 v[2:5], v[150:153], v[220:223], v[2:5]
	v_mfma_f32_16x16x32_bf16 v[62:65], v[146:149], v[184:187], v[62:65]
	v_mfma_f32_16x16x32_bf16 v[50:53], v[154:157], v[184:187], v[50:53]
	v_mfma_f32_16x16x32_bf16 v[46:49], v[146:149], v[208:211], v[46:49]
	v_mfma_f32_16x16x32_bf16 v[34:37], v[154:157], v[208:211], v[34:37]
	v_mfma_f32_16x16x32_bf16 v[30:33], v[146:149], v[216:219], v[30:33]
	v_mfma_f32_16x16x32_bf16 v[18:21], v[154:157], v[216:219], v[18:21]
	v_mfma_f32_16x16x32_bf16 v[10:13], v[146:149], v[224:227], v[10:13]
	v_mfma_f32_16x16x32_bf16 v[2:5], v[154:157], v[224:227], v[2:5]
	v_mfma_f32_16x16x32_bf16 v[58:61], v[158:161], v[180:183], v[58:61]
	v_mfma_f32_16x16x32_bf16 v[54:57], v[172:175], v[180:183], v[54:57]
	v_mfma_f32_16x16x32_bf16 v[42:45], v[158:161], v[188:191], v[42:45]
	v_mfma_f32_16x16x32_bf16 v[38:41], v[172:175], v[188:191], v[38:41]
	v_mfma_f32_16x16x32_bf16 v[26:29], v[158:161], v[212:215], v[26:29]
	v_mfma_f32_16x16x32_bf16 v[22:25], v[172:175], v[212:215], v[22:25]
	v_mfma_f32_16x16x32_bf16 v[14:17], v[158:161], v[220:223], v[14:17]
	v_mfma_f32_16x16x32_bf16 v[6:9], v[172:175], v[220:223], v[6:9]
	v_mfma_f32_16x16x32_bf16 v[58:61], v[168:171], v[184:187], v[58:61]
	v_mfma_f32_16x16x32_bf16 v[54:57], v[176:179], v[184:187], v[54:57]
	v_mfma_f32_16x16x32_bf16 v[42:45], v[168:171], v[208:211], v[42:45]
	v_mfma_f32_16x16x32_bf16 v[38:41], v[176:179], v[208:211], v[38:41]
	v_mfma_f32_16x16x32_bf16 v[26:29], v[168:171], v[216:219], v[26:29]
	v_mfma_f32_16x16x32_bf16 v[22:25], v[176:179], v[216:219], v[22:25]
	v_mfma_f32_16x16x32_bf16 v[14:17], v[168:171], v[224:227], v[14:17]
	v_mfma_f32_16x16x32_bf16 v[6:9], v[176:179], v[224:227], v[6:9]
	s_barrier
	s_add_u32 s38, s38, 0x100
	s_addc_u32 s39, s39, 0
	s_add_u32 s83, s83, 0x100
	s_addc_u32 s84, s84, 0
	s_cmp_ge_i32 s85, s11
	s_mov_b32 s40, s85
	s_cbranch_scc0 .LBB0_485
	s_setprio 0

; #define PG8_STAGE(bufoff, gbase, voff) do { _Pragma("unroll") for (int _i = 0; _i < 2; ++_i) \
;         __builtin_amdgcn_global_load_lds((const unsigned*)((const char*)(gbase) + (voff)[_i]), (LAS unsigned*)(lds + (bufoff) + ldsw + _i * 8192), 16, 0, 0); } while (0)
; #define PG8_LDA(dst, b, h) do { _Pragma("unroll") for (int m = 0; m < 4; ++m) _Pragma("unroll") for (int k = 0; k < 2; ++k) dst[m][k] = *(const LAS bf16x8*)(lds + PG8_SA(b, h) + aoff + m * 2048 + k * 1024); } while (0)
; #define PG8_LDB(dst, b, h) do { _Pragma("unroll") for (int n = 0; n < 2; ++n) _Pragma("unroll") for (int k = 0; k < 2; ++k) dst[n][k] = *(const LAS bf16x8*)(lds + PG8_SB(b, h) + boff + n * 2048 + k * 1024); } while (0)
; #define PG8_MMA(ai, bj, At, Bt) do { __builtin_amdgcn_s_setprio(1); _Pragma("unroll") for (int m = 0; m < 4; ++m) _Pragma("unroll") for (int n = 0; n < 2; ++n) _Pragma("unroll") for (int k = 0; k < 2; ++k) \
;         acc[ai][bj][m][n] = __builtin_amdgcn_mfma_f32_16x16x32_bf16(Bt[n][k], At[m][k], acc[ai][bj][m][n], 0, 0, 0); __builtin_amdgcn_s_setprio(0); } while (0)
; #define PG8_WAIT_V(n) asm volatile("s_waitcnt vmcnt(" #n ")" ::: "memory")
; #define PG8_WAIT_L(n) asm volatile("s_waitcnt lgkmcnt(" #n ")" ::: "memory")
; template <class Epi, class Sched>
; __device__ __forceinline__ void gemm_phase(LAS unsigned char* lds, const Gemm g, const Sched& S, const Epi& E) {
;     ...
;             const bool last = (t == nt - 2);
;             const char* a1 = cA + (size_t)(t + 1) * kstep;
;             const char* a2 = last ? nA : cA + (size_t)(t + 2) * kstep; const char* b2 = last ? nB : cB + (size_t)(t + 2) * kstep;
;             const char* a3 = a2 + kstep; const char* b3 = b2 + kstep;
;             if constexpr (Epi::MIDK) { if (t == (nt >> 1)) { int fr_ = fr, fq_ = fq; asm volatile("" : "+v"(fr_), "+v"(fq_)); E.mid(acc, cur, wr, wc, fr_, fq_); } }
;             PG8_LDB(B0, 0, 0); PG8_LDB(B1, 0, 1); PG8_SCHED; PG8_LDA(At, 0, 0); PG8_STAGE(PG8_SA(1, 1), a1 + hsA, voffA);
;             PG8_WAIT_V(8); PG8_WAIT_L(0); PG8_BAR; PG8_MMA(0, 0, At, B0); PG8_MMA(0, 1, At, B1); PG8_BAR; PG8_SCHED;
;             PG8_LDA(At, 0, 1); PG8_STAGE(PG8_SB(0, 0), b2, voffB); PG8_STAGE(PG8_SB(0, 1), b2 + hsB, voffB); PG8_STAGE(PG8_SA(0, 0), a2, voffA);
;             PG8_WAIT_V(8); PG8_WAIT_L(0); PG8_BAR; PG8_MMA(1, 0, At, B0); PG8_MMA(1, 1, At, B1); PG8_BAR; PG8_SCHED;
.Lnp_536:
.LBB0_536:
	s_add_i32 s83, s46, 2
	s_add_u32 s74, s44, 0xfffc0080
	s_addc_u32 s47, s45, -1
	s_add_i32 s75, 0, 0x10000
	s_cmp_eq_u32 s51, s46
	s_cselect_b32 s47, s73, s47
	s_cselect_b32 s46, s76, s74
	v_add_u32_e32 v144, s75, v148
	s_cselect_b32 s85, s77, s82
	s_cselect_b32 s84, s78, s80
	s_add_i32 s74, 0, 0x14000
	ds_read_b128 v[140:143], v144
	ds_read_b128 v[150:153], v144 offset:1024
	ds_read_b128 v[154:157], v144 offset:2048
	ds_read_b128 v[158:161], v144 offset:3072
	v_add_u32_e32 v144, s74, v148
	ds_read_b128 v[162:165], v144
	ds_read_b128 v[166:169], v144 offset:1024
	ds_read_b128 v[170:173], v144 offset:2048
	ds_read_b128 v[174:177], v144 offset:3072
	v_lshl_add_u64 v[144:145], s[44:45], 0, v[136:137]
	s_add_i32 m0, s11, 0xc000
	ds_read_b128 v[178:181], v149
	ds_read_b128 v[182:185], v149 offset:1024
	ds_read_b128 v[186:189], v149 offset:2048
	ds_read_b128 v[208:211], v149 offset:3072
	ds_read_b128 v[212:215], v149 offset:4096
	ds_read_b128 v[216:219], v149 offset:5120
	ds_read_b128 v[220:223], v149 offset:6144
	global_load_lds_dwordx4 v[144:145], off
	v_lshl_add_u64 v[144:145], s[44:45], 0, v[138:139]
	s_add_i32 m0, s11, 0xe000
	ds_read_b128 v[224:227], v149 offset:7168
	global_load_lds_dwordx4 v[144:145], off
	s_waitcnt vmcnt(8)
	s_waitcnt lgkmcnt(0)
	s_barrier
	s_waitcnt lgkmcnt(0)
	v_mfma_f32_16x16x32_bf16 v[122:125], v[140:143], v[178:181], v[122:125]
	v_mfma_f32_16x16x32_bf16 v[126:129], v[154:157], v[178:181], v[126:129]
	v_mfma_f32_16x16x32_bf16 v[110:113], v[140:143], v[186:189], v[110:113]
	v_mfma_f32_16x16x32_bf16 v[106:109], v[154:157], v[186:189], v[106:109]
	v_mfma_f32_16x16x32_bf16 v[94:97], v[140:143], v[212:215], v[94:97]
	v_mfma_f32_16x16x32_bf16 v[90:93], v[154:157], v[212:215], v[90:93]
	v_mfma_f32_16x16x32_bf16 v[78:81], v[140:143], v[220:223], v[78:81]
	v_mfma_f32_16x16x32_bf16 v[74:77], v[154:157], v[220:223], v[74:77]
	v_mfma_f32_16x16x32_bf16 v[122:125], v[150:153], v[182:185], v[122:125]
	v_mfma_f32_16x16x32_bf16 v[126:129], v[158:161], v[182:185], v[126:129]
	v_mfma_f32_16x16x32_bf16 v[110:113], v[150:153], v[208:211], v[110:113]
	v_mfma_f32_16x16x32_bf16 v[106:109], v[158:161], v[208:211], v[106:109]
	v_mfma_f32_16x16x32_bf16 v[94:97], v[150:153], v[216:219], v[94:97]
	v_mfma_f32_16x16x32_bf16 v[90:93], v[158:161], v[216:219], v[90:93]
	v_mfma_f32_16x16x32_bf16 v[78:81], v[150:153], v[224:227], v[78:81]
	v_mfma_f32_16x16x32_bf16 v[74:77], v[158:161], v[224:227], v[74:77]
	v_mfma_f32_16x16x32_bf16 v[118:121], v[162:165], v[178:181], v[118:121]
	v_mfma_f32_16x16x32_bf16 v[114:117], v[170:173], v[178:181], v[114:117]
	v_mfma_f32_16x16x32_bf16 v[102:105], v[162:165], v[186:189], v[102:105]
	v_mfma_f32_16x16x32_bf16 v[98:101], v[170:173], v[186:189], v[98:101]
	v_mfma_f32_16x16x32_bf16 v[86:89], v[162:165], v[212:215], v[86:89]
	v_mfma_f32_16x16x32_bf16 v[82:85], v[170:173], v[212:215], v[82:85]
	v_mfma_f32_16x16x32_bf16 v[70:73], v[162:165], v[220:223], v[70:73]
	v_mfma_f32_16x16x32_bf16 v[66:69], v[170:173], v[220:223], v[66:69]
	v_mfma_f32_16x16x32_bf16 v[118:121], v[166:169], v[182:185], v[118:121]
	v_mfma_f32_16x16x32_bf16 v[114:117], v[174:177], v[182:185], v[114:117]
	v_mfma_f32_16x16x32_bf16 v[102:105], v[166:169], v[208:211], v[102:105]
	v_mfma_f32_16x16x32_bf16 v[98:101], v[174:177], v[208:211], v[98:101]
	v_mfma_f32_16x16x32_bf16 v[86:89], v[166:169], v[216:219], v[86:89]
	v_mfma_f32_16x16x32_bf16 v[82:85], v[174:177], v[216:219], v[82:85]
	v_mfma_f32_16x16x32_bf16 v[70:73], v[166:169], v[224:227], v[70:73]
	v_mfma_f32_16x16x32_bf16 v[66:69], v[174:177], v[224:227], v[66:69]
	s_barrier
	s_add_i32 s75, s75, s7
	v_lshl_add_u64 v[144:145], s[84:85], 0, v[0:1]
	s_mov_b32 m0, s75
	ds_read_b128 v[178:181], v149 offset:16384
	ds_read_b128 v[182:185], v149 offset:17408
	ds_read_b128 v[186:189], v149 offset:18432
	ds_read_b128 v[208:211], v149 offset:19456
	ds_read_b128 v[212:215], v149 offset:20480
	global_load_lds_dwordx4 v[144:145], off
	v_lshl_add_u64 v[190:191], s[84:85], 0, v[130:131]
	s_add_i32 m0, s75, 0x2000
	s_add_i32 s74, s74, s7
	global_load_lds_dwordx4 v[190:191], off
	v_lshl_add_u64 v[228:229], v[144:145], 0, s[22:23]
	s_mov_b32 m0, s74
	v_lshl_add_u64 v[230:231], s[46:47], 0, v[132:133]
	global_load_lds_dwordx4 v[228:229], off
	v_lshl_add_u64 v[228:229], v[190:191], 0, s[22:23]
	s_add_i32 m0, s74, 0x2000
	ds_read_b128 v[216:219], v149 offset:21504
	global_load_lds_dwordx4 v[228:229], off
	v_lshl_add_u64 v[228:229], s[46:47], 0, v[134:135]
	s_mov_b32 m0, s11
	ds_read_b128 v[220:223], v149 offset:22528
	global_load_lds_dwordx4 v[228:229], off
	s_mov_b32 m0, s12
	ds_read_b128 v[224:227], v149 offset:23552
	global_load_lds_dwordx4 v[230:231], off
	s_waitcnt vmcnt(8)
	s_waitcnt lgkmcnt(0)
	s_barrier
; #define PG8_STAGE(bufoff, gbase, voff) do { _Pragma("unroll") for (int _i = 0; _i < 2; ++_i) \
;         __builtin_amdgcn_global_load_lds((const unsigned*)((const char*)(gbase) + (voff)[_i]), (LAS unsigned*)(lds + (bufoff) + ldsw + _i * 8192), 16, 0, 0); } while (0)
; #define PG8_LDA(dst, b, h) do { _Pragma("unroll") for (int m = 0; m < 4; ++m) _Pragma("unroll") for (int k = 0; k < 2; ++k) dst[m][k] = *(const LAS bf16x8*)(lds + PG8_SA(b, h) + aoff + m * 2048 + k * 1024); } while (0)
; #define PG8_LDB(dst, b, h) do { _Pragma("unroll") for (int n = 0; n < 2; ++n) _Pragma("unroll") for (int k = 0; k < 2; ++k) dst[n][k] = *(const LAS bf16x8*)(lds + PG8_SB(b, h) + boff + n * 2048 + k * 1024); } while (0)
; #define PG8_MMA(ai, bj, At, Bt) do { __builtin_amdgcn_s_setprio(1); _Pragma("unroll") for (int m = 0; m < 4; ++m) _Pragma("unroll") for (int n = 0; n < 2; ++n) _Pragma("unroll") for (int k = 0; k < 2; ++k) \
;         acc[ai][bj][m][n] = __builtin_amdgcn_mfma_f32_16x16x32_bf16(Bt[n][k], At[m][k], acc[ai][bj][m][n], 0, 0, 0); __builtin_amdgcn_s_setprio(0); } while (0)
; #define PG8_WAIT_V(n) asm volatile("s_waitcnt vmcnt(" #n ")" ::: "memory")
; #define PG8_WAIT_L(n) asm volatile("s_waitcnt lgkmcnt(" #n ")" ::: "memory")
; #define PG8_BAR __builtin_amdgcn_s_barrier()
; #define PG8_SCHED __builtin_amdgcn_sched_barrier(0)
; template <class Epi, class Sched>
; __device__ __forceinline__ void gemm_phase(LAS unsigned char* lds, const Gemm g, const Sched& S, const Epi& E) {
;     ...
;             PG8_WAIT_V(8); PG8_WAIT_L(0); PG8_BAR; PG8_MMA(1, 0, At, B0); PG8_MMA(1, 1, At, B1); PG8_BAR; PG8_SCHED;
;             PG8_LDB(B0, 1, 0); PG8_LDB(B1, 1, 1); PG8_SCHED; PG8_LDA(At, 1, 0); PG8_STAGE(PG8_SA(0, 1), a2 + hsA, voffA);
;             PG8_WAIT_V(8); PG8_WAIT_L(0); PG8_BAR; PG8_MMA(0, 0, At, B0); PG8_MMA(0, 1, At, B1); PG8_BAR; PG8_SCHED;
	s_waitcnt lgkmcnt(0)
	v_mfma_f32_16x16x32_bf16 v[62:65], v[140:143], v[178:181], v[62:65]
	v_mfma_f32_16x16x32_bf16 v[58:61], v[154:157], v[178:181], v[58:61]
	v_mfma_f32_16x16x32_bf16 v[46:49], v[140:143], v[186:189], v[46:49]
	v_mfma_f32_16x16x32_bf16 v[42:45], v[154:157], v[186:189], v[42:45]
	v_mfma_f32_16x16x32_bf16 v[30:33], v[140:143], v[212:215], v[30:33]
	v_mfma_f32_16x16x32_bf16 v[26:29], v[154:157], v[212:215], v[26:29]
	v_mfma_f32_16x16x32_bf16 v[14:17], v[140:143], v[220:223], v[14:17]
	v_mfma_f32_16x16x32_bf16 v[10:13], v[154:157], v[220:223], v[10:13]
	v_mfma_f32_16x16x32_bf16 v[62:65], v[150:153], v[182:185], v[62:65]
	v_mfma_f32_16x16x32_bf16 v[58:61], v[158:161], v[182:185], v[58:61]
	v_mfma_f32_16x16x32_bf16 v[46:49], v[150:153], v[208:211], v[46:49]
	v_mfma_f32_16x16x32_bf16 v[42:45], v[158:161], v[208:211], v[42:45]
	v_mfma_f32_16x16x32_bf16 v[30:33], v[150:153], v[216:219], v[30:33]
	v_mfma_f32_16x16x32_bf16 v[26:29], v[158:161], v[216:219], v[26:29]
	v_mfma_f32_16x16x32_bf16 v[14:17], v[150:153], v[224:227], v[14:17]
	v_mfma_f32_16x16x32_bf16 v[10:13], v[158:161], v[224:227], v[10:13]
	v_mfma_f32_16x16x32_bf16 v[54:57], v[162:165], v[178:181], v[54:57]
	v_mfma_f32_16x16x32_bf16 v[50:53], v[170:173], v[178:181], v[50:53]
	v_mfma_f32_16x16x32_bf16 v[38:41], v[162:165], v[186:189], v[38:41]
	v_mfma_f32_16x16x32_bf16 v[34:37], v[170:173], v[186:189], v[34:37]
	v_mfma_f32_16x16x32_bf16 v[22:25], v[162:165], v[212:215], v[22:25]
	v_mfma_f32_16x16x32_bf16 v[18:21], v[170:173], v[212:215], v[18:21]
	v_mfma_f32_16x16x32_bf16 v[6:9], v[162:165], v[220:223], v[6:9]
	v_mfma_f32_16x16x32_bf16 v[2:5], v[170:173], v[220:223], v[2:5]
	v_mfma_f32_16x16x32_bf16 v[54:57], v[166:169], v[182:185], v[54:57]
	v_mfma_f32_16x16x32_bf16 v[50:53], v[174:177], v[182:185], v[50:53]
	v_mfma_f32_16x16x32_bf16 v[38:41], v[166:169], v[208:211], v[38:41]
	v_mfma_f32_16x16x32_bf16 v[34:37], v[174:177], v[208:211], v[34:37]
	v_mfma_f32_16x16x32_bf16 v[22:25], v[166:169], v[216:219], v[22:25]
	v_mfma_f32_16x16x32_bf16 v[18:21], v[174:177], v[216:219], v[18:21]
	v_mfma_f32_16x16x32_bf16 v[6:9], v[166:169], v[224:227], v[6:9]
	v_mfma_f32_16x16x32_bf16 v[2:5], v[174:177], v[224:227], v[2:5]
	s_barrier
	s_add_i32 s74, 0, 0x18000
	s_add_i32 s75, 0, 0x1c000
	v_add_u32_e32 v158, s74, v148
	v_add_u32_e32 v174, s75, v148
	ds_read_b128 v[140:143], v158
	ds_read_b128 v[150:153], v158 offset:1024
	ds_read_b128 v[154:157], v158 offset:2048
	ds_read_b128 v[158:161], v158 offset:3072
	ds_read_b128 v[162:165], v174
	ds_read_b128 v[166:169], v174 offset:1024
	ds_read_b128 v[170:173], v174 offset:2048
	ds_read_b128 v[174:177], v174 offset:3072
	s_add_u32 s46, s46, 0x40000
	s_addc_u32 s47, s47, 0
	s_mov_b32 m0, s16
	v_lshl_add_u64 v[232:233], s[46:47], 0, v[134:135]
	ds_read_b128 v[178:181], v149 offset:32768
	ds_read_b128 v[182:185], v149 offset:33792
	ds_read_b128 v[186:189], v149 offset:34816
	ds_read_b128 v[208:211], v149 offset:35840
	ds_read_b128 v[212:215], v149 offset:36864
	ds_read_b128 v[216:219], v149 offset:37888
	ds_read_b128 v[220:223], v149 offset:38912
	global_load_lds_dwordx4 v[232:233], off
	v_lshl_add_u64 v[232:233], s[46:47], 0, v[132:133]
	s_mov_b32 m0, s24
	ds_read_b128 v[224:227], v149 offset:39936
	global_load_lds_dwordx4 v[232:233], off
	s_waitcnt vmcnt(8)
	s_waitcnt lgkmcnt(0)
	s_barrier
	s_waitcnt lgkmcnt(0)
	v_mfma_f32_16x16x32_bf16 v[122:125], v[140:143], v[178:181], v[122:125]
	v_mfma_f32_16x16x32_bf16 v[126:129], v[154:157], v[178:181], v[126:129]
	v_mfma_f32_16x16x32_bf16 v[110:113], v[140:143], v[186:189], v[110:113]
	v_mfma_f32_16x16x32_bf16 v[106:109], v[154:157], v[186:189], v[106:109]
	v_mfma_f32_16x16x32_bf16 v[94:97], v[140:143], v[212:215], v[94:97]
	v_mfma_f32_16x16x32_bf16 v[90:93], v[154:157], v[212:215], v[90:93]
	v_mfma_f32_16x16x32_bf16 v[78:81], v[140:143], v[220:223], v[78:81]
	v_mfma_f32_16x16x32_bf16 v[74:77], v[154:157], v[220:223], v[74:77]
	v_mfma_f32_16x16x32_bf16 v[122:125], v[150:153], v[182:185], v[122:125]
	v_mfma_f32_16x16x32_bf16 v[126:129], v[158:161], v[182:185], v[126:129]
	v_mfma_f32_16x16x32_bf16 v[110:113], v[150:153], v[208:211], v[110:113]
	v_mfma_f32_16x16x32_bf16 v[106:109], v[158:161], v[208:211], v[106:109]
	v_mfma_f32_16x16x32_bf16 v[94:97], v[150:153], v[216:219], v[94:97]
	v_mfma_f32_16x16x32_bf16 v[90:93], v[158:161], v[216:219], v[90:93]
	v_mfma_f32_16x16x32_bf16 v[78:81], v[150:153], v[224:227], v[78:81]
	v_mfma_f32_16x16x32_bf16 v[74:77], v[158:161], v[224:227], v[74:77]
	v_mfma_f32_16x16x32_bf16 v[118:121], v[162:165], v[178:181], v[118:121]
	v_mfma_f32_16x16x32_bf16 v[114:117], v[170:173], v[178:181], v[114:117]
	v_mfma_f32_16x16x32_bf16 v[102:105], v[162:165], v[186:189], v[102:105]
	v_mfma_f32_16x16x32_bf16 v[98:101], v[170:173], v[186:189], v[98:101]
	v_mfma_f32_16x16x32_bf16 v[86:89], v[162:165], v[212:215], v[86:89]
	v_mfma_f32_16x16x32_bf16 v[82:85], v[170:173], v[212:215], v[82:85]
	v_mfma_f32_16x16x32_bf16 v[70:73], v[162:165], v[220:223], v[70:73]
	v_mfma_f32_16x16x32_bf16 v[66:69], v[170:173], v[220:223], v[66:69]
	v_mfma_f32_16x16x32_bf16 v[118:121], v[166:169], v[182:185], v[118:121]
	v_mfma_f32_16x16x32_bf16 v[114:117], v[174:177], v[182:185], v[114:117]
	v_mfma_f32_16x16x32_bf16 v[102:105], v[166:169], v[208:211], v[102:105]
	v_mfma_f32_16x16x32_bf16 v[98:101], v[174:177], v[208:211], v[98:101]
	v_mfma_f32_16x16x32_bf16 v[86:89], v[166:169], v[216:219], v[86:89]
	v_mfma_f32_16x16x32_bf16 v[82:85], v[174:177], v[216:219], v[82:85]
	v_mfma_f32_16x16x32_bf16 v[70:73], v[166:169], v[224:227], v[70:73]
	v_mfma_f32_16x16x32_bf16 v[66:69], v[174:177], v[224:227], v[66:69]
	s_barrier
; #define PG8_STAGE(bufoff, gbase, voff) do { _Pragma("unroll") for (int _i = 0; _i < 2; ++_i) \
;         __builtin_amdgcn_global_load_lds((const unsigned*)((const char*)(gbase) + (voff)[_i]), (LAS unsigned*)(lds + (bufoff) + ldsw + _i * 8192), 16, 0, 0); } while (0)
; #define PG8_LDA(dst, b, h) do { _Pragma("unroll") for (int m = 0; m < 4; ++m) _Pragma("unroll") for (int k = 0; k < 2; ++k) dst[m][k] = *(const LAS bf16x8*)(lds + PG8_SA(b, h) + aoff + m * 2048 + k * 1024); } while (0)
; #define PG8_MMA(ai, bj, At, Bt) do { __builtin_amdgcn_s_setprio(1); _Pragma("unroll") for (int m = 0; m < 4; ++m) _Pragma("unroll") for (int n = 0; n < 2; ++n) _Pragma("unroll") for (int k = 0; k < 2; ++k) \
;         acc[ai][bj][m][n] = __builtin_amdgcn_mfma_f32_16x16x32_bf16(Bt[n][k], At[m][k], acc[ai][bj][m][n], 0, 0, 0); __builtin_amdgcn_s_setprio(0); } while (0)
; #define PG8_WAIT_V(n) asm volatile("s_waitcnt vmcnt(" #n ")" ::: "memory")
; #define PG8_WAIT_L(n) asm volatile("s_waitcnt lgkmcnt(" #n ")" ::: "memory")
; #define PG8_BAR __builtin_amdgcn_s_barrier()
; #define PG8_SCHED __builtin_amdgcn_sched_barrier(0)
; template <class Epi, class Sched>
; __device__ __forceinline__ void gemm_phase(LAS unsigned char* lds, const Gemm g, const Sched& S, const Epi& E) {
;     ...
;             PG8_LDA(At, 1, 1); PG8_STAGE(PG8_SB(1, 0), b3, voffB); PG8_STAGE(PG8_SB(1, 1), b3 + hsB, voffB); PG8_STAGE(PG8_SA(1, 0), a3, voffA);
;             PG8_WAIT_V(8); PG8_WAIT_L(0); PG8_BAR; PG8_MMA(1, 0, At, B0); PG8_MMA(1, 1, At, B1); PG8_BAR; PG8_SCHED;
;         }
	s_add_i32 s46, s74, s7
	v_lshl_add_u64 v[232:233], v[144:145], 0, s[18:19]
	s_mov_b32 m0, s46
	ds_read_b128 v[178:181], v149 offset:49152
	ds_read_b128 v[182:185], v149 offset:50176
	ds_read_b128 v[186:189], v149 offset:51200
	ds_read_b128 v[208:211], v149 offset:52224
	global_load_lds_dwordx4 v[232:233], off
	v_lshl_add_u64 v[232:233], v[190:191], 0, s[18:19]
	s_add_i32 m0, s46, 0x2000
	s_add_i32 s46, s75, s7
	global_load_lds_dwordx4 v[232:233], off
	v_lshl_add_u64 v[144:145], v[144:145], 0, vcc
	s_mov_b32 m0, s46
	ds_read_b128 v[212:215], v149 offset:53248
	global_load_lds_dwordx4 v[144:145], off
	v_lshl_add_u64 v[144:145], v[190:191], 0, vcc
	s_add_i32 m0, s46, 0x2000
	ds_read_b128 v[216:219], v149 offset:54272
	global_load_lds_dwordx4 v[144:145], off
	v_lshl_add_u64 v[144:145], v[228:229], 0, s[18:19]
	s_mov_b32 m0, s49
	ds_read_b128 v[220:223], v149 offset:55296
	global_load_lds_dwordx4 v[144:145], off
	v_lshl_add_u64 v[144:145], v[230:231], 0, s[18:19]
	s_mov_b32 m0, s50
	ds_read_b128 v[224:227], v149 offset:56320
	global_load_lds_dwordx4 v[144:145], off
	s_waitcnt vmcnt(8)
	s_waitcnt lgkmcnt(0)
	s_barrier
	s_waitcnt lgkmcnt(0)
	v_mfma_f32_16x16x32_bf16 v[62:65], v[140:143], v[178:181], v[62:65]
	v_mfma_f32_16x16x32_bf16 v[58:61], v[154:157], v[178:181], v[58:61]
	v_mfma_f32_16x16x32_bf16 v[46:49], v[140:143], v[186:189], v[46:49]
	v_mfma_f32_16x16x32_bf16 v[42:45], v[154:157], v[186:189], v[42:45]
	v_mfma_f32_16x16x32_bf16 v[30:33], v[140:143], v[212:215], v[30:33]
	v_mfma_f32_16x16x32_bf16 v[26:29], v[154:157], v[212:215], v[26:29]
	v_mfma_f32_16x16x32_bf16 v[14:17], v[140:143], v[220:223], v[14:17]
	v_mfma_f32_16x16x32_bf16 v[10:13], v[154:157], v[220:223], v[10:13]
	v_mfma_f32_16x16x32_bf16 v[62:65], v[150:153], v[182:185], v[62:65]
	v_mfma_f32_16x16x32_bf16 v[58:61], v[158:161], v[182:185], v[58:61]
	v_mfma_f32_16x16x32_bf16 v[46:49], v[150:153], v[208:211], v[46:49]
	v_mfma_f32_16x16x32_bf16 v[42:45], v[158:161], v[208:211], v[42:45]
	v_mfma_f32_16x16x32_bf16 v[30:33], v[150:153], v[216:219], v[30:33]
	v_mfma_f32_16x16x32_bf16 v[26:29], v[158:161], v[216:219], v[26:29]
	v_mfma_f32_16x16x32_bf16 v[14:17], v[150:153], v[224:227], v[14:17]
	v_mfma_f32_16x16x32_bf16 v[10:13], v[158:161], v[224:227], v[10:13]
	v_mfma_f32_16x16x32_bf16 v[54:57], v[162:165], v[178:181], v[54:57]
	v_mfma_f32_16x16x32_bf16 v[50:53], v[170:173], v[178:181], v[50:53]
	v_mfma_f32_16x16x32_bf16 v[38:41], v[162:165], v[186:189], v[38:41]
	v_mfma_f32_16x16x32_bf16 v[34:37], v[170:173], v[186:189], v[34:37]
	v_mfma_f32_16x16x32_bf16 v[22:25], v[162:165], v[212:215], v[22:25]
	v_mfma_f32_16x16x32_bf16 v[18:21], v[170:173], v[212:215], v[18:21]
	v_mfma_f32_16x16x32_bf16 v[6:9], v[162:165], v[220:223], v[6:9]
	v_mfma_f32_16x16x32_bf16 v[2:5], v[170:173], v[220:223], v[2:5]
	v_mfma_f32_16x16x32_bf16 v[54:57], v[166:169], v[182:185], v[54:57]
	v_mfma_f32_16x16x32_bf16 v[50:53], v[174:177], v[182:185], v[50:53]
	v_mfma_f32_16x16x32_bf16 v[38:41], v[166:169], v[208:211], v[38:41]
	v_mfma_f32_16x16x32_bf16 v[34:37], v[174:177], v[208:211], v[34:37]
	v_mfma_f32_16x16x32_bf16 v[22:25], v[166:169], v[216:219], v[22:25]
	v_mfma_f32_16x16x32_bf16 v[18:21], v[174:177], v[216:219], v[18:21]
	v_mfma_f32_16x16x32_bf16 v[6:9], v[166:169], v[224:227], v[6:9]
	v_mfma_f32_16x16x32_bf16 v[2:5], v[174:177], v[224:227], v[2:5]
	s_barrier
	s_add_u32 s44, s44, 0x100
	s_addc_u32 s45, s45, 0
	s_add_u32 s80, s80, 0x100
	s_addc_u32 s82, s82, 0
	s_cmp_ge_i32 s83, s26
	s_mov_b32 s46, s83
	s_cbranch_scc0 .LBB0_536
	s_setprio 0
	v_readlane_b32 s82, v254, 45
	v_readlane_b32 s83, v254, 46

; #define PG8_STAGE(bufoff, gbase, voff) do { _Pragma("unroll") for (int _i = 0; _i < 2; ++_i) \
;         __builtin_amdgcn_global_load_lds((const unsigned*)((const char*)(gbase) + (voff)[_i]), (LAS unsigned*)(lds + (bufoff) + ldsw + _i * 8192), 16, 0, 0); } while (0)
; #define PG8_LDA(dst, b, h) do { _Pragma("unroll") for (int m = 0; m < 4; ++m) _Pragma("unroll") for (int k = 0; k < 2; ++k) dst[m][k] = *(const LAS bf16x8*)(lds + PG8_SA(b, h) + aoff + m * 2048 + k * 1024); } while (0)
; #define PG8_LDB(dst, b, h) do { _Pragma("unroll") for (int n = 0; n < 2; ++n) _Pragma("unroll") for (int k = 0; k < 2; ++k) dst[n][k] = *(const LAS bf16x8*)(lds + PG8_SB(b, h) + boff + n * 2048 + k * 1024); } while (0)
; #define PG8_MMA(ai, bj, At, Bt) do { __builtin_amdgcn_s_setprio(1); _Pragma("unroll") for (int m = 0; m < 4; ++m) _Pragma("unroll") for (int n = 0; n < 2; ++n) _Pragma("unroll") for (int k = 0; k < 2; ++k) \
;         acc[ai][bj][m][n] = __builtin_amdgcn_mfma_f32_16x16x32_bf16(Bt[n][k], At[m][k], acc[ai][bj][m][n], 0, 0, 0); __builtin_amdgcn_s_setprio(0); } while (0)
; #define PG8_WAIT_V(n) asm volatile("s_waitcnt vmcnt(" #n ")" ::: "memory")
; #define PG8_WAIT_L(n) asm volatile("s_waitcnt lgkmcnt(" #n ")" ::: "memory")
; template <class Epi, class Sched>
; __device__ __forceinline__ void gemm_phase(LAS unsigned char* lds, const Gemm g, const Sched& S, const Epi& E) {
;     ...
;             const bool last = (t == nt - 2);
;             const char* a1 = cA + (size_t)(t + 1) * kstep;
;             const char* a2 = last ? nA : cA + (size_t)(t + 2) * kstep; const char* b2 = last ? nB : cB + (size_t)(t + 2) * kstep;
;             const char* a3 = a2 + kstep; const char* b3 = b2 + kstep;
;             if constexpr (Epi::MIDK) { if (t == (nt >> 1)) { int fr_ = fr, fq_ = fq; asm volatile("" : "+v"(fr_), "+v"(fq_)); E.mid(acc, cur, wr, wc, fr_, fq_); } }
;             PG8_LDB(B0, 0, 0); PG8_LDB(B1, 0, 1); PG8_SCHED; PG8_LDA(At, 0, 0); PG8_STAGE(PG8_SA(1, 1), a1 + hsA, voffA);
;             PG8_WAIT_V(8); PG8_WAIT_L(0); PG8_BAR; PG8_MMA(0, 0, At, B0); PG8_MMA(0, 1, At, B1); PG8_BAR; PG8_SCHED;
;             PG8_LDA(At, 0, 1); PG8_STAGE(PG8_SB(0, 0), b2, voffB); PG8_STAGE(PG8_SB(0, 1), b2 + hsB, voffB); PG8_STAGE(PG8_SA(0, 0), a2, voffA);
;             PG8_WAIT_V(8); PG8_WAIT_L(0); PG8_BAR; PG8_MMA(1, 0, At, B0); PG8_MMA(1, 1, At, B1); PG8_BAR; PG8_SCHED;
.Lnp_637:
.LBB0_637:
	s_add_i32 s0, s46, 2
	s_add_u32 s44, s42, 0x100
	s_addc_u32 s45, s43, 0
	s_add_u32 s1, s77, s42
	s_addc_u32 s22, s78, s43
	s_cmp_eq_u32 s56, s46
	s_cselect_b32 s48, 0, s44
	s_cselect_b32 s23, 0, s45
	s_cselect_b32 s46, s76, s1
	s_cselect_b32 s47, s73, s22
	s_add_u32 s48, s58, s48
	s_addc_u32 s49, s59, s23
	s_add_i32 s1, 0, 0x10000
	v_add_u32_e32 v0, s1, v152
	s_add_i32 s22, 0, 0x14000
	ds_read_b128 v[142:145], v0
	ds_read_b128 v[146:149], v0 offset:1024
	ds_read_b128 v[154:157], v0 offset:2048
	ds_read_b128 v[158:161], v0 offset:3072
	v_add_u32_e32 v0, s22, v152
	ds_read_b128 v[162:165], v0
	ds_read_b128 v[166:169], v0 offset:1024
	ds_read_b128 v[170:173], v0 offset:2048
	ds_read_b128 v[174:177], v0 offset:3072
	v_lshl_add_u64 v[190:191], v[138:139], 0, s[42:43]
	s_add_i32 m0, s11, 0xc000
	ds_read_b128 v[178:181], v153
	ds_read_b128 v[182:185], v153 offset:1024
	ds_read_b128 v[186:189], v153 offset:2048
	ds_read_b128 v[208:211], v153 offset:3072
	ds_read_b128 v[212:215], v153 offset:4096
	ds_read_b128 v[216:219], v153 offset:5120
	ds_read_b128 v[220:223], v153 offset:6144
	global_load_lds_dwordx4 v[190:191], off
	v_lshl_add_u64 v[190:191], v[140:141], 0, s[42:43]
	s_add_i32 m0, s11, 0xe000
	ds_read_b128 v[224:227], v153 offset:7168
	global_load_lds_dwordx4 v[190:191], off
	s_waitcnt vmcnt(8)
	s_waitcnt lgkmcnt(0)
	s_barrier
	s_waitcnt lgkmcnt(0)
	v_mfma_f32_16x16x32_bf16 v[126:129], v[142:145], v[178:181], v[126:129]
	v_mfma_f32_16x16x32_bf16 v[118:121], v[154:157], v[178:181], v[118:121]
	v_mfma_f32_16x16x32_bf16 v[94:97], v[142:145], v[186:189], v[94:97]
	v_mfma_f32_16x16x32_bf16 v[86:89], v[154:157], v[186:189], v[86:89]
	v_mfma_f32_16x16x32_bf16 v[62:65], v[142:145], v[212:215], v[62:65]
	v_mfma_f32_16x16x32_bf16 v[54:57], v[154:157], v[212:215], v[54:57]
	v_mfma_f32_16x16x32_bf16 v[30:33], v[142:145], v[220:223], v[30:33]
	v_mfma_f32_16x16x32_bf16 v[22:25], v[154:157], v[220:223], v[22:25]
	v_mfma_f32_16x16x32_bf16 v[126:129], v[146:149], v[182:185], v[126:129]
	v_mfma_f32_16x16x32_bf16 v[118:121], v[158:161], v[182:185], v[118:121]
	v_mfma_f32_16x16x32_bf16 v[94:97], v[146:149], v[208:211], v[94:97]
	v_mfma_f32_16x16x32_bf16 v[86:89], v[158:161], v[208:211], v[86:89]
	v_mfma_f32_16x16x32_bf16 v[62:65], v[146:149], v[216:219], v[62:65]
	v_mfma_f32_16x16x32_bf16 v[54:57], v[158:161], v[216:219], v[54:57]
	v_mfma_f32_16x16x32_bf16 v[30:33], v[146:149], v[224:227], v[30:33]
	v_mfma_f32_16x16x32_bf16 v[22:25], v[158:161], v[224:227], v[22:25]
	v_mfma_f32_16x16x32_bf16 v[110:113], v[162:165], v[178:181], v[110:113]
	v_mfma_f32_16x16x32_bf16 v[102:105], v[170:173], v[178:181], v[102:105]
	v_mfma_f32_16x16x32_bf16 v[78:81], v[162:165], v[186:189], v[78:81]
	v_mfma_f32_16x16x32_bf16 v[70:73], v[170:173], v[186:189], v[70:73]
	v_mfma_f32_16x16x32_bf16 v[46:49], v[162:165], v[212:215], v[46:49]
	v_mfma_f32_16x16x32_bf16 v[38:41], v[170:173], v[212:215], v[38:41]
	v_mfma_f32_16x16x32_bf16 v[14:17], v[162:165], v[220:223], v[14:17]
	v_mfma_f32_16x16x32_bf16 v[6:9], v[170:173], v[220:223], v[6:9]
	v_mfma_f32_16x16x32_bf16 v[110:113], v[166:169], v[182:185], v[110:113]
	v_mfma_f32_16x16x32_bf16 v[102:105], v[174:177], v[182:185], v[102:105]
	v_mfma_f32_16x16x32_bf16 v[78:81], v[166:169], v[208:211], v[78:81]
	v_mfma_f32_16x16x32_bf16 v[70:73], v[174:177], v[208:211], v[70:73]
	v_mfma_f32_16x16x32_bf16 v[46:49], v[166:169], v[216:219], v[46:49]
	v_mfma_f32_16x16x32_bf16 v[38:41], v[174:177], v[216:219], v[38:41]
	v_mfma_f32_16x16x32_bf16 v[14:17], v[166:169], v[224:227], v[14:17]
	v_mfma_f32_16x16x32_bf16 v[6:9], v[174:177], v[224:227], v[6:9]
	s_barrier
	s_add_i32 s1, s1, s7
	v_lshl_add_u64 v[190:191], s[46:47], 0, v[134:135]
	s_mov_b32 m0, s1
	ds_read_b128 v[178:181], v153 offset:16384
	ds_read_b128 v[182:185], v153 offset:17408
	ds_read_b128 v[186:189], v153 offset:18432
	ds_read_b128 v[208:211], v153 offset:19456
	ds_read_b128 v[212:215], v153 offset:20480
	global_load_lds_dwordx4 v[190:191], off
	s_add_i32 m0, s1, 0x2000
	s_add_u32 s42, s46, 0x10000
	v_lshl_add_u64 v[228:229], s[46:47], 0, v[130:131]
	s_addc_u32 s43, s47, 0
	s_add_i32 s1, s22, s7
	global_load_lds_dwordx4 v[228:229], off
	v_lshl_add_u64 v[230:231], s[42:43], 0, v[134:135]
	s_mov_b32 m0, s1
	v_lshl_add_u64 v[232:233], s[48:49], 0, v[132:133]
	global_load_lds_dwordx4 v[230:231], off
	v_lshl_add_u64 v[230:231], s[42:43], 0, v[130:131]
	s_add_i32 m0, s1, 0x2000
	ds_read_b128 v[216:219], v153 offset:21504
	global_load_lds_dwordx4 v[230:231], off
	v_lshl_add_u64 v[230:231], s[48:49], 0, v[136:137]
	s_mov_b32 m0, s11
	ds_read_b128 v[220:223], v153 offset:22528
	global_load_lds_dwordx4 v[230:231], off
	s_mov_b32 m0, s12
	ds_read_b128 v[224:227], v153 offset:23552
	global_load_lds_dwordx4 v[232:233], off
	s_waitcnt vmcnt(8)
	s_waitcnt lgkmcnt(0)
	s_barrier
; #define PG8_STAGE(bufoff, gbase, voff) do { _Pragma("unroll") for (int _i = 0; _i < 2; ++_i) \
;         __builtin_amdgcn_global_load_lds((const unsigned*)((const char*)(gbase) + (voff)[_i]), (LAS unsigned*)(lds + (bufoff) + ldsw + _i * 8192), 16, 0, 0); } while (0)
; #define PG8_LDA(dst, b, h) do { _Pragma("unroll") for (int m = 0; m < 4; ++m) _Pragma("unroll") for (int k = 0; k < 2; ++k) dst[m][k] = *(const LAS bf16x8*)(lds + PG8_SA(b, h) + aoff + m * 2048 + k * 1024); } while (0)
; #define PG8_LDB(dst, b, h) do { _Pragma("unroll") for (int n = 0; n < 2; ++n) _Pragma("unroll") for (int k = 0; k < 2; ++k) dst[n][k] = *(const LAS bf16x8*)(lds + PG8_SB(b, h) + boff + n * 2048 + k * 1024); } while (0)
; #define PG8_MMA(ai, bj, At, Bt) do { __builtin_amdgcn_s_setprio(1); _Pragma("unroll") for (int m = 0; m < 4; ++m) _Pragma("unroll") for (int n = 0; n < 2; ++n) _Pragma("unroll") for (int k = 0; k < 2; ++k) \
;         acc[ai][bj][m][n] = __builtin_amdgcn_mfma_f32_16x16x32_bf16(Bt[n][k], At[m][k], acc[ai][bj][m][n], 0, 0, 0); __builtin_amdgcn_s_setprio(0); } while (0)
; #define PG8_WAIT_V(n) asm volatile("s_waitcnt vmcnt(" #n ")" ::: "memory")
; #define PG8_WAIT_L(n) asm volatile("s_waitcnt lgkmcnt(" #n ")" ::: "memory")
; #define PG8_BAR __builtin_amdgcn_s_barrier()
; #define PG8_SCHED __builtin_amdgcn_sched_barrier(0)
; template <class Epi, class Sched>
; __device__ __forceinline__ void gemm_phase(LAS unsigned char* lds, const Gemm g, const Sched& S, const Epi& E) {
;     ...
;             PG8_WAIT_V(8); PG8_WAIT_L(0); PG8_BAR; PG8_MMA(1, 0, At, B0); PG8_MMA(1, 1, At, B1); PG8_BAR; PG8_SCHED;
;             PG8_LDB(B0, 1, 0); PG8_LDB(B1, 1, 1); PG8_SCHED; PG8_LDA(At, 1, 0); PG8_STAGE(PG8_SA(0, 1), a2 + hsA, voffA);
;             PG8_WAIT_V(8); PG8_WAIT_L(0); PG8_BAR; PG8_MMA(0, 0, At, B0); PG8_MMA(0, 1, At, B1); PG8_BAR; PG8_SCHED;
	s_waitcnt lgkmcnt(0)
	v_mfma_f32_16x16x32_bf16 v[122:125], v[142:145], v[178:181], v[122:125]
	v_mfma_f32_16x16x32_bf16 v[114:117], v[154:157], v[178:181], v[114:117]
	v_mfma_f32_16x16x32_bf16 v[90:93], v[142:145], v[186:189], v[90:93]
	v_mfma_f32_16x16x32_bf16 v[82:85], v[154:157], v[186:189], v[82:85]
	v_mfma_f32_16x16x32_bf16 v[58:61], v[142:145], v[212:215], v[58:61]
	v_mfma_f32_16x16x32_bf16 v[50:53], v[154:157], v[212:215], v[50:53]
	v_mfma_f32_16x16x32_bf16 v[26:29], v[142:145], v[220:223], v[26:29]
	v_mfma_f32_16x16x32_bf16 v[18:21], v[154:157], v[220:223], v[18:21]
	v_mfma_f32_16x16x32_bf16 v[122:125], v[146:149], v[182:185], v[122:125]
	v_mfma_f32_16x16x32_bf16 v[114:117], v[158:161], v[182:185], v[114:117]
	v_mfma_f32_16x16x32_bf16 v[90:93], v[146:149], v[208:211], v[90:93]
	v_mfma_f32_16x16x32_bf16 v[82:85], v[158:161], v[208:211], v[82:85]
	v_mfma_f32_16x16x32_bf16 v[58:61], v[146:149], v[216:219], v[58:61]
	v_mfma_f32_16x16x32_bf16 v[50:53], v[158:161], v[216:219], v[50:53]
	v_mfma_f32_16x16x32_bf16 v[26:29], v[146:149], v[224:227], v[26:29]
	v_mfma_f32_16x16x32_bf16 v[18:21], v[158:161], v[224:227], v[18:21]
	v_mfma_f32_16x16x32_bf16 v[106:109], v[162:165], v[178:181], v[106:109]
	v_mfma_f32_16x16x32_bf16 v[98:101], v[170:173], v[178:181], v[98:101]
	v_mfma_f32_16x16x32_bf16 v[74:77], v[162:165], v[186:189], v[74:77]
	v_mfma_f32_16x16x32_bf16 v[66:69], v[170:173], v[186:189], v[66:69]
	v_mfma_f32_16x16x32_bf16 v[42:45], v[162:165], v[212:215], v[42:45]
	v_mfma_f32_16x16x32_bf16 v[34:37], v[170:173], v[212:215], v[34:37]
	v_mfma_f32_16x16x32_bf16 v[10:13], v[162:165], v[220:223], v[10:13]
	v_mfma_f32_16x16x32_bf16 v[2:5], v[170:173], v[220:223], v[2:5]
	v_mfma_f32_16x16x32_bf16 v[106:109], v[166:169], v[182:185], v[106:109]
	v_mfma_f32_16x16x32_bf16 v[98:101], v[174:177], v[182:185], v[98:101]
	v_mfma_f32_16x16x32_bf16 v[74:77], v[166:169], v[208:211], v[74:77]
	v_mfma_f32_16x16x32_bf16 v[66:69], v[174:177], v[208:211], v[66:69]
	v_mfma_f32_16x16x32_bf16 v[42:45], v[166:169], v[216:219], v[42:45]
	v_mfma_f32_16x16x32_bf16 v[34:37], v[174:177], v[216:219], v[34:37]
	v_mfma_f32_16x16x32_bf16 v[10:13], v[166:169], v[224:227], v[10:13]
	v_mfma_f32_16x16x32_bf16 v[2:5], v[174:177], v[224:227], v[2:5]
	s_barrier
	s_add_i32 s1, 0, 0x18000
	v_add_u32_e32 v0, s1, v152
	s_add_i32 s22, 0, 0x1c000
	ds_read_b128 v[142:145], v0
	ds_read_b128 v[146:149], v0 offset:1024
	ds_read_b128 v[154:157], v0 offset:2048
	ds_read_b128 v[158:161], v0 offset:3072
	v_add_u32_e32 v0, s22, v152
	ds_read_b128 v[162:165], v0
	ds_read_b128 v[166:169], v0 offset:1024
	ds_read_b128 v[170:173], v0 offset:2048
	ds_read_b128 v[174:177], v0 offset:3072
	s_add_u32 s42, s48, 0x10000
	s_addc_u32 s43, s49, 0
	s_mov_b32 m0, s16
	v_lshl_add_u64 v[238:239], s[42:43], 0, v[136:137]
	ds_read_b128 v[178:181], v153 offset:32768
	ds_read_b128 v[182:185], v153 offset:33792
	ds_read_b128 v[186:189], v153 offset:34816
	ds_read_b128 v[208:211], v153 offset:35840
	ds_read_b128 v[212:215], v153 offset:36864
	ds_read_b128 v[216:219], v153 offset:37888
	ds_read_b128 v[220:223], v153 offset:38912
	global_load_lds_dwordx4 v[238:239], off
	v_lshl_add_u64 v[238:239], s[42:43], 0, v[132:133]
	s_mov_b32 m0, s24
	ds_read_b128 v[224:227], v153 offset:39936
	global_load_lds_dwordx4 v[238:239], off
	s_waitcnt vmcnt(8)
	s_waitcnt lgkmcnt(0)
	s_barrier
	s_waitcnt lgkmcnt(0)
	v_mfma_f32_16x16x32_bf16 v[126:129], v[142:145], v[178:181], v[126:129]
	v_mfma_f32_16x16x32_bf16 v[118:121], v[154:157], v[178:181], v[118:121]
	v_mfma_f32_16x16x32_bf16 v[94:97], v[142:145], v[186:189], v[94:97]
	v_mfma_f32_16x16x32_bf16 v[86:89], v[154:157], v[186:189], v[86:89]
	v_mfma_f32_16x16x32_bf16 v[62:65], v[142:145], v[212:215], v[62:65]
	v_mfma_f32_16x16x32_bf16 v[54:57], v[154:157], v[212:215], v[54:57]
	v_mfma_f32_16x16x32_bf16 v[30:33], v[142:145], v[220:223], v[30:33]
	v_mfma_f32_16x16x32_bf16 v[22:25], v[154:157], v[220:223], v[22:25]
	v_mfma_f32_16x16x32_bf16 v[126:129], v[146:149], v[182:185], v[126:129]
	v_mfma_f32_16x16x32_bf16 v[118:121], v[158:161], v[182:185], v[118:121]
	v_mfma_f32_16x16x32_bf16 v[94:97], v[146:149], v[208:211], v[94:97]
	v_mfma_f32_16x16x32_bf16 v[86:89], v[158:161], v[208:211], v[86:89]
	v_mfma_f32_16x16x32_bf16 v[62:65], v[146:149], v[216:219], v[62:65]
	v_mfma_f32_16x16x32_bf16 v[54:57], v[158:161], v[216:219], v[54:57]
	v_mfma_f32_16x16x32_bf16 v[30:33], v[146:149], v[224:227], v[30:33]
	v_mfma_f32_16x16x32_bf16 v[22:25], v[158:161], v[224:227], v[22:25]
	v_mfma_f32_16x16x32_bf16 v[110:113], v[162:165], v[178:181], v[110:113]
	v_mfma_f32_16x16x32_bf16 v[102:105], v[170:173], v[178:181], v[102:105]
	v_mfma_f32_16x16x32_bf16 v[78:81], v[162:165], v[186:189], v[78:81]
	v_mfma_f32_16x16x32_bf16 v[70:73], v[170:173], v[186:189], v[70:73]
	v_mfma_f32_16x16x32_bf16 v[46:49], v[162:165], v[212:215], v[46:49]
	v_mfma_f32_16x16x32_bf16 v[38:41], v[170:173], v[212:215], v[38:41]
	v_mfma_f32_16x16x32_bf16 v[14:17], v[162:165], v[220:223], v[14:17]
	v_mfma_f32_16x16x32_bf16 v[6:9], v[170:173], v[220:223], v[6:9]
	v_mfma_f32_16x16x32_bf16 v[110:113], v[166:169], v[182:185], v[110:113]
	v_mfma_f32_16x16x32_bf16 v[102:105], v[174:177], v[182:185], v[102:105]
	v_mfma_f32_16x16x32_bf16 v[78:81], v[166:169], v[208:211], v[78:81]
	v_mfma_f32_16x16x32_bf16 v[70:73], v[174:177], v[208:211], v[70:73]
	v_mfma_f32_16x16x32_bf16 v[46:49], v[166:169], v[216:219], v[46:49]
	v_mfma_f32_16x16x32_bf16 v[38:41], v[174:177], v[216:219], v[38:41]
	v_mfma_f32_16x16x32_bf16 v[14:17], v[166:169], v[224:227], v[14:17]
	v_mfma_f32_16x16x32_bf16 v[6:9], v[174:177], v[224:227], v[6:9]
	s_barrier
; #define PG8_STAGE(bufoff, gbase, voff) do { _Pragma("unroll") for (int _i = 0; _i < 2; ++_i) \
;         __builtin_amdgcn_global_load_lds((const unsigned*)((const char*)(gbase) + (voff)[_i]), (LAS unsigned*)(lds + (bufoff) + ldsw + _i * 8192), 16, 0, 0); } while (0)
; #define PG8_LDA(dst, b, h) do { _Pragma("unroll") for (int m = 0; m < 4; ++m) _Pragma("unroll") for (int k = 0; k < 2; ++k) dst[m][k] = *(const LAS bf16x8*)(lds + PG8_SA(b, h) + aoff + m * 2048 + k * 1024); } while (0)
; #define PG8_MMA(ai, bj, At, Bt) do { __builtin_amdgcn_s_setprio(1); _Pragma("unroll") for (int m = 0; m < 4; ++m) _Pragma("unroll") for (int n = 0; n < 2; ++n) _Pragma("unroll") for (int k = 0; k < 2; ++k) \
;         acc[ai][bj][m][n] = __builtin_amdgcn_mfma_f32_16x16x32_bf16(Bt[n][k], At[m][k], acc[ai][bj][m][n], 0, 0, 0); __builtin_amdgcn_s_setprio(0); } while (0)
; #define PG8_WAIT_V(n) asm volatile("s_waitcnt vmcnt(" #n ")" ::: "memory")
; #define PG8_WAIT_L(n) asm volatile("s_waitcnt lgkmcnt(" #n ")" ::: "memory")
; #define PG8_BAR __builtin_amdgcn_s_barrier()
; #define PG8_SCHED __builtin_amdgcn_sched_barrier(0)
; template <class Epi, class Sched>
; __device__ __forceinline__ void gemm_phase(LAS unsigned char* lds, const Gemm g, const Sched& S, const Epi& E) {
;     ...
;             PG8_LDA(At, 1, 1); PG8_STAGE(PG8_SB(1, 0), b3, voffB); PG8_STAGE(PG8_SB(1, 1), b3 + hsB, voffB); PG8_STAGE(PG8_SA(1, 0), a3, voffA);
;             PG8_WAIT_V(8); PG8_WAIT_L(0); PG8_BAR; PG8_MMA(1, 0, At, B0); PG8_MMA(1, 1, At, B1); PG8_BAR; PG8_SCHED;
;         }
	s_add_i32 s1, s1, s7
	v_lshl_add_u64 v[190:191], v[190:191], 0, s[18:19]
	s_mov_b32 m0, s1
	ds_read_b128 v[178:181], v153 offset:49152
	ds_read_b128 v[182:185], v153 offset:50176
	ds_read_b128 v[186:189], v153 offset:51200
	ds_read_b128 v[208:211], v153 offset:52224
	global_load_lds_dwordx4 v[190:191], off
	s_add_i32 m0, s1, 0x2000
	s_add_u32 s42, s46, 0x10080
	v_lshl_add_u64 v[190:191], v[228:229], 0, s[18:19]
	s_addc_u32 s43, s47, 0
	s_add_i32 s1, s22, s7
	global_load_lds_dwordx4 v[190:191], off
	v_lshl_add_u64 v[190:191], s[42:43], 0, v[134:135]
	s_mov_b32 m0, s1
	ds_read_b128 v[212:215], v153 offset:53248
	global_load_lds_dwordx4 v[190:191], off
	v_lshl_add_u64 v[190:191], s[42:43], 0, v[130:131]
	s_add_i32 m0, s1, 0x2000
	ds_read_b128 v[216:219], v153 offset:54272
	global_load_lds_dwordx4 v[190:191], off
	v_lshl_add_u64 v[190:191], v[230:231], 0, s[18:19]
	s_mov_b32 m0, s51
	ds_read_b128 v[220:223], v153 offset:55296
	global_load_lds_dwordx4 v[190:191], off
	v_lshl_add_u64 v[190:191], v[232:233], 0, s[18:19]
	s_mov_b32 m0, s52
	ds_read_b128 v[224:227], v153 offset:56320
	global_load_lds_dwordx4 v[190:191], off
	s_waitcnt vmcnt(8)
	s_waitcnt lgkmcnt(0)
	s_barrier
	s_waitcnt lgkmcnt(0)
	v_mfma_f32_16x16x32_bf16 v[122:125], v[142:145], v[178:181], v[122:125]
	v_mfma_f32_16x16x32_bf16 v[114:117], v[154:157], v[178:181], v[114:117]
	v_mfma_f32_16x16x32_bf16 v[90:93], v[142:145], v[186:189], v[90:93]
	v_mfma_f32_16x16x32_bf16 v[82:85], v[154:157], v[186:189], v[82:85]
	v_mfma_f32_16x16x32_bf16 v[58:61], v[142:145], v[212:215], v[58:61]
	v_mfma_f32_16x16x32_bf16 v[50:53], v[154:157], v[212:215], v[50:53]
	v_mfma_f32_16x16x32_bf16 v[26:29], v[142:145], v[220:223], v[26:29]
	v_mfma_f32_16x16x32_bf16 v[18:21], v[154:157], v[220:223], v[18:21]
	v_mfma_f32_16x16x32_bf16 v[122:125], v[146:149], v[182:185], v[122:125]
	v_mfma_f32_16x16x32_bf16 v[114:117], v[158:161], v[182:185], v[114:117]
	v_mfma_f32_16x16x32_bf16 v[90:93], v[146:149], v[208:211], v[90:93]
	v_mfma_f32_16x16x32_bf16 v[82:85], v[158:161], v[208:211], v[82:85]
	v_mfma_f32_16x16x32_bf16 v[58:61], v[146:149], v[216:219], v[58:61]
	v_mfma_f32_16x16x32_bf16 v[50:53], v[158:161], v[216:219], v[50:53]
	v_mfma_f32_16x16x32_bf16 v[26:29], v[146:149], v[224:227], v[26:29]
	v_mfma_f32_16x16x32_bf16 v[18:21], v[158:161], v[224:227], v[18:21]
	v_mfma_f32_16x16x32_bf16 v[106:109], v[162:165], v[178:181], v[106:109]
	v_mfma_f32_16x16x32_bf16 v[98:101], v[170:173], v[178:181], v[98:101]
	v_mfma_f32_16x16x32_bf16 v[74:77], v[162:165], v[186:189], v[74:77]
	v_mfma_f32_16x16x32_bf16 v[66:69], v[170:173], v[186:189], v[66:69]
	v_mfma_f32_16x16x32_bf16 v[42:45], v[162:165], v[212:215], v[42:45]
	v_mfma_f32_16x16x32_bf16 v[34:37], v[170:173], v[212:215], v[34:37]
	v_mfma_f32_16x16x32_bf16 v[10:13], v[162:165], v[220:223], v[10:13]
	v_mfma_f32_16x16x32_bf16 v[2:5], v[170:173], v[220:223], v[2:5]
	v_mfma_f32_16x16x32_bf16 v[106:109], v[166:169], v[182:185], v[106:109]
	v_mfma_f32_16x16x32_bf16 v[98:101], v[174:177], v[182:185], v[98:101]
	v_mfma_f32_16x16x32_bf16 v[74:77], v[166:169], v[208:211], v[74:77]
	v_mfma_f32_16x16x32_bf16 v[66:69], v[174:177], v[208:211], v[66:69]
	v_mfma_f32_16x16x32_bf16 v[42:45], v[166:169], v[216:219], v[42:45]
	v_mfma_f32_16x16x32_bf16 v[34:37], v[174:177], v[216:219], v[34:37]
	v_mfma_f32_16x16x32_bf16 v[10:13], v[166:169], v[224:227], v[10:13]
	v_mfma_f32_16x16x32_bf16 v[2:5], v[174:177], v[224:227], v[2:5]
	s_barrier
	s_cmp_ge_i32 s0, s26
	s_mov_b64 s[42:43], s[44:45]
	s_mov_b32 s46, s0
	s_cbranch_scc0 .LBB0_637
	s_setprio 0

; #define PG8_STAGE(bufoff, gbase, voff) do { _Pragma("unroll") for (int _i = 0; _i < 2; ++_i) \
;         __builtin_amdgcn_global_load_lds((const unsigned*)((const char*)(gbase) + (voff)[_i]), (LAS unsigned*)(lds + (bufoff) + ldsw + _i * 8192), 16, 0, 0); } while (0)
; #define PG8_LDA(dst, b, h) do { _Pragma("unroll") for (int m = 0; m < 4; ++m) _Pragma("unroll") for (int k = 0; k < 2; ++k) dst[m][k] = *(const LAS bf16x8*)(lds + PG8_SA(b, h) + aoff + m * 2048 + k * 1024); } while (0)
; #define PG8_LDB(dst, b, h) do { _Pragma("unroll") for (int n = 0; n < 2; ++n) _Pragma("unroll") for (int k = 0; k < 2; ++k) dst[n][k] = *(const LAS bf16x8*)(lds + PG8_SB(b, h) + boff + n * 2048 + k * 1024); } while (0)
; #define PG8_MMA(ai, bj, At, Bt) do { __builtin_amdgcn_s_setprio(1); _Pragma("unroll") for (int m = 0; m < 4; ++m) _Pragma("unroll") for (int n = 0; n < 2; ++n) _Pragma("unroll") for (int k = 0; k < 2; ++k) \
;         acc[ai][bj][m][n] = __builtin_amdgcn_mfma_f32_16x16x32_bf16(Bt[n][k], At[m][k], acc[ai][bj][m][n], 0, 0, 0); __builtin_amdgcn_s_setprio(0); } while (0)
; #define PG8_WAIT_V(n) asm volatile("s_waitcnt vmcnt(" #n ")" ::: "memory")
; #define PG8_WAIT_L(n) asm volatile("s_waitcnt lgkmcnt(" #n ")" ::: "memory")
; template <class Epi, class Sched>
; __device__ __forceinline__ void gemm_phase(LAS unsigned char* lds, const Gemm g, const Sched& S, const Epi& E) {
;     ...
;             const bool last = (t == nt - 2);
;             const char* a1 = cA + (size_t)(t + 1) * kstep;
;             const char* a2 = last ? nA : cA + (size_t)(t + 2) * kstep; const char* b2 = last ? nB : cB + (size_t)(t + 2) * kstep;
;             const char* a3 = a2 + kstep; const char* b3 = b2 + kstep;
;             if constexpr (Epi::MIDK) { if (t == (nt >> 1)) { int fr_ = fr, fq_ = fq; asm volatile("" : "+v"(fr_), "+v"(fq_)); E.mid(acc, cur, wr, wc, fr_, fq_); } }
;             PG8_LDB(B0, 0, 0); PG8_LDB(B1, 0, 1); PG8_SCHED; PG8_LDA(At, 0, 0); PG8_STAGE(PG8_SA(1, 1), a1 + hsA, voffA);
;             PG8_WAIT_V(8); PG8_WAIT_L(0); PG8_BAR; PG8_MMA(0, 0, At, B0); PG8_MMA(0, 1, At, B1); PG8_BAR; PG8_SCHED;
;             PG8_LDA(At, 0, 1); PG8_STAGE(PG8_SB(0, 0), b2, voffB); PG8_STAGE(PG8_SB(0, 1), b2 + hsB, voffB); PG8_STAGE(PG8_SA(0, 0), a2, voffA);
;             PG8_WAIT_V(8); PG8_WAIT_L(0); PG8_BAR; PG8_MMA(1, 0, At, B0); PG8_MMA(1, 1, At, B1); PG8_BAR; PG8_SCHED;
.Lnp_660:
.LBB0_660:
	s_add_i32 s0, s40, 2
	s_add_u32 s1, s36, 0xfffc0080
	s_addc_u32 s41, s37, -1
	s_add_i32 s74, 0, 0x10000
	s_cmp_eq_u32 s11, s40
	s_cselect_b32 s85, s47, s41
	s_cselect_b32 s84, s49, s1
	s_cselect_b32 s41, s83, s96
	s_cselect_b32 s40, vcc_lo, vcc_hi
	s_add_i32 s1, 0, 0x14000
	v_add_u32_e32 v154, s74, v165
	v_add_u32_e32 v162, s1, v165
	ds_read_b128 v[142:145], v154
	ds_read_b128 v[146:149], v154 offset:1024
	ds_read_b128 v[150:153], v154 offset:2048
	ds_read_b128 v[154:157], v154 offset:3072
	ds_read_b128 v[158:161], v162
	ds_read_b128 v[168:171], v162 offset:1024
	ds_read_b128 v[172:175], v162 offset:2048
	ds_read_b128 v[176:179], v162 offset:3072
	v_lshl_add_u64 v[228:229], s[36:37], 0, v[138:139]
	s_add_i32 m0, s16, 0xc000
	ds_read_b128 v[180:183], v166
	ds_read_b128 v[184:187], v166 offset:1024
	ds_read_b128 v[188:191], v166 offset:2048
	ds_read_b128 v[208:211], v166 offset:3072
	ds_read_b128 v[212:215], v166 offset:4096
	ds_read_b128 v[216:219], v166 offset:5120
	ds_read_b128 v[220:223], v166 offset:6144
	global_load_lds_dwordx4 v[228:229], off
	v_lshl_add_u64 v[228:229], s[36:37], 0, v[140:141]
	s_add_i32 m0, s16, 0xe000
	ds_read_b128 v[224:227], v166 offset:7168
	global_load_lds_dwordx4 v[228:229], off
	s_waitcnt vmcnt(8)
	s_waitcnt lgkmcnt(0)
	s_barrier
	s_waitcnt lgkmcnt(0)
	v_mfma_f32_16x16x32_bf16 v[122:125], v[142:145], v[180:183], v[122:125]
	v_mfma_f32_16x16x32_bf16 v[114:117], v[150:153], v[180:183], v[114:117]
	v_mfma_f32_16x16x32_bf16 v[110:113], v[142:145], v[188:191], v[110:113]
	v_mfma_f32_16x16x32_bf16 v[98:101], v[150:153], v[188:191], v[98:101]
	v_mfma_f32_16x16x32_bf16 v[94:97], v[142:145], v[212:215], v[94:97]
	v_mfma_f32_16x16x32_bf16 v[82:85], v[150:153], v[212:215], v[82:85]
	v_mfma_f32_16x16x32_bf16 v[78:81], v[142:145], v[220:223], v[78:81]
	v_mfma_f32_16x16x32_bf16 v[66:69], v[150:153], v[220:223], v[66:69]
	v_mfma_f32_16x16x32_bf16 v[122:125], v[146:149], v[184:187], v[122:125]
	v_mfma_f32_16x16x32_bf16 v[114:117], v[154:157], v[184:187], v[114:117]
	v_mfma_f32_16x16x32_bf16 v[110:113], v[146:149], v[208:211], v[110:113]
	v_mfma_f32_16x16x32_bf16 v[98:101], v[154:157], v[208:211], v[98:101]
	v_mfma_f32_16x16x32_bf16 v[94:97], v[146:149], v[216:219], v[94:97]
	v_mfma_f32_16x16x32_bf16 v[82:85], v[154:157], v[216:219], v[82:85]
	v_mfma_f32_16x16x32_bf16 v[78:81], v[146:149], v[224:227], v[78:81]
	v_mfma_f32_16x16x32_bf16 v[66:69], v[154:157], v[224:227], v[66:69]
	v_mfma_f32_16x16x32_bf16 v[126:129], v[158:161], v[180:183], v[126:129]
	v_mfma_f32_16x16x32_bf16 v[118:121], v[172:175], v[180:183], v[118:121]
	v_mfma_f32_16x16x32_bf16 v[106:109], v[158:161], v[188:191], v[106:109]
	v_mfma_f32_16x16x32_bf16 v[102:105], v[172:175], v[188:191], v[102:105]
	v_mfma_f32_16x16x32_bf16 v[90:93], v[158:161], v[212:215], v[90:93]
	v_mfma_f32_16x16x32_bf16 v[86:89], v[172:175], v[212:215], v[86:89]
	v_mfma_f32_16x16x32_bf16 v[74:77], v[158:161], v[220:223], v[74:77]
	v_mfma_f32_16x16x32_bf16 v[70:73], v[172:175], v[220:223], v[70:73]
	v_mfma_f32_16x16x32_bf16 v[126:129], v[168:171], v[184:187], v[126:129]
	v_mfma_f32_16x16x32_bf16 v[118:121], v[176:179], v[184:187], v[118:121]
	v_mfma_f32_16x16x32_bf16 v[106:109], v[168:171], v[208:211], v[106:109]
	v_mfma_f32_16x16x32_bf16 v[102:105], v[176:179], v[208:211], v[102:105]
	v_mfma_f32_16x16x32_bf16 v[90:93], v[168:171], v[216:219], v[90:93]
	v_mfma_f32_16x16x32_bf16 v[86:89], v[176:179], v[216:219], v[86:89]
	v_mfma_f32_16x16x32_bf16 v[74:77], v[168:171], v[224:227], v[74:77]
	v_mfma_f32_16x16x32_bf16 v[70:73], v[176:179], v[224:227], v[70:73]
	s_barrier
	s_add_i32 s74, s74, s12
	v_lshl_add_u64 v[228:229], s[40:41], 0, v[0:1]
	s_mov_b32 m0, s74
	ds_read_b128 v[180:183], v166 offset:16384
	ds_read_b128 v[184:187], v166 offset:17408
	ds_read_b128 v[188:191], v166 offset:18432
	ds_read_b128 v[208:211], v166 offset:19456
	ds_read_b128 v[212:215], v166 offset:20480
	global_load_lds_dwordx4 v[228:229], off
	s_add_i32 m0, s74, 0x2000
	s_add_u32 s74, s40, 0x40000
	v_lshl_add_u64 v[230:231], s[40:41], 0, v[130:131]
	s_addc_u32 s75, s41, 0
	s_add_i32 s1, s1, s12
	global_load_lds_dwordx4 v[230:231], off
	v_lshl_add_u64 v[232:233], s[74:75], 0, v[0:1]
	s_mov_b32 m0, s1
	v_lshl_add_u64 v[238:239], s[84:85], 0, v[132:133]
	global_load_lds_dwordx4 v[232:233], off
	v_lshl_add_u64 v[232:233], s[74:75], 0, v[130:131]
	s_add_i32 m0, s1, 0x2000
	ds_read_b128 v[216:219], v166 offset:21504
	global_load_lds_dwordx4 v[232:233], off
	v_lshl_add_u64 v[232:233], s[84:85], 0, v[134:135]
	s_mov_b32 m0, s16
	ds_read_b128 v[220:223], v166 offset:22528
	global_load_lds_dwordx4 v[232:233], off
	s_mov_b32 m0, s52
	ds_read_b128 v[224:227], v166 offset:23552
	global_load_lds_dwordx4 v[238:239], off
	s_waitcnt vmcnt(8)
	s_waitcnt lgkmcnt(0)
	s_barrier
; #define PG8_STAGE(bufoff, gbase, voff) do { _Pragma("unroll") for (int _i = 0; _i < 2; ++_i) \
;         __builtin_amdgcn_global_load_lds((const unsigned*)((const char*)(gbase) + (voff)[_i]), (LAS unsigned*)(lds + (bufoff) + ldsw + _i * 8192), 16, 0, 0); } while (0)
; #define PG8_LDA(dst, b, h) do { _Pragma("unroll") for (int m = 0; m < 4; ++m) _Pragma("unroll") for (int k = 0; k < 2; ++k) dst[m][k] = *(const LAS bf16x8*)(lds + PG8_SA(b, h) + aoff + m * 2048 + k * 1024); } while (0)
; #define PG8_LDB(dst, b, h) do { _Pragma("unroll") for (int n = 0; n < 2; ++n) _Pragma("unroll") for (int k = 0; k < 2; ++k) dst[n][k] = *(const LAS bf16x8*)(lds + PG8_SB(b, h) + boff + n * 2048 + k * 1024); } while (0)
; #define PG8_MMA(ai, bj, At, Bt) do { __builtin_amdgcn_s_setprio(1); _Pragma("unroll") for (int m = 0; m < 4; ++m) _Pragma("unroll") for (int n = 0; n < 2; ++n) _Pragma("unroll") for (int k = 0; k < 2; ++k) \
;         acc[ai][bj][m][n] = __builtin_amdgcn_mfma_f32_16x16x32_bf16(Bt[n][k], At[m][k], acc[ai][bj][m][n], 0, 0, 0); __builtin_amdgcn_s_setprio(0); } while (0)
; #define PG8_WAIT_V(n) asm volatile("s_waitcnt vmcnt(" #n ")" ::: "memory")
; #define PG8_WAIT_L(n) asm volatile("s_waitcnt lgkmcnt(" #n ")" ::: "memory")
; #define PG8_BAR __builtin_amdgcn_s_barrier()
; #define PG8_SCHED __builtin_amdgcn_sched_barrier(0)
; template <class Epi, class Sched>
; __device__ __forceinline__ void gemm_phase(LAS unsigned char* lds, const Gemm g, const Sched& S, const Epi& E) {
;     ...
;             PG8_WAIT_V(8); PG8_WAIT_L(0); PG8_BAR; PG8_MMA(1, 0, At, B0); PG8_MMA(1, 1, At, B1); PG8_BAR; PG8_SCHED;
;             PG8_LDB(B0, 1, 0); PG8_LDB(B1, 1, 1); PG8_SCHED; PG8_LDA(At, 1, 0); PG8_STAGE(PG8_SA(0, 1), a2 + hsA, voffA);
;             PG8_WAIT_V(8); PG8_WAIT_L(0); PG8_BAR; PG8_MMA(0, 0, At, B0); PG8_MMA(0, 1, At, B1); PG8_BAR; PG8_SCHED;
	s_waitcnt lgkmcnt(0)
	v_mfma_f32_16x16x32_bf16 v[62:65], v[142:145], v[180:183], v[62:65]
	v_mfma_f32_16x16x32_bf16 v[50:53], v[150:153], v[180:183], v[50:53]
	v_mfma_f32_16x16x32_bf16 v[46:49], v[142:145], v[188:191], v[46:49]
	v_mfma_f32_16x16x32_bf16 v[34:37], v[150:153], v[188:191], v[34:37]
	v_mfma_f32_16x16x32_bf16 v[30:33], v[142:145], v[212:215], v[30:33]
	v_mfma_f32_16x16x32_bf16 v[18:21], v[150:153], v[212:215], v[18:21]
	v_mfma_f32_16x16x32_bf16 v[10:13], v[142:145], v[220:223], v[10:13]
	v_mfma_f32_16x16x32_bf16 v[2:5], v[150:153], v[220:223], v[2:5]
	v_mfma_f32_16x16x32_bf16 v[62:65], v[146:149], v[184:187], v[62:65]
	v_mfma_f32_16x16x32_bf16 v[50:53], v[154:157], v[184:187], v[50:53]
	v_mfma_f32_16x16x32_bf16 v[46:49], v[146:149], v[208:211], v[46:49]
	v_mfma_f32_16x16x32_bf16 v[34:37], v[154:157], v[208:211], v[34:37]
	v_mfma_f32_16x16x32_bf16 v[30:33], v[146:149], v[216:219], v[30:33]
	v_mfma_f32_16x16x32_bf16 v[18:21], v[154:157], v[216:219], v[18:21]
	v_mfma_f32_16x16x32_bf16 v[10:13], v[146:149], v[224:227], v[10:13]
	v_mfma_f32_16x16x32_bf16 v[2:5], v[154:157], v[224:227], v[2:5]
	v_mfma_f32_16x16x32_bf16 v[58:61], v[158:161], v[180:183], v[58:61]
	v_mfma_f32_16x16x32_bf16 v[54:57], v[172:175], v[180:183], v[54:57]
	v_mfma_f32_16x16x32_bf16 v[42:45], v[158:161], v[188:191], v[42:45]
	v_mfma_f32_16x16x32_bf16 v[38:41], v[172:175], v[188:191], v[38:41]
	v_mfma_f32_16x16x32_bf16 v[26:29], v[158:161], v[212:215], v[26:29]
	v_mfma_f32_16x16x32_bf16 v[22:25], v[172:175], v[212:215], v[22:25]
	v_mfma_f32_16x16x32_bf16 v[14:17], v[158:161], v[220:223], v[14:17]
	v_mfma_f32_16x16x32_bf16 v[6:9], v[172:175], v[220:223], v[6:9]
	v_mfma_f32_16x16x32_bf16 v[58:61], v[168:171], v[184:187], v[58:61]
	v_mfma_f32_16x16x32_bf16 v[54:57], v[176:179], v[184:187], v[54:57]
	v_mfma_f32_16x16x32_bf16 v[42:45], v[168:171], v[208:211], v[42:45]
	v_mfma_f32_16x16x32_bf16 v[38:41], v[176:179], v[208:211], v[38:41]
	v_mfma_f32_16x16x32_bf16 v[26:29], v[168:171], v[216:219], v[26:29]
	v_mfma_f32_16x16x32_bf16 v[22:25], v[176:179], v[216:219], v[22:25]
	v_mfma_f32_16x16x32_bf16 v[14:17], v[168:171], v[224:227], v[14:17]
	v_mfma_f32_16x16x32_bf16 v[6:9], v[176:179], v[224:227], v[6:9]
	s_barrier
	s_add_i32 s1, 0, 0x18000
	s_add_i32 s22, 0, 0x1c000
	v_add_u32_e32 v154, s1, v165
	v_add_u32_e32 v162, s22, v165
	ds_read_b128 v[142:145], v154
	ds_read_b128 v[146:149], v154 offset:1024
	ds_read_b128 v[150:153], v154 offset:2048
	ds_read_b128 v[154:157], v154 offset:3072
	ds_read_b128 v[158:161], v162
	ds_read_b128 v[168:171], v162 offset:1024
	ds_read_b128 v[172:175], v162 offset:2048
	ds_read_b128 v[176:179], v162 offset:3072
	s_add_u32 s74, s84, 0x40000
	s_addc_u32 s75, s85, 0
	s_mov_b32 m0, s64
	v_lshl_add_u64 v[240:241], s[74:75], 0, v[134:135]
	ds_read_b128 v[180:183], v166 offset:32768
	ds_read_b128 v[184:187], v166 offset:33792
	ds_read_b128 v[188:191], v166 offset:34816
	ds_read_b128 v[208:211], v166 offset:35840
	ds_read_b128 v[212:215], v166 offset:36864
	ds_read_b128 v[216:219], v166 offset:37888
	ds_read_b128 v[220:223], v166 offset:38912
	global_load_lds_dwordx4 v[240:241], off
	v_lshl_add_u64 v[240:241], s[74:75], 0, v[132:133]
	s_mov_b32 m0, s78
	ds_read_b128 v[224:227], v166 offset:39936
	global_load_lds_dwordx4 v[240:241], off
	s_waitcnt vmcnt(8)
	s_waitcnt lgkmcnt(0)
	s_barrier
	s_waitcnt lgkmcnt(0)
	v_mfma_f32_16x16x32_bf16 v[122:125], v[142:145], v[180:183], v[122:125]
	v_mfma_f32_16x16x32_bf16 v[114:117], v[150:153], v[180:183], v[114:117]
	v_mfma_f32_16x16x32_bf16 v[110:113], v[142:145], v[188:191], v[110:113]
	v_mfma_f32_16x16x32_bf16 v[98:101], v[150:153], v[188:191], v[98:101]
	v_mfma_f32_16x16x32_bf16 v[94:97], v[142:145], v[212:215], v[94:97]
	v_mfma_f32_16x16x32_bf16 v[82:85], v[150:153], v[212:215], v[82:85]
	v_mfma_f32_16x16x32_bf16 v[78:81], v[142:145], v[220:223], v[78:81]
	v_mfma_f32_16x16x32_bf16 v[66:69], v[150:153], v[220:223], v[66:69]
	v_mfma_f32_16x16x32_bf16 v[122:125], v[146:149], v[184:187], v[122:125]
	v_mfma_f32_16x16x32_bf16 v[114:117], v[154:157], v[184:187], v[114:117]
	v_mfma_f32_16x16x32_bf16 v[110:113], v[146:149], v[208:211], v[110:113]
	v_mfma_f32_16x16x32_bf16 v[98:101], v[154:157], v[208:211], v[98:101]
	v_mfma_f32_16x16x32_bf16 v[94:97], v[146:149], v[216:219], v[94:97]
	v_mfma_f32_16x16x32_bf16 v[82:85], v[154:157], v[216:219], v[82:85]
	v_mfma_f32_16x16x32_bf16 v[78:81], v[146:149], v[224:227], v[78:81]
	v_mfma_f32_16x16x32_bf16 v[66:69], v[154:157], v[224:227], v[66:69]
	v_mfma_f32_16x16x32_bf16 v[126:129], v[158:161], v[180:183], v[126:129]
	v_mfma_f32_16x16x32_bf16 v[118:121], v[172:175], v[180:183], v[118:121]
	v_mfma_f32_16x16x32_bf16 v[106:109], v[158:161], v[188:191], v[106:109]
	v_mfma_f32_16x16x32_bf16 v[102:105], v[172:175], v[188:191], v[102:105]
	v_mfma_f32_16x16x32_bf16 v[90:93], v[158:161], v[212:215], v[90:93]
	v_mfma_f32_16x16x32_bf16 v[86:89], v[172:175], v[212:215], v[86:89]
	v_mfma_f32_16x16x32_bf16 v[74:77], v[158:161], v[220:223], v[74:77]
	v_mfma_f32_16x16x32_bf16 v[70:73], v[172:175], v[220:223], v[70:73]
	v_mfma_f32_16x16x32_bf16 v[126:129], v[168:171], v[184:187], v[126:129]
	v_mfma_f32_16x16x32_bf16 v[118:121], v[176:179], v[184:187], v[118:121]
	v_mfma_f32_16x16x32_bf16 v[106:109], v[168:171], v[208:211], v[106:109]
	v_mfma_f32_16x16x32_bf16 v[102:105], v[176:179], v[208:211], v[102:105]
	v_mfma_f32_16x16x32_bf16 v[90:93], v[168:171], v[216:219], v[90:93]
	v_mfma_f32_16x16x32_bf16 v[86:89], v[176:179], v[216:219], v[86:89]
	v_mfma_f32_16x16x32_bf16 v[74:77], v[168:171], v[224:227], v[74:77]
	v_mfma_f32_16x16x32_bf16 v[70:73], v[176:179], v[224:227], v[70:73]
	s_barrier
; #define PG8_STAGE(bufoff, gbase, voff) do { _Pragma("unroll") for (int _i = 0; _i < 2; ++_i) \
;         __builtin_amdgcn_global_load_lds((const unsigned*)((const char*)(gbase) + (voff)[_i]), (LAS unsigned*)(lds + (bufoff) + ldsw + _i * 8192), 16, 0, 0); } while (0)
; #define PG8_LDA(dst, b, h) do { _Pragma("unroll") for (int m = 0; m < 4; ++m) _Pragma("unroll") for (int k = 0; k < 2; ++k) dst[m][k] = *(const LAS bf16x8*)(lds + PG8_SA(b, h) + aoff + m * 2048 + k * 1024); } while (0)
; #define PG8_MMA(ai, bj, At, Bt) do { __builtin_amdgcn_s_setprio(1); _Pragma("unroll") for (int m = 0; m < 4; ++m) _Pragma("unroll") for (int n = 0; n < 2; ++n) _Pragma("unroll") for (int k = 0; k < 2; ++k) \
;         acc[ai][bj][m][n] = __builtin_amdgcn_mfma_f32_16x16x32_bf16(Bt[n][k], At[m][k], acc[ai][bj][m][n], 0, 0, 0); __builtin_amdgcn_s_setprio(0); } while (0)
; #define PG8_WAIT_V(n) asm volatile("s_waitcnt vmcnt(" #n ")" ::: "memory")
; #define PG8_WAIT_L(n) asm volatile("s_waitcnt lgkmcnt(" #n ")" ::: "memory")
; #define PG8_BAR __builtin_amdgcn_s_barrier()
; #define PG8_SCHED __builtin_amdgcn_sched_barrier(0)
; template <class Epi, class Sched>
; __device__ __forceinline__ void gemm_phase(LAS unsigned char* lds, const Gemm g, const Sched& S, const Epi& E) {
;     ...
;             PG8_LDA(At, 1, 1); PG8_STAGE(PG8_SB(1, 0), b3, voffB); PG8_STAGE(PG8_SB(1, 1), b3 + hsB, voffB); PG8_STAGE(PG8_SA(1, 0), a3, voffA);
;             PG8_WAIT_V(8); PG8_WAIT_L(0); PG8_BAR; PG8_MMA(1, 0, At, B0); PG8_MMA(1, 1, At, B1); PG8_BAR; PG8_SCHED;
;         }
	s_add_i32 s1, s1, s12
	v_lshl_add_u64 v[228:229], v[228:229], 0, s[18:19]
	s_mov_b32 m0, s1
	ds_read_b128 v[180:183], v166 offset:49152
	ds_read_b128 v[184:187], v166 offset:50176
	ds_read_b128 v[188:191], v166 offset:51200
	ds_read_b128 v[208:211], v166 offset:52224
	global_load_lds_dwordx4 v[228:229], off
	s_add_i32 m0, s1, 0x2000
	s_add_u32 s40, s40, 0x40080
	v_lshl_add_u64 v[228:229], v[230:231], 0, s[18:19]
	s_addc_u32 s41, s41, 0
	s_add_i32 s1, s22, s12
	global_load_lds_dwordx4 v[228:229], off
	v_lshl_add_u64 v[228:229], s[40:41], 0, v[0:1]
	s_mov_b32 m0, s1
	ds_read_b128 v[212:215], v166 offset:53248
	global_load_lds_dwordx4 v[228:229], off
	v_lshl_add_u64 v[228:229], s[40:41], 0, v[130:131]
	s_add_i32 m0, s1, 0x2000
	ds_read_b128 v[216:219], v166 offset:54272
	global_load_lds_dwordx4 v[228:229], off
	v_lshl_add_u64 v[228:229], v[232:233], 0, s[18:19]
	s_mov_b32 m0, s26
	ds_read_b128 v[220:223], v166 offset:55296
	global_load_lds_dwordx4 v[228:229], off
	v_lshl_add_u64 v[228:229], v[238:239], 0, s[18:19]
	s_mov_b32 m0, s57
	ds_read_b128 v[224:227], v166 offset:56320
	global_load_lds_dwordx4 v[228:229], off
	s_waitcnt vmcnt(8)
	s_waitcnt lgkmcnt(0)
	s_barrier
	s_waitcnt lgkmcnt(0)
	v_mfma_f32_16x16x32_bf16 v[62:65], v[142:145], v[180:183], v[62:65]
	v_mfma_f32_16x16x32_bf16 v[50:53], v[150:153], v[180:183], v[50:53]
	v_mfma_f32_16x16x32_bf16 v[46:49], v[142:145], v[188:191], v[46:49]
	v_mfma_f32_16x16x32_bf16 v[34:37], v[150:153], v[188:191], v[34:37]
	v_mfma_f32_16x16x32_bf16 v[30:33], v[142:145], v[212:215], v[30:33]
	v_mfma_f32_16x16x32_bf16 v[18:21], v[150:153], v[212:215], v[18:21]
	v_mfma_f32_16x16x32_bf16 v[10:13], v[142:145], v[220:223], v[10:13]
	v_mfma_f32_16x16x32_bf16 v[2:5], v[150:153], v[220:223], v[2:5]
	v_mfma_f32_16x16x32_bf16 v[62:65], v[146:149], v[184:187], v[62:65]
	v_mfma_f32_16x16x32_bf16 v[50:53], v[154:157], v[184:187], v[50:53]
	v_mfma_f32_16x16x32_bf16 v[46:49], v[146:149], v[208:211], v[46:49]
	v_mfma_f32_16x16x32_bf16 v[34:37], v[154:157], v[208:211], v[34:37]
	v_mfma_f32_16x16x32_bf16 v[30:33], v[146:149], v[216:219], v[30:33]
	v_mfma_f32_16x16x32_bf16 v[18:21], v[154:157], v[216:219], v[18:21]
	v_mfma_f32_16x16x32_bf16 v[10:13], v[146:149], v[224:227], v[10:13]
	v_mfma_f32_16x16x32_bf16 v[2:5], v[154:157], v[224:227], v[2:5]
	v_mfma_f32_16x16x32_bf16 v[58:61], v[158:161], v[180:183], v[58:61]
	v_mfma_f32_16x16x32_bf16 v[54:57], v[172:175], v[180:183], v[54:57]
	v_mfma_f32_16x16x32_bf16 v[42:45], v[158:161], v[188:191], v[42:45]
	v_mfma_f32_16x16x32_bf16 v[38:41], v[172:175], v[188:191], v[38:41]
	v_mfma_f32_16x16x32_bf16 v[26:29], v[158:161], v[212:215], v[26:29]
	v_mfma_f32_16x16x32_bf16 v[22:25], v[172:175], v[212:215], v[22:25]
	v_mfma_f32_16x16x32_bf16 v[14:17], v[158:161], v[220:223], v[14:17]
	v_mfma_f32_16x16x32_bf16 v[6:9], v[172:175], v[220:223], v[6:9]
	v_mfma_f32_16x16x32_bf16 v[58:61], v[168:171], v[184:187], v[58:61]
	v_mfma_f32_16x16x32_bf16 v[54:57], v[176:179], v[184:187], v[54:57]
	v_mfma_f32_16x16x32_bf16 v[42:45], v[168:171], v[208:211], v[42:45]
	v_mfma_f32_16x16x32_bf16 v[38:41], v[176:179], v[208:211], v[38:41]
	v_mfma_f32_16x16x32_bf16 v[26:29], v[168:171], v[216:219], v[26:29]
	v_mfma_f32_16x16x32_bf16 v[22:25], v[176:179], v[216:219], v[22:25]
	v_mfma_f32_16x16x32_bf16 v[14:17], v[168:171], v[224:227], v[14:17]
	v_mfma_f32_16x16x32_bf16 v[6:9], v[176:179], v[224:227], v[6:9]
	s_barrier
	s_add_u32 s36, s36, 0x100
	s_addc_u32 s37, s37, 0
	s_add_u32 vcc_hi, vcc_hi, 0x100
	s_addc_u32 s96, s96, 0
	s_cmp_ge_i32 s0, s56
	s_mov_b32 s40, s0
	s_cbranch_scc0 .LBB0_660
	s_setprio 0
	v_readlane_b32 s96, v250, 43

; #define PG8_STAGE(bufoff, gbase, voff) do { _Pragma("unroll") for (int _i = 0; _i < 2; ++_i) \
;         __builtin_amdgcn_global_load_lds((const unsigned*)((const char*)(gbase) + (voff)[_i]), (LAS unsigned*)(lds + (bufoff) + ldsw + _i * 8192), 16, 0, 0); } while (0)
; #define PG8_LDA(dst, b, h) do { _Pragma("unroll") for (int m = 0; m < 4; ++m) _Pragma("unroll") for (int k = 0; k < 2; ++k) dst[m][k] = *(const LAS bf16x8*)(lds + PG8_SA(b, h) + aoff + m * 2048 + k * 1024); } while (0)
; #define PG8_LDB(dst, b, h) do { _Pragma("unroll") for (int n = 0; n < 2; ++n) _Pragma("unroll") for (int k = 0; k < 2; ++k) dst[n][k] = *(const LAS bf16x8*)(lds + PG8_SB(b, h) + boff + n * 2048 + k * 1024); } while (0)
; #define PG8_MMA(ai, bj, At, Bt) do { __builtin_amdgcn_s_setprio(1); _Pragma("unroll") for (int m = 0; m < 4; ++m) _Pragma("unroll") for (int n = 0; n < 2; ++n) _Pragma("unroll") for (int k = 0; k < 2; ++k) \
;         acc[ai][bj][m][n] = __builtin_amdgcn_mfma_f32_16x16x32_bf16(Bt[n][k], At[m][k], acc[ai][bj][m][n], 0, 0, 0); __builtin_amdgcn_s_setprio(0); } while (0)
; #define PG8_WAIT_V(n) asm volatile("s_waitcnt vmcnt(" #n ")" ::: "memory")
; #define PG8_WAIT_L(n) asm volatile("s_waitcnt lgkmcnt(" #n ")" ::: "memory")
; template <class Epi, class Sched>
; __device__ __forceinline__ void gemm_phase(LAS unsigned char* lds, const Gemm g, const Sched& S, const Epi& E) {
;     ...
;             const bool last = (t == nt - 2);
;             const char* a1 = cA + (size_t)(t + 1) * kstep;
;             const char* a2 = last ? nA : cA + (size_t)(t + 2) * kstep; const char* b2 = last ? nB : cB + (size_t)(t + 2) * kstep;
;             const char* a3 = a2 + kstep; const char* b3 = b2 + kstep;
;             if constexpr (Epi::MIDK) { if (t == (nt >> 1)) { int fr_ = fr, fq_ = fq; asm volatile("" : "+v"(fr_), "+v"(fq_)); E.mid(acc, cur, wr, wc, fr_, fq_); } }
;             PG8_LDB(B0, 0, 0); PG8_LDB(B1, 0, 1); PG8_SCHED; PG8_LDA(At, 0, 0); PG8_STAGE(PG8_SA(1, 1), a1 + hsA, voffA);
;             PG8_WAIT_V(8); PG8_WAIT_L(0); PG8_BAR; PG8_MMA(0, 0, At, B0); PG8_MMA(0, 1, At, B1); PG8_BAR; PG8_SCHED;
;             PG8_LDA(At, 0, 1); PG8_STAGE(PG8_SB(0, 0), b2, voffB); PG8_STAGE(PG8_SB(0, 1), b2 + hsB, voffB); PG8_STAGE(PG8_SA(0, 0), a2, voffA);
;             PG8_WAIT_V(8); PG8_WAIT_L(0); PG8_BAR; PG8_MMA(1, 0, At, B0); PG8_MMA(1, 1, At, B1); PG8_BAR; PG8_SCHED;
.Lnp_763:
.LBB0_763:
	s_add_i32 s73, s46, 2
	s_add_u32 s44, s42, 0x100
	s_addc_u32 s45, s43, 0
	s_add_u32 s47, s57, s42
	s_addc_u32 s74, s64, s43
	s_cmp_eq_u32 s49, s46
	s_cselect_b32 s46, 0, s44
	s_cselect_b32 s75, 0, s45
	s_cselect_b32 s76, s56, s47
	s_cselect_b32 s77, s52, s74
	s_add_u32 s46, s22, s46
	s_addc_u32 s47, s23, s75
	s_add_i32 s74, 0, 0x10000
	v_add_u32_e32 v0, s74, v144
	s_add_i32 s75, 0, 0x14000
	ds_read_b128 v[146:149], v0
	ds_read_b128 v[150:153], v0 offset:1024
	ds_read_b128 v[154:157], v0 offset:2048
	ds_read_b128 v[158:161], v0 offset:3072
	v_add_u32_e32 v0, s75, v144
	ds_read_b128 v[162:165], v0
	ds_read_b128 v[166:169], v0 offset:1024
	ds_read_b128 v[170:173], v0 offset:2048
	ds_read_b128 v[174:177], v0 offset:3072
	v_lshl_add_u64 v[190:191], v[138:139], 0, s[42:43]
	s_add_i32 m0, s11, 0xc000
	ds_read_b128 v[178:181], v145
	ds_read_b128 v[182:185], v145 offset:1024
	ds_read_b128 v[186:189], v145 offset:2048
	ds_read_b128 v[208:211], v145 offset:3072
	ds_read_b128 v[212:215], v145 offset:4096
	ds_read_b128 v[216:219], v145 offset:5120
	ds_read_b128 v[220:223], v145 offset:6144
	global_load_lds_dwordx4 v[190:191], off
	v_lshl_add_u64 v[190:191], v[140:141], 0, s[42:43]
	s_add_i32 m0, s11, 0xe000
	ds_read_b128 v[224:227], v145 offset:7168
	global_load_lds_dwordx4 v[190:191], off
	s_waitcnt vmcnt(8)
	s_waitcnt lgkmcnt(0)
	s_barrier
	s_waitcnt lgkmcnt(0)
	v_mfma_f32_16x16x32_bf16 v[122:125], v[146:149], v[178:181], v[122:125]
	v_mfma_f32_16x16x32_bf16 v[126:129], v[154:157], v[178:181], v[126:129]
	v_mfma_f32_16x16x32_bf16 v[110:113], v[146:149], v[186:189], v[110:113]
	v_mfma_f32_16x16x32_bf16 v[106:109], v[154:157], v[186:189], v[106:109]
	v_mfma_f32_16x16x32_bf16 v[94:97], v[146:149], v[212:215], v[94:97]
	v_mfma_f32_16x16x32_bf16 v[90:93], v[154:157], v[212:215], v[90:93]
	v_mfma_f32_16x16x32_bf16 v[78:81], v[146:149], v[220:223], v[78:81]
	v_mfma_f32_16x16x32_bf16 v[74:77], v[154:157], v[220:223], v[74:77]
	v_mfma_f32_16x16x32_bf16 v[122:125], v[150:153], v[182:185], v[122:125]
	v_mfma_f32_16x16x32_bf16 v[126:129], v[158:161], v[182:185], v[126:129]
	v_mfma_f32_16x16x32_bf16 v[110:113], v[150:153], v[208:211], v[110:113]
	v_mfma_f32_16x16x32_bf16 v[106:109], v[158:161], v[208:211], v[106:109]
	v_mfma_f32_16x16x32_bf16 v[94:97], v[150:153], v[216:219], v[94:97]
	v_mfma_f32_16x16x32_bf16 v[90:93], v[158:161], v[216:219], v[90:93]
	v_mfma_f32_16x16x32_bf16 v[78:81], v[150:153], v[224:227], v[78:81]
	v_mfma_f32_16x16x32_bf16 v[74:77], v[158:161], v[224:227], v[74:77]
	v_mfma_f32_16x16x32_bf16 v[118:121], v[162:165], v[178:181], v[118:121]
	v_mfma_f32_16x16x32_bf16 v[114:117], v[170:173], v[178:181], v[114:117]
	v_mfma_f32_16x16x32_bf16 v[102:105], v[162:165], v[186:189], v[102:105]
	v_mfma_f32_16x16x32_bf16 v[98:101], v[170:173], v[186:189], v[98:101]
	v_mfma_f32_16x16x32_bf16 v[86:89], v[162:165], v[212:215], v[86:89]
	v_mfma_f32_16x16x32_bf16 v[82:85], v[170:173], v[212:215], v[82:85]
	v_mfma_f32_16x16x32_bf16 v[70:73], v[162:165], v[220:223], v[70:73]
	v_mfma_f32_16x16x32_bf16 v[66:69], v[170:173], v[220:223], v[66:69]
	v_mfma_f32_16x16x32_bf16 v[118:121], v[166:169], v[182:185], v[118:121]
	v_mfma_f32_16x16x32_bf16 v[114:117], v[174:177], v[182:185], v[114:117]
	v_mfma_f32_16x16x32_bf16 v[102:105], v[166:169], v[208:211], v[102:105]
	v_mfma_f32_16x16x32_bf16 v[98:101], v[174:177], v[208:211], v[98:101]
	v_mfma_f32_16x16x32_bf16 v[86:89], v[166:169], v[216:219], v[86:89]
	v_mfma_f32_16x16x32_bf16 v[82:85], v[174:177], v[216:219], v[82:85]
	v_mfma_f32_16x16x32_bf16 v[70:73], v[166:169], v[224:227], v[70:73]
	v_mfma_f32_16x16x32_bf16 v[66:69], v[174:177], v[224:227], v[66:69]
	s_barrier
	s_add_i32 s42, s74, s7
	v_lshl_add_u64 v[190:191], s[76:77], 0, v[134:135]
	s_mov_b32 m0, s42
	ds_read_b128 v[178:181], v145 offset:16384
	ds_read_b128 v[182:185], v145 offset:17408
	ds_read_b128 v[186:189], v145 offset:18432
	ds_read_b128 v[208:211], v145 offset:19456
	ds_read_b128 v[212:215], v145 offset:20480
	ds_read_b128 v[216:219], v145 offset:21504
	ds_read_b128 v[220:223], v145 offset:22528
	global_load_lds_dwordx4 v[190:191], off
	s_add_i32 m0, s42, 0x2000
	s_add_u32 s42, s76, s78
	v_lshl_add_u64 v[228:229], s[76:77], 0, v[130:131]
	s_addc_u32 s43, s77, 0
	s_add_i32 s74, s75, s7
	global_load_lds_dwordx4 v[228:229], off
	v_lshl_add_u64 v[230:231], s[42:43], 0, v[134:135]
	s_mov_b32 m0, s74
	v_lshl_add_u64 v[232:233], s[42:43], 0, v[130:131]
	global_load_lds_dwordx4 v[230:231], off
	s_add_i32 m0, s74, 0x2000
	v_lshl_add_u64 v[238:239], s[46:47], 0, v[136:137]
	global_load_lds_dwordx4 v[232:233], off
	s_mov_b32 m0, s11
	v_lshl_add_u64 v[240:241], s[46:47], 0, v[132:133]
	global_load_lds_dwordx4 v[238:239], off
	s_mov_b32 m0, s10
	ds_read_b128 v[224:227], v145 offset:23552
	global_load_lds_dwordx4 v[240:241], off
	s_waitcnt vmcnt(8)
	s_waitcnt lgkmcnt(0)
	s_barrier
; #define PG8_STAGE(bufoff, gbase, voff) do { _Pragma("unroll") for (int _i = 0; _i < 2; ++_i) \
;         __builtin_amdgcn_global_load_lds((const unsigned*)((const char*)(gbase) + (voff)[_i]), (LAS unsigned*)(lds + (bufoff) + ldsw + _i * 8192), 16, 0, 0); } while (0)
; #define PG8_LDA(dst, b, h) do { _Pragma("unroll") for (int m = 0; m < 4; ++m) _Pragma("unroll") for (int k = 0; k < 2; ++k) dst[m][k] = *(const LAS bf16x8*)(lds + PG8_SA(b, h) + aoff + m * 2048 + k * 1024); } while (0)
; #define PG8_LDB(dst, b, h) do { _Pragma("unroll") for (int n = 0; n < 2; ++n) _Pragma("unroll") for (int k = 0; k < 2; ++k) dst[n][k] = *(const LAS bf16x8*)(lds + PG8_SB(b, h) + boff + n * 2048 + k * 1024); } while (0)
; #define PG8_MMA(ai, bj, At, Bt) do { __builtin_amdgcn_s_setprio(1); _Pragma("unroll") for (int m = 0; m < 4; ++m) _Pragma("unroll") for (int n = 0; n < 2; ++n) _Pragma("unroll") for (int k = 0; k < 2; ++k) \
;         acc[ai][bj][m][n] = __builtin_amdgcn_mfma_f32_16x16x32_bf16(Bt[n][k], At[m][k], acc[ai][bj][m][n], 0, 0, 0); __builtin_amdgcn_s_setprio(0); } while (0)
; #define PG8_WAIT_V(n) asm volatile("s_waitcnt vmcnt(" #n ")" ::: "memory")
; #define PG8_WAIT_L(n) asm volatile("s_waitcnt lgkmcnt(" #n ")" ::: "memory")
; #define PG8_BAR __builtin_amdgcn_s_barrier()
; #define PG8_SCHED __builtin_amdgcn_sched_barrier(0)
; template <class Epi, class Sched>
; __device__ __forceinline__ void gemm_phase(LAS unsigned char* lds, const Gemm g, const Sched& S, const Epi& E) {
;     ...
;             PG8_WAIT_V(8); PG8_WAIT_L(0); PG8_BAR; PG8_MMA(1, 0, At, B0); PG8_MMA(1, 1, At, B1); PG8_BAR; PG8_SCHED;
;             PG8_LDB(B0, 1, 0); PG8_LDB(B1, 1, 1); PG8_SCHED; PG8_LDA(At, 1, 0); PG8_STAGE(PG8_SA(0, 1), a2 + hsA, voffA);
;             PG8_WAIT_V(8); PG8_WAIT_L(0); PG8_BAR; PG8_MMA(0, 0, At, B0); PG8_MMA(0, 1, At, B1); PG8_BAR; PG8_SCHED;
	s_waitcnt lgkmcnt(0)
	v_mfma_f32_16x16x32_bf16 v[62:65], v[146:149], v[178:181], v[62:65]
	v_mfma_f32_16x16x32_bf16 v[58:61], v[154:157], v[178:181], v[58:61]
	v_mfma_f32_16x16x32_bf16 v[46:49], v[146:149], v[186:189], v[46:49]
	v_mfma_f32_16x16x32_bf16 v[42:45], v[154:157], v[186:189], v[42:45]
	v_mfma_f32_16x16x32_bf16 v[30:33], v[146:149], v[212:215], v[30:33]
	v_mfma_f32_16x16x32_bf16 v[26:29], v[154:157], v[212:215], v[26:29]
	v_mfma_f32_16x16x32_bf16 v[14:17], v[146:149], v[220:223], v[14:17]
	v_mfma_f32_16x16x32_bf16 v[10:13], v[154:157], v[220:223], v[10:13]
	v_mfma_f32_16x16x32_bf16 v[62:65], v[150:153], v[182:185], v[62:65]
	v_mfma_f32_16x16x32_bf16 v[58:61], v[158:161], v[182:185], v[58:61]
	v_mfma_f32_16x16x32_bf16 v[46:49], v[150:153], v[208:211], v[46:49]
	v_mfma_f32_16x16x32_bf16 v[42:45], v[158:161], v[208:211], v[42:45]
	v_mfma_f32_16x16x32_bf16 v[30:33], v[150:153], v[216:219], v[30:33]
	v_mfma_f32_16x16x32_bf16 v[26:29], v[158:161], v[216:219], v[26:29]
	v_mfma_f32_16x16x32_bf16 v[14:17], v[150:153], v[224:227], v[14:17]
	v_mfma_f32_16x16x32_bf16 v[10:13], v[158:161], v[224:227], v[10:13]
	v_mfma_f32_16x16x32_bf16 v[54:57], v[162:165], v[178:181], v[54:57]
	v_mfma_f32_16x16x32_bf16 v[50:53], v[170:173], v[178:181], v[50:53]
	v_mfma_f32_16x16x32_bf16 v[38:41], v[162:165], v[186:189], v[38:41]
	v_mfma_f32_16x16x32_bf16 v[34:37], v[170:173], v[186:189], v[34:37]
	v_mfma_f32_16x16x32_bf16 v[22:25], v[162:165], v[212:215], v[22:25]
	v_mfma_f32_16x16x32_bf16 v[18:21], v[170:173], v[212:215], v[18:21]
	v_mfma_f32_16x16x32_bf16 v[6:9], v[162:165], v[220:223], v[6:9]
	v_mfma_f32_16x16x32_bf16 v[2:5], v[170:173], v[220:223], v[2:5]
	v_mfma_f32_16x16x32_bf16 v[54:57], v[166:169], v[182:185], v[54:57]
	v_mfma_f32_16x16x32_bf16 v[50:53], v[174:177], v[182:185], v[50:53]
	v_mfma_f32_16x16x32_bf16 v[38:41], v[166:169], v[208:211], v[38:41]
	v_mfma_f32_16x16x32_bf16 v[34:37], v[174:177], v[208:211], v[34:37]
	v_mfma_f32_16x16x32_bf16 v[22:25], v[166:169], v[216:219], v[22:25]
	v_mfma_f32_16x16x32_bf16 v[18:21], v[174:177], v[216:219], v[18:21]
	v_mfma_f32_16x16x32_bf16 v[6:9], v[166:169], v[224:227], v[6:9]
	v_mfma_f32_16x16x32_bf16 v[2:5], v[174:177], v[224:227], v[2:5]
	s_barrier
	s_add_i32 s74, 0, 0x18000
	v_add_u32_e32 v0, s74, v144
	s_add_i32 s75, 0, 0x1c000
	ds_read_b128 v[146:149], v0
	ds_read_b128 v[150:153], v0 offset:1024
	ds_read_b128 v[154:157], v0 offset:2048
	ds_read_b128 v[158:161], v0 offset:3072
	v_add_u32_e32 v0, s75, v144
	ds_read_b128 v[162:165], v0
	ds_read_b128 v[166:169], v0 offset:1024
	ds_read_b128 v[170:173], v0 offset:2048
	ds_read_b128 v[174:177], v0 offset:3072
	s_add_u32 s42, s46, 0x20000
	s_addc_u32 s43, s47, 0
	s_mov_b32 m0, s12
	v_lshl_add_u64 v[242:243], s[42:43], 0, v[136:137]
	ds_read_b128 v[178:181], v145 offset:32768
	ds_read_b128 v[182:185], v145 offset:33792
	ds_read_b128 v[186:189], v145 offset:34816
	ds_read_b128 v[208:211], v145 offset:35840
	ds_read_b128 v[212:215], v145 offset:36864
	ds_read_b128 v[216:219], v145 offset:37888
	ds_read_b128 v[220:223], v145 offset:38912
	global_load_lds_dwordx4 v[242:243], off
	v_lshl_add_u64 v[242:243], s[42:43], 0, v[132:133]
	s_mov_b32 m0, s16
	ds_read_b128 v[224:227], v145 offset:39936
	global_load_lds_dwordx4 v[242:243], off
	s_waitcnt vmcnt(8)
	s_waitcnt lgkmcnt(0)
	s_barrier
	s_waitcnt lgkmcnt(0)
	v_mfma_f32_16x16x32_bf16 v[122:125], v[146:149], v[178:181], v[122:125]
	v_mfma_f32_16x16x32_bf16 v[126:129], v[154:157], v[178:181], v[126:129]
	v_mfma_f32_16x16x32_bf16 v[110:113], v[146:149], v[186:189], v[110:113]
	v_mfma_f32_16x16x32_bf16 v[106:109], v[154:157], v[186:189], v[106:109]
	v_mfma_f32_16x16x32_bf16 v[94:97], v[146:149], v[212:215], v[94:97]
	v_mfma_f32_16x16x32_bf16 v[90:93], v[154:157], v[212:215], v[90:93]
	v_mfma_f32_16x16x32_bf16 v[78:81], v[146:149], v[220:223], v[78:81]
	v_mfma_f32_16x16x32_bf16 v[74:77], v[154:157], v[220:223], v[74:77]
	v_mfma_f32_16x16x32_bf16 v[122:125], v[150:153], v[182:185], v[122:125]
	v_mfma_f32_16x16x32_bf16 v[126:129], v[158:161], v[182:185], v[126:129]
	v_mfma_f32_16x16x32_bf16 v[110:113], v[150:153], v[208:211], v[110:113]
	v_mfma_f32_16x16x32_bf16 v[106:109], v[158:161], v[208:211], v[106:109]
	v_mfma_f32_16x16x32_bf16 v[94:97], v[150:153], v[216:219], v[94:97]
	v_mfma_f32_16x16x32_bf16 v[90:93], v[158:161], v[216:219], v[90:93]
	v_mfma_f32_16x16x32_bf16 v[78:81], v[150:153], v[224:227], v[78:81]
	v_mfma_f32_16x16x32_bf16 v[74:77], v[158:161], v[224:227], v[74:77]
	v_mfma_f32_16x16x32_bf16 v[118:121], v[162:165], v[178:181], v[118:121]
	v_mfma_f32_16x16x32_bf16 v[114:117], v[170:173], v[178:181], v[114:117]
	v_mfma_f32_16x16x32_bf16 v[102:105], v[162:165], v[186:189], v[102:105]
	v_mfma_f32_16x16x32_bf16 v[98:101], v[170:173], v[186:189], v[98:101]
	v_mfma_f32_16x16x32_bf16 v[86:89], v[162:165], v[212:215], v[86:89]
	v_mfma_f32_16x16x32_bf16 v[82:85], v[170:173], v[212:215], v[82:85]
	v_mfma_f32_16x16x32_bf16 v[70:73], v[162:165], v[220:223], v[70:73]
	v_mfma_f32_16x16x32_bf16 v[66:69], v[170:173], v[220:223], v[66:69]
	v_mfma_f32_16x16x32_bf16 v[118:121], v[166:169], v[182:185], v[118:121]
	v_mfma_f32_16x16x32_bf16 v[114:117], v[174:177], v[182:185], v[114:117]
	v_mfma_f32_16x16x32_bf16 v[102:105], v[166:169], v[208:211], v[102:105]
	v_mfma_f32_16x16x32_bf16 v[98:101], v[174:177], v[208:211], v[98:101]
	v_mfma_f32_16x16x32_bf16 v[86:89], v[166:169], v[216:219], v[86:89]
	v_mfma_f32_16x16x32_bf16 v[82:85], v[174:177], v[216:219], v[82:85]
	v_mfma_f32_16x16x32_bf16 v[70:73], v[166:169], v[224:227], v[70:73]
	v_mfma_f32_16x16x32_bf16 v[66:69], v[174:177], v[224:227], v[66:69]
	s_barrier
; #define PG8_STAGE(bufoff, gbase, voff) do { _Pragma("unroll") for (int _i = 0; _i < 2; ++_i) \
;         __builtin_amdgcn_global_load_lds((const unsigned*)((const char*)(gbase) + (voff)[_i]), (LAS unsigned*)(lds + (bufoff) + ldsw + _i * 8192), 16, 0, 0); } while (0)
; #define PG8_LDA(dst, b, h) do { _Pragma("unroll") for (int m = 0; m < 4; ++m) _Pragma("unroll") for (int k = 0; k < 2; ++k) dst[m][k] = *(const LAS bf16x8*)(lds + PG8_SA(b, h) + aoff + m * 2048 + k * 1024); } while (0)
; #define PG8_MMA(ai, bj, At, Bt) do { __builtin_amdgcn_s_setprio(1); _Pragma("unroll") for (int m = 0; m < 4; ++m) _Pragma("unroll") for (int n = 0; n < 2; ++n) _Pragma("unroll") for (int k = 0; k < 2; ++k) \
;         acc[ai][bj][m][n] = __builtin_amdgcn_mfma_f32_16x16x32_bf16(Bt[n][k], At[m][k], acc[ai][bj][m][n], 0, 0, 0); __builtin_amdgcn_s_setprio(0); } while (0)
; #define PG8_WAIT_V(n) asm volatile("s_waitcnt vmcnt(" #n ")" ::: "memory")
; #define PG8_WAIT_L(n) asm volatile("s_waitcnt lgkmcnt(" #n ")" ::: "memory")
; #define PG8_BAR __builtin_amdgcn_s_barrier()
; #define PG8_SCHED __builtin_amdgcn_sched_barrier(0)
; template <class Epi, class Sched>
; __device__ __forceinline__ void gemm_phase(LAS unsigned char* lds, const Gemm g, const Sched& S, const Epi& E) {
;     ...
;             PG8_LDA(At, 1, 1); PG8_STAGE(PG8_SB(1, 0), b3, voffB); PG8_STAGE(PG8_SB(1, 1), b3 + hsB, voffB); PG8_STAGE(PG8_SA(1, 0), a3, voffA);
;             PG8_WAIT_V(8); PG8_WAIT_L(0); PG8_BAR; PG8_MMA(1, 0, At, B0); PG8_MMA(1, 1, At, B1); PG8_BAR; PG8_SCHED;
;         }
	s_add_i32 s42, s74, s7
	v_lshl_add_u64 v[190:191], v[190:191], 0, s[18:19]
	s_mov_b32 m0, s42
	ds_read_b128 v[178:181], v145 offset:49152
	ds_read_b128 v[182:185], v145 offset:50176
	ds_read_b128 v[186:189], v145 offset:51200
	ds_read_b128 v[208:211], v145 offset:52224
	global_load_lds_dwordx4 v[190:191], off
	v_lshl_add_u64 v[190:191], v[228:229], 0, s[18:19]
	s_add_i32 m0, s42, 0x2000
	s_add_i32 s42, s75, s7
	global_load_lds_dwordx4 v[190:191], off
	v_lshl_add_u64 v[190:191], v[230:231], 0, s[18:19]
	s_mov_b32 m0, s42
	ds_read_b128 v[212:215], v145 offset:53248
	global_load_lds_dwordx4 v[190:191], off
	v_lshl_add_u64 v[190:191], v[232:233], 0, s[18:19]
	s_add_i32 m0, s42, 0x2000
	ds_read_b128 v[216:219], v145 offset:54272
	global_load_lds_dwordx4 v[190:191], off
	v_lshl_add_u64 v[190:191], v[238:239], 0, s[18:19]
	s_mov_b32 m0, s30
	ds_read_b128 v[220:223], v145 offset:55296
	global_load_lds_dwordx4 v[190:191], off
	v_lshl_add_u64 v[190:191], v[240:241], 0, s[18:19]
	s_mov_b32 m0, s48
	ds_read_b128 v[224:227], v145 offset:56320
	global_load_lds_dwordx4 v[190:191], off
	s_waitcnt vmcnt(8)
	s_waitcnt lgkmcnt(0)
	s_barrier
	s_waitcnt lgkmcnt(0)
	v_mfma_f32_16x16x32_bf16 v[62:65], v[146:149], v[178:181], v[62:65]
	v_mfma_f32_16x16x32_bf16 v[58:61], v[154:157], v[178:181], v[58:61]
	v_mfma_f32_16x16x32_bf16 v[46:49], v[146:149], v[186:189], v[46:49]
	v_mfma_f32_16x16x32_bf16 v[42:45], v[154:157], v[186:189], v[42:45]
	v_mfma_f32_16x16x32_bf16 v[30:33], v[146:149], v[212:215], v[30:33]
	v_mfma_f32_16x16x32_bf16 v[26:29], v[154:157], v[212:215], v[26:29]
	v_mfma_f32_16x16x32_bf16 v[14:17], v[146:149], v[220:223], v[14:17]
	v_mfma_f32_16x16x32_bf16 v[10:13], v[154:157], v[220:223], v[10:13]
	v_mfma_f32_16x16x32_bf16 v[62:65], v[150:153], v[182:185], v[62:65]
	v_mfma_f32_16x16x32_bf16 v[58:61], v[158:161], v[182:185], v[58:61]
	v_mfma_f32_16x16x32_bf16 v[46:49], v[150:153], v[208:211], v[46:49]
	v_mfma_f32_16x16x32_bf16 v[42:45], v[158:161], v[208:211], v[42:45]
	v_mfma_f32_16x16x32_bf16 v[30:33], v[150:153], v[216:219], v[30:33]
	v_mfma_f32_16x16x32_bf16 v[26:29], v[158:161], v[216:219], v[26:29]
	v_mfma_f32_16x16x32_bf16 v[14:17], v[150:153], v[224:227], v[14:17]
	v_mfma_f32_16x16x32_bf16 v[10:13], v[158:161], v[224:227], v[10:13]
	v_mfma_f32_16x16x32_bf16 v[54:57], v[162:165], v[178:181], v[54:57]
	v_mfma_f32_16x16x32_bf16 v[50:53], v[170:173], v[178:181], v[50:53]
	v_mfma_f32_16x16x32_bf16 v[38:41], v[162:165], v[186:189], v[38:41]
	v_mfma_f32_16x16x32_bf16 v[34:37], v[170:173], v[186:189], v[34:37]
	v_mfma_f32_16x16x32_bf16 v[22:25], v[162:165], v[212:215], v[22:25]
	v_mfma_f32_16x16x32_bf16 v[18:21], v[170:173], v[212:215], v[18:21]
	v_mfma_f32_16x16x32_bf16 v[6:9], v[162:165], v[220:223], v[6:9]
	v_mfma_f32_16x16x32_bf16 v[2:5], v[170:173], v[220:223], v[2:5]
	v_mfma_f32_16x16x32_bf16 v[54:57], v[166:169], v[182:185], v[54:57]
	v_mfma_f32_16x16x32_bf16 v[50:53], v[174:177], v[182:185], v[50:53]
	v_mfma_f32_16x16x32_bf16 v[38:41], v[166:169], v[208:211], v[38:41]
	v_mfma_f32_16x16x32_bf16 v[34:37], v[174:177], v[208:211], v[34:37]
	v_mfma_f32_16x16x32_bf16 v[22:25], v[166:169], v[216:219], v[22:25]
	v_mfma_f32_16x16x32_bf16 v[18:21], v[174:177], v[216:219], v[18:21]
	v_mfma_f32_16x16x32_bf16 v[6:9], v[166:169], v[224:227], v[6:9]
	v_mfma_f32_16x16x32_bf16 v[2:5], v[174:177], v[224:227], v[2:5]
	s_barrier
	s_cmp_ge_i32 s73, s24
	s_mov_b64 s[42:43], s[44:45]
	s_mov_b32 s46, s73
	s_cbranch_scc0 .LBB0_763
	s_setprio 0

; #define PG8_STAGE(bufoff, gbase, voff) do { _Pragma("unroll") for (int _i = 0; _i < 2; ++_i) \
;         __builtin_amdgcn_global_load_lds((const unsigned*)((const char*)(gbase) + (voff)[_i]), (LAS unsigned*)(lds + (bufoff) + ldsw + _i * 8192), 16, 0, 0); } while (0)
; #define PG8_LDA(dst, b, h) do { _Pragma("unroll") for (int m = 0; m < 4; ++m) _Pragma("unroll") for (int k = 0; k < 2; ++k) dst[m][k] = *(const LAS bf16x8*)(lds + PG8_SA(b, h) + aoff + m * 2048 + k * 1024); } while (0)
; #define PG8_LDB(dst, b, h) do { _Pragma("unroll") for (int n = 0; n < 2; ++n) _Pragma("unroll") for (int k = 0; k < 2; ++k) dst[n][k] = *(const LAS bf16x8*)(lds + PG8_SB(b, h) + boff + n * 2048 + k * 1024); } while (0)
; #define PG8_MMA(ai, bj, At, Bt) do { __builtin_amdgcn_s_setprio(1); _Pragma("unroll") for (int m = 0; m < 4; ++m) _Pragma("unroll") for (int n = 0; n < 2; ++n) _Pragma("unroll") for (int k = 0; k < 2; ++k) \
;         acc[ai][bj][m][n] = __builtin_amdgcn_mfma_f32_16x16x32_bf16(Bt[n][k], At[m][k], acc[ai][bj][m][n], 0, 0, 0); __builtin_amdgcn_s_setprio(0); } while (0)
; #define PG8_WAIT_V(n) asm volatile("s_waitcnt vmcnt(" #n ")" ::: "memory")
; #define PG8_WAIT_L(n) asm volatile("s_waitcnt lgkmcnt(" #n ")" ::: "memory")
; template <class Epi, class Sched>
; __device__ __forceinline__ void gemm_phase(LAS unsigned char* lds, const Gemm g, const Sched& S, const Epi& E) {
;     ...
;             const bool last = (t == nt - 2);
;             const char* a1 = cA + (size_t)(t + 1) * kstep;
;             const char* a2 = last ? nA : cA + (size_t)(t + 2) * kstep; const char* b2 = last ? nB : cB + (size_t)(t + 2) * kstep;
;             const char* a3 = a2 + kstep; const char* b3 = b2 + kstep;
;             if constexpr (Epi::MIDK) { if (t == (nt >> 1)) { int fr_ = fr, fq_ = fq; asm volatile("" : "+v"(fr_), "+v"(fq_)); E.mid(acc, cur, wr, wc, fr_, fq_); } }
;             PG8_LDB(B0, 0, 0); PG8_LDB(B1, 0, 1); PG8_SCHED; PG8_LDA(At, 0, 0); PG8_STAGE(PG8_SA(1, 1), a1 + hsA, voffA);
;             PG8_WAIT_V(8); PG8_WAIT_L(0); PG8_BAR; PG8_MMA(0, 0, At, B0); PG8_MMA(0, 1, At, B1); PG8_BAR; PG8_SCHED;
;             PG8_LDA(At, 0, 1); PG8_STAGE(PG8_SB(0, 0), b2, voffB); PG8_STAGE(PG8_SB(0, 1), b2 + hsB, voffB); PG8_STAGE(PG8_SA(0, 0), a2, voffA);
;             PG8_WAIT_V(8); PG8_WAIT_L(0); PG8_BAR; PG8_MMA(1, 0, At, B0); PG8_MMA(1, 1, At, B1); PG8_BAR; PG8_SCHED;
.LBB0_837:
	s_add_i32 s96, s76, 2
	s_add_u32 s74, s50, 0xfffc0080
	s_addc_u32 s75, s51, -1
	s_cmp_eq_u32 s64, s76
	s_cselect_b32 s85, s10, s75
	s_cselect_b32 s84, s35, s74
	s_cselect_b32 s77, s41, s1
	s_cselect_b32 s76, s83, s0
	s_add_i32 s74, 0, 0x10000
	v_add_u32_e32 v0, s74, v206
	s_add_i32 s75, 0, 0x14000
	ds_read_b128 v[132:135], v0
	ds_read_b128 v[136:139], v0 offset:1024
	ds_read_b128 v[140:143], v0 offset:2048
	ds_read_b128 v[144:147], v0 offset:3072
	v_add_u32_e32 v0, s75, v206
	ds_read_b128 v[148:151], v0
	ds_read_b128 v[152:155], v0 offset:1024
	ds_read_b128 v[156:159], v0 offset:2048
	ds_read_b128 v[160:163], v0 offset:3072
	v_lshl_add_u64 v[2:3], s[50:51], 0, v[216:217]
	s_add_i32 m0, s11, 0xc000
	ds_read_b128 v[164:167], v238
	ds_read_b128 v[168:171], v238 offset:1024
	ds_read_b128 v[172:175], v238 offset:2048
	ds_read_b128 v[176:179], v238 offset:3072
	ds_read_b128 v[180:183], v238 offset:4096
	ds_read_b128 v[184:187], v238 offset:5120
	ds_read_b128 v[188:191], v238 offset:6144
	global_load_lds_dwordx4 v[2:3], off
	v_lshl_add_u64 v[2:3], s[50:51], 0, v[218:219]
	s_add_i32 m0, s11, 0xe000
	ds_read_b128 v[220:223], v238 offset:7168
	global_load_lds_dwordx4 v[2:3], off
	s_waitcnt vmcnt(8)
	s_waitcnt lgkmcnt(0)
	s_barrier
	s_waitcnt lgkmcnt(0)
	v_mfma_f32_16x16x32_bf16 v[124:127], v[132:135], v[164:167], v[124:127]
	v_mfma_f32_16x16x32_bf16 v[128:131], v[140:143], v[164:167], v[128:131]
	v_mfma_f32_16x16x32_bf16 v[112:115], v[132:135], v[172:175], v[112:115]
	v_mfma_f32_16x16x32_bf16 v[108:111], v[140:143], v[172:175], v[108:111]
	v_mfma_f32_16x16x32_bf16 v[96:99], v[132:135], v[180:183], v[96:99]
	v_mfma_f32_16x16x32_bf16 v[92:95], v[140:143], v[180:183], v[92:95]
	v_mfma_f32_16x16x32_bf16 v[80:83], v[132:135], v[188:191], v[80:83]
	v_mfma_f32_16x16x32_bf16 v[76:79], v[140:143], v[188:191], v[76:79]
	v_mfma_f32_16x16x32_bf16 v[124:127], v[136:139], v[168:171], v[124:127]
	v_mfma_f32_16x16x32_bf16 v[128:131], v[144:147], v[168:171], v[128:131]
	v_mfma_f32_16x16x32_bf16 v[112:115], v[136:139], v[176:179], v[112:115]
	v_mfma_f32_16x16x32_bf16 v[108:111], v[144:147], v[176:179], v[108:111]
	v_mfma_f32_16x16x32_bf16 v[96:99], v[136:139], v[184:187], v[96:99]
	v_mfma_f32_16x16x32_bf16 v[92:95], v[144:147], v[184:187], v[92:95]
	v_mfma_f32_16x16x32_bf16 v[80:83], v[136:139], v[220:223], v[80:83]
	v_mfma_f32_16x16x32_bf16 v[76:79], v[144:147], v[220:223], v[76:79]
	v_mfma_f32_16x16x32_bf16 v[116:119], v[148:151], v[164:167], v[116:119]
	v_mfma_f32_16x16x32_bf16 v[120:123], v[156:159], v[164:167], v[120:123]
	v_mfma_f32_16x16x32_bf16 v[104:107], v[148:151], v[172:175], v[104:107]
	v_mfma_f32_16x16x32_bf16 v[100:103], v[156:159], v[172:175], v[100:103]
	v_mfma_f32_16x16x32_bf16 v[88:91], v[148:151], v[180:183], v[88:91]
	v_mfma_f32_16x16x32_bf16 v[84:87], v[156:159], v[180:183], v[84:87]
	v_mfma_f32_16x16x32_bf16 v[72:75], v[148:151], v[188:191], v[72:75]
	v_mfma_f32_16x16x32_bf16 v[68:71], v[156:159], v[188:191], v[68:71]
	v_mfma_f32_16x16x32_bf16 v[116:119], v[152:155], v[168:171], v[116:119]
	v_mfma_f32_16x16x32_bf16 v[120:123], v[160:163], v[168:171], v[120:123]
	v_mfma_f32_16x16x32_bf16 v[104:107], v[152:155], v[176:179], v[104:107]
	v_mfma_f32_16x16x32_bf16 v[100:103], v[160:163], v[176:179], v[100:103]
	v_mfma_f32_16x16x32_bf16 v[88:91], v[152:155], v[184:187], v[88:91]
	v_mfma_f32_16x16x32_bf16 v[84:87], v[160:163], v[184:187], v[84:87]
	v_mfma_f32_16x16x32_bf16 v[72:75], v[152:155], v[220:223], v[72:75]
	v_mfma_f32_16x16x32_bf16 v[68:71], v[160:163], v[220:223], v[68:71]
	s_barrier
	s_add_i32 s74, s74, s7
	v_lshl_add_u64 v[224:225], s[76:77], 0, v[212:213]
	s_mov_b32 m0, s74
	ds_read_b128 v[164:167], v238 offset:16384
	ds_read_b128 v[168:171], v238 offset:17408
	ds_read_b128 v[172:175], v238 offset:18432
	ds_read_b128 v[176:179], v238 offset:19456
	ds_read_b128 v[180:183], v238 offset:20480
	ds_read_b128 v[184:187], v238 offset:21504
	global_load_lds_dwordx4 v[224:225], off
	s_add_i32 m0, s74, 0x2000
	s_add_u32 vcc_lo, s76, 0x40000
	v_lshl_add_u64 v[226:227], s[76:77], 0, v[208:209]
	s_addc_u32 vcc_hi, s77, 0
	s_add_i32 s74, s75, s7
	global_load_lds_dwordx4 v[226:227], off
	v_lshl_add_u64 v[2:3], vcc, 0, v[212:213]
	s_mov_b32 m0, s74
	v_lshl_add_u64 v[228:229], s[84:85], 0, v[214:215]
	global_load_lds_dwordx4 v[2:3], off
	v_lshl_add_u64 v[2:3], vcc, 0, v[208:209]
	s_add_i32 m0, s74, 0x2000
	v_lshl_add_u64 v[230:231], s[84:85], 0, v[210:211]
	global_load_lds_dwordx4 v[2:3], off
	s_mov_b32 m0, s11
	ds_read_b128 v[188:191], v238 offset:22528
	global_load_lds_dwordx4 v[228:229], off
	s_mov_b32 m0, s12
	ds_read_b128 v[220:223], v238 offset:23552
	global_load_lds_dwordx4 v[230:231], off
	s_waitcnt vmcnt(8)
	s_waitcnt lgkmcnt(0)
	s_barrier
; #define PG8_STAGE(bufoff, gbase, voff) do { _Pragma("unroll") for (int _i = 0; _i < 2; ++_i) \
;         __builtin_amdgcn_global_load_lds((const unsigned*)((const char*)(gbase) + (voff)[_i]), (LAS unsigned*)(lds + (bufoff) + ldsw + _i * 8192), 16, 0, 0); } while (0)
; #define PG8_LDA(dst, b, h) do { _Pragma("unroll") for (int m = 0; m < 4; ++m) _Pragma("unroll") for (int k = 0; k < 2; ++k) dst[m][k] = *(const LAS bf16x8*)(lds + PG8_SA(b, h) + aoff + m * 2048 + k * 1024); } while (0)
; #define PG8_LDB(dst, b, h) do { _Pragma("unroll") for (int n = 0; n < 2; ++n) _Pragma("unroll") for (int k = 0; k < 2; ++k) dst[n][k] = *(const LAS bf16x8*)(lds + PG8_SB(b, h) + boff + n * 2048 + k * 1024); } while (0)
; #define PG8_MMA(ai, bj, At, Bt) do { __builtin_amdgcn_s_setprio(1); _Pragma("unroll") for (int m = 0; m < 4; ++m) _Pragma("unroll") for (int n = 0; n < 2; ++n) _Pragma("unroll") for (int k = 0; k < 2; ++k) \
;         acc[ai][bj][m][n] = __builtin_amdgcn_mfma_f32_16x16x32_bf16(Bt[n][k], At[m][k], acc[ai][bj][m][n], 0, 0, 0); __builtin_amdgcn_s_setprio(0); } while (0)
; #define PG8_WAIT_V(n) asm volatile("s_waitcnt vmcnt(" #n ")" ::: "memory")
; #define PG8_WAIT_L(n) asm volatile("s_waitcnt lgkmcnt(" #n ")" ::: "memory")
; #define PG8_BAR __builtin_amdgcn_s_barrier()
; #define PG8_SCHED __builtin_amdgcn_sched_barrier(0)
; template <class Epi, class Sched>
; __device__ __forceinline__ void gemm_phase(LAS unsigned char* lds, const Gemm g, const Sched& S, const Epi& E) {
;     ...
;             PG8_WAIT_V(8); PG8_WAIT_L(0); PG8_BAR; PG8_MMA(1, 0, At, B0); PG8_MMA(1, 1, At, B1); PG8_BAR; PG8_SCHED;
;             PG8_LDB(B0, 1, 0); PG8_LDB(B1, 1, 1); PG8_SCHED; PG8_LDA(At, 1, 0); PG8_STAGE(PG8_SA(0, 1), a2 + hsA, voffA);
;             PG8_WAIT_V(8); PG8_WAIT_L(0); PG8_BAR; PG8_MMA(0, 0, At, B0); PG8_MMA(0, 1, At, B1); PG8_BAR; PG8_SCHED;
	s_waitcnt lgkmcnt(0)
	v_mfma_f32_16x16x32_bf16 v[64:67], v[132:135], v[164:167], v[64:67]
	v_mfma_f32_16x16x32_bf16 v[60:63], v[140:143], v[164:167], v[60:63]
	v_mfma_f32_16x16x32_bf16 v[48:51], v[132:135], v[172:175], v[48:51]
	v_mfma_f32_16x16x32_bf16 v[44:47], v[140:143], v[172:175], v[44:47]
	v_mfma_f32_16x16x32_bf16 v[32:35], v[132:135], v[180:183], v[32:35]
	v_mfma_f32_16x16x32_bf16 v[28:31], v[140:143], v[180:183], v[28:31]
	v_mfma_f32_16x16x32_bf16 v[16:19], v[132:135], v[188:191], v[16:19]
	v_mfma_f32_16x16x32_bf16 v[12:15], v[140:143], v[188:191], v[12:15]
	v_mfma_f32_16x16x32_bf16 v[64:67], v[136:139], v[168:171], v[64:67]
	v_mfma_f32_16x16x32_bf16 v[60:63], v[144:147], v[168:171], v[60:63]
	v_mfma_f32_16x16x32_bf16 v[48:51], v[136:139], v[176:179], v[48:51]
	v_mfma_f32_16x16x32_bf16 v[44:47], v[144:147], v[176:179], v[44:47]
	v_mfma_f32_16x16x32_bf16 v[32:35], v[136:139], v[184:187], v[32:35]
	v_mfma_f32_16x16x32_bf16 v[28:31], v[144:147], v[184:187], v[28:31]
	v_mfma_f32_16x16x32_bf16 v[16:19], v[136:139], v[220:223], v[16:19]
	v_mfma_f32_16x16x32_bf16 v[12:15], v[144:147], v[220:223], v[12:15]
	v_mfma_f32_16x16x32_bf16 v[56:59], v[148:151], v[164:167], v[56:59]
	v_mfma_f32_16x16x32_bf16 v[52:55], v[156:159], v[164:167], v[52:55]
	v_mfma_f32_16x16x32_bf16 v[40:43], v[148:151], v[172:175], v[40:43]
	v_mfma_f32_16x16x32_bf16 v[36:39], v[156:159], v[172:175], v[36:39]
	v_mfma_f32_16x16x32_bf16 v[24:27], v[148:151], v[180:183], v[24:27]
	v_mfma_f32_16x16x32_bf16 v[20:23], v[156:159], v[180:183], v[20:23]
	v_mfma_f32_16x16x32_bf16 v[8:11], v[148:151], v[188:191], v[8:11]
	v_mfma_f32_16x16x32_bf16 v[2:5], v[156:159], v[188:191], v[4:7]
	v_mfma_f32_16x16x32_bf16 v[56:59], v[152:155], v[168:171], v[56:59]
	v_mfma_f32_16x16x32_bf16 v[52:55], v[160:163], v[168:171], v[52:55]
	v_mfma_f32_16x16x32_bf16 v[40:43], v[152:155], v[176:179], v[40:43]
	v_mfma_f32_16x16x32_bf16 v[36:39], v[160:163], v[176:179], v[36:39]
	v_mfma_f32_16x16x32_bf16 v[24:27], v[152:155], v[184:187], v[24:27]
	v_mfma_f32_16x16x32_bf16 v[20:23], v[160:163], v[184:187], v[20:23]
	v_mfma_f32_16x16x32_bf16 v[8:11], v[152:155], v[220:223], v[8:11]
	v_mfma_f32_16x16x32_bf16 v[2:5], v[160:163], v[220:223], v[2:5]
	s_barrier
	s_add_i32 s74, 0, 0x18000
	v_add_u32_e32 v0, s74, v206
	s_add_i32 s75, 0, 0x1c000
	ds_read_b128 v[132:135], v0
	ds_read_b128 v[136:139], v0 offset:1024
	ds_read_b128 v[140:143], v0 offset:2048
	ds_read_b128 v[144:147], v0 offset:3072
	v_add_u32_e32 v0, s75, v206
	ds_read_b128 v[148:151], v0
	ds_read_b128 v[152:155], v0 offset:1024
	ds_read_b128 v[156:159], v0 offset:2048
	ds_read_b128 v[160:163], v0 offset:3072
	s_add_u32 s84, s84, 0x40000
	s_addc_u32 s85, s85, 0
	s_mov_b32 m0, s16
	v_lshl_add_u64 v[6:7], s[84:85], 0, v[214:215]
	ds_read_b128 v[164:167], v238 offset:32768
	ds_read_b128 v[168:171], v238 offset:33792
	ds_read_b128 v[172:175], v238 offset:34816
	ds_read_b128 v[176:179], v238 offset:35840
	ds_read_b128 v[180:183], v238 offset:36864
	ds_read_b128 v[184:187], v238 offset:37888
	ds_read_b128 v[188:191], v238 offset:38912
	global_load_lds_dwordx4 v[6:7], off
	v_lshl_add_u64 v[6:7], s[84:85], 0, v[210:211]
	s_mov_b32 m0, s24
	ds_read_b128 v[220:223], v238 offset:39936
	global_load_lds_dwordx4 v[6:7], off
	s_waitcnt vmcnt(8)
	s_waitcnt lgkmcnt(0)
	s_barrier
	s_waitcnt lgkmcnt(0)
	v_mfma_f32_16x16x32_bf16 v[124:127], v[132:135], v[164:167], v[124:127]
	v_mfma_f32_16x16x32_bf16 v[128:131], v[140:143], v[164:167], v[128:131]
	v_mfma_f32_16x16x32_bf16 v[112:115], v[132:135], v[172:175], v[112:115]
	v_mfma_f32_16x16x32_bf16 v[108:111], v[140:143], v[172:175], v[108:111]
	v_mfma_f32_16x16x32_bf16 v[96:99], v[132:135], v[180:183], v[96:99]
	v_mfma_f32_16x16x32_bf16 v[92:95], v[140:143], v[180:183], v[92:95]
	v_mfma_f32_16x16x32_bf16 v[80:83], v[132:135], v[188:191], v[80:83]
	v_mfma_f32_16x16x32_bf16 v[76:79], v[140:143], v[188:191], v[76:79]
	v_mfma_f32_16x16x32_bf16 v[124:127], v[136:139], v[168:171], v[124:127]
	v_mfma_f32_16x16x32_bf16 v[128:131], v[144:147], v[168:171], v[128:131]
	v_mfma_f32_16x16x32_bf16 v[112:115], v[136:139], v[176:179], v[112:115]
	v_mfma_f32_16x16x32_bf16 v[108:111], v[144:147], v[176:179], v[108:111]
	v_mfma_f32_16x16x32_bf16 v[96:99], v[136:139], v[184:187], v[96:99]
	v_mfma_f32_16x16x32_bf16 v[92:95], v[144:147], v[184:187], v[92:95]
	v_mfma_f32_16x16x32_bf16 v[80:83], v[136:139], v[220:223], v[80:83]
	v_mfma_f32_16x16x32_bf16 v[76:79], v[144:147], v[220:223], v[76:79]
	v_mfma_f32_16x16x32_bf16 v[116:119], v[148:151], v[164:167], v[116:119]
	v_mfma_f32_16x16x32_bf16 v[120:123], v[156:159], v[164:167], v[120:123]
	v_mfma_f32_16x16x32_bf16 v[104:107], v[148:151], v[172:175], v[104:107]
	v_mfma_f32_16x16x32_bf16 v[100:103], v[156:159], v[172:175], v[100:103]
	v_mfma_f32_16x16x32_bf16 v[88:91], v[148:151], v[180:183], v[88:91]
	v_mfma_f32_16x16x32_bf16 v[84:87], v[156:159], v[180:183], v[84:87]
	v_mfma_f32_16x16x32_bf16 v[72:75], v[148:151], v[188:191], v[72:75]
	v_mfma_f32_16x16x32_bf16 v[68:71], v[156:159], v[188:191], v[68:71]
	v_mfma_f32_16x16x32_bf16 v[116:119], v[152:155], v[168:171], v[116:119]
	v_mfma_f32_16x16x32_bf16 v[120:123], v[160:163], v[168:171], v[120:123]
	v_mfma_f32_16x16x32_bf16 v[104:107], v[152:155], v[176:179], v[104:107]
	v_mfma_f32_16x16x32_bf16 v[100:103], v[160:163], v[176:179], v[100:103]
	v_mfma_f32_16x16x32_bf16 v[88:91], v[152:155], v[184:187], v[88:91]
	v_mfma_f32_16x16x32_bf16 v[84:87], v[160:163], v[184:187], v[84:87]
	v_mfma_f32_16x16x32_bf16 v[72:75], v[152:155], v[220:223], v[72:75]
	v_mfma_f32_16x16x32_bf16 v[68:71], v[160:163], v[220:223], v[68:71]
	s_barrier
; #define PG8_STAGE(bufoff, gbase, voff) do { _Pragma("unroll") for (int _i = 0; _i < 2; ++_i) \
;         __builtin_amdgcn_global_load_lds((const unsigned*)((const char*)(gbase) + (voff)[_i]), (LAS unsigned*)(lds + (bufoff) + ldsw + _i * 8192), 16, 0, 0); } while (0)
; #define PG8_LDA(dst, b, h) do { _Pragma("unroll") for (int m = 0; m < 4; ++m) _Pragma("unroll") for (int k = 0; k < 2; ++k) dst[m][k] = *(const LAS bf16x8*)(lds + PG8_SA(b, h) + aoff + m * 2048 + k * 1024); } while (0)
; #define PG8_MMA(ai, bj, At, Bt) do { __builtin_amdgcn_s_setprio(1); _Pragma("unroll") for (int m = 0; m < 4; ++m) _Pragma("unroll") for (int n = 0; n < 2; ++n) _Pragma("unroll") for (int k = 0; k < 2; ++k) \
;         acc[ai][bj][m][n] = __builtin_amdgcn_mfma_f32_16x16x32_bf16(Bt[n][k], At[m][k], acc[ai][bj][m][n], 0, 0, 0); __builtin_amdgcn_s_setprio(0); } while (0)
; #define PG8_WAIT_V(n) asm volatile("s_waitcnt vmcnt(" #n ")" ::: "memory")
; #define PG8_WAIT_L(n) asm volatile("s_waitcnt lgkmcnt(" #n ")" ::: "memory")
; #define PG8_BAR __builtin_amdgcn_s_barrier()
; #define PG8_SCHED __builtin_amdgcn_sched_barrier(0)
; template <class Epi, class Sched>
; __device__ __forceinline__ void gemm_phase(LAS unsigned char* lds, const Gemm g, const Sched& S, const Epi& E) {
;     ...
;             PG8_LDA(At, 1, 1); PG8_STAGE(PG8_SB(1, 0), b3, voffB); PG8_STAGE(PG8_SB(1, 1), b3 + hsB, voffB); PG8_STAGE(PG8_SA(1, 0), a3, voffA);
;             PG8_WAIT_V(8); PG8_WAIT_L(0); PG8_BAR; PG8_MMA(1, 0, At, B0); PG8_MMA(1, 1, At, B1); PG8_BAR; PG8_SCHED;
;         }
	s_add_i32 s74, s74, s7
	v_lshl_add_u64 v[6:7], v[224:225], 0, s[18:19]
	s_mov_b32 m0, s74
	ds_read_b128 v[164:167], v238 offset:49152
	ds_read_b128 v[168:171], v238 offset:50176
	ds_read_b128 v[172:175], v238 offset:51200
	ds_read_b128 v[176:179], v238 offset:52224
	global_load_lds_dwordx4 v[6:7], off
	s_add_i32 m0, s74, 0x2000
	s_add_u32 s76, s76, 0x40080
	v_lshl_add_u64 v[6:7], v[226:227], 0, s[18:19]
	s_addc_u32 s77, s77, 0
	s_add_i32 s74, s75, s7
	global_load_lds_dwordx4 v[6:7], off
	v_lshl_add_u64 v[6:7], s[76:77], 0, v[212:213]
	s_mov_b32 m0, s74
	ds_read_b128 v[180:183], v238 offset:53248
	global_load_lds_dwordx4 v[6:7], off
	v_lshl_add_u64 v[6:7], s[76:77], 0, v[208:209]
	s_add_i32 m0, s74, 0x2000
	ds_read_b128 v[184:187], v238 offset:54272
	global_load_lds_dwordx4 v[6:7], off
	v_lshl_add_u64 v[6:7], v[228:229], 0, s[18:19]
	s_mov_b32 m0, s56
	ds_read_b128 v[188:191], v238 offset:55296
	global_load_lds_dwordx4 v[6:7], off
	v_lshl_add_u64 v[6:7], v[230:231], 0, s[18:19]
	s_mov_b32 m0, s57
	ds_read_b128 v[220:223], v238 offset:56320
	global_load_lds_dwordx4 v[6:7], off
	s_waitcnt vmcnt(8)
	s_waitcnt lgkmcnt(0)
	s_barrier
	s_waitcnt lgkmcnt(0)
	v_mfma_f32_16x16x32_bf16 v[64:67], v[132:135], v[164:167], v[64:67]
	v_mfma_f32_16x16x32_bf16 v[60:63], v[140:143], v[164:167], v[60:63]
	v_mfma_f32_16x16x32_bf16 v[48:51], v[132:135], v[172:175], v[48:51]
	v_mfma_f32_16x16x32_bf16 v[44:47], v[140:143], v[172:175], v[44:47]
	v_mfma_f32_16x16x32_bf16 v[32:35], v[132:135], v[180:183], v[32:35]
	v_mfma_f32_16x16x32_bf16 v[28:31], v[140:143], v[180:183], v[28:31]
	v_mfma_f32_16x16x32_bf16 v[16:19], v[132:135], v[188:191], v[16:19]
	v_mfma_f32_16x16x32_bf16 v[12:15], v[140:143], v[188:191], v[12:15]
	v_mfma_f32_16x16x32_bf16 v[64:67], v[136:139], v[168:171], v[64:67]
	v_mfma_f32_16x16x32_bf16 v[60:63], v[144:147], v[168:171], v[60:63]
	v_mfma_f32_16x16x32_bf16 v[48:51], v[136:139], v[176:179], v[48:51]
	v_mfma_f32_16x16x32_bf16 v[44:47], v[144:147], v[176:179], v[44:47]
	v_mfma_f32_16x16x32_bf16 v[32:35], v[136:139], v[184:187], v[32:35]
	v_mfma_f32_16x16x32_bf16 v[28:31], v[144:147], v[184:187], v[28:31]
	v_mfma_f32_16x16x32_bf16 v[16:19], v[136:139], v[220:223], v[16:19]
	v_mfma_f32_16x16x32_bf16 v[12:15], v[144:147], v[220:223], v[12:15]
	v_mfma_f32_16x16x32_bf16 v[56:59], v[148:151], v[164:167], v[56:59]
	v_mfma_f32_16x16x32_bf16 v[52:55], v[156:159], v[164:167], v[52:55]
	v_mfma_f32_16x16x32_bf16 v[40:43], v[148:151], v[172:175], v[40:43]
	v_mfma_f32_16x16x32_bf16 v[36:39], v[156:159], v[172:175], v[36:39]
	v_mfma_f32_16x16x32_bf16 v[24:27], v[148:151], v[180:183], v[24:27]
	v_mfma_f32_16x16x32_bf16 v[20:23], v[156:159], v[180:183], v[20:23]
	v_mfma_f32_16x16x32_bf16 v[6:9], v[148:151], v[188:191], v[8:11]
	v_mfma_f32_16x16x32_bf16 v[2:5], v[156:159], v[188:191], v[2:5]
	v_mfma_f32_16x16x32_bf16 v[56:59], v[152:155], v[168:171], v[56:59]
	v_mfma_f32_16x16x32_bf16 v[52:55], v[160:163], v[168:171], v[52:55]
	v_mfma_f32_16x16x32_bf16 v[40:43], v[152:155], v[176:179], v[40:43]
	v_mfma_f32_16x16x32_bf16 v[36:39], v[160:163], v[176:179], v[36:39]
	v_mfma_f32_16x16x32_bf16 v[24:27], v[152:155], v[184:187], v[24:27]
	v_mfma_f32_16x16x32_bf16 v[20:23], v[160:163], v[184:187], v[20:23]
	v_mfma_f32_16x16x32_bf16 v[8:11], v[152:155], v[220:223], v[6:9]
	v_mfma_f32_16x16x32_bf16 v[4:7], v[160:163], v[220:223], v[2:5]
	s_barrier
	s_add_u32 s50, s50, 0x100
	s_addc_u32 s51, s51, 0
	s_add_u32 s0, s0, 0x100
	s_addc_u32 s1, s1, 0
	s_cmp_ge_i32 s96, s26
	s_cbranch_scc1 .LBB0_839
	s_mov_b32 s76, s96
	s_cmp_lg_u32 s73, s76
	s_cbranch_scc0 .LBB0_836
	s_branch .LBB0_837

; #define PG8_STAGE(bufoff, gbase, voff) do { _Pragma("unroll") for (int _i = 0; _i < 2; ++_i) \
;         __builtin_amdgcn_global_load_lds((const unsigned*)((const char*)(gbase) + (voff)[_i]), (LAS unsigned*)(lds + (bufoff) + ldsw + _i * 8192), 16, 0, 0); } while (0)
; #define PG8_LDA(dst, b, h) do { _Pragma("unroll") for (int m = 0; m < 4; ++m) _Pragma("unroll") for (int k = 0; k < 2; ++k) dst[m][k] = *(const LAS bf16x8*)(lds + PG8_SA(b, h) + aoff + m * 2048 + k * 1024); } while (0)
; #define PG8_LDB(dst, b, h) do { _Pragma("unroll") for (int n = 0; n < 2; ++n) _Pragma("unroll") for (int k = 0; k < 2; ++k) dst[n][k] = *(const LAS bf16x8*)(lds + PG8_SB(b, h) + boff + n * 2048 + k * 1024); } while (0)
; #define PG8_MMA(ai, bj, At, Bt) do { __builtin_amdgcn_s_setprio(1); _Pragma("unroll") for (int m = 0; m < 4; ++m) _Pragma("unroll") for (int n = 0; n < 2; ++n) _Pragma("unroll") for (int k = 0; k < 2; ++k) \
;         acc[ai][bj][m][n] = __builtin_amdgcn_mfma_f32_16x16x32_bf16(Bt[n][k], At[m][k], acc[ai][bj][m][n], 0, 0, 0); __builtin_amdgcn_s_setprio(0); } while (0)
; #define PG8_WAIT_V(n) asm volatile("s_waitcnt vmcnt(" #n ")" ::: "memory")
; #define PG8_WAIT_L(n) asm volatile("s_waitcnt lgkmcnt(" #n ")" ::: "memory")
; template <class Epi, class Sched>
; __device__ __forceinline__ void gemm_phase(LAS unsigned char* lds, const Gemm g, const Sched& S, const Epi& E) {
;     ...
;             const bool last = (t == nt - 2);
;             const char* a1 = cA + (size_t)(t + 1) * kstep;
;             const char* a2 = last ? nA : cA + (size_t)(t + 2) * kstep; const char* b2 = last ? nB : cB + (size_t)(t + 2) * kstep;
;             const char* a3 = a2 + kstep; const char* b3 = b2 + kstep;
;             if constexpr (Epi::MIDK) { if (t == (nt >> 1)) { int fr_ = fr, fq_ = fq; asm volatile("" : "+v"(fr_), "+v"(fq_)); E.mid(acc, cur, wr, wc, fr_, fq_); } }
;             PG8_LDB(B0, 0, 0); PG8_LDB(B1, 0, 1); PG8_SCHED; PG8_LDA(At, 0, 0); PG8_STAGE(PG8_SA(1, 1), a1 + hsA, voffA);
;             PG8_WAIT_V(8); PG8_WAIT_L(0); PG8_BAR; PG8_MMA(0, 0, At, B0); PG8_MMA(0, 1, At, B1); PG8_BAR; PG8_SCHED;
;             PG8_LDA(At, 0, 1); PG8_STAGE(PG8_SB(0, 0), b2, voffB); PG8_STAGE(PG8_SB(0, 1), b2 + hsB, voffB); PG8_STAGE(PG8_SA(0, 0), a2, voffA);
;             PG8_WAIT_V(8); PG8_WAIT_L(0); PG8_BAR; PG8_MMA(1, 0, At, B0); PG8_MMA(1, 1, At, B1); PG8_BAR; PG8_SCHED;
.Lnp_912:
.LBB0_912:
	s_add_i32 s96, s50, 2
	s_add_u32 s51, s0, 0xfffc0080
	s_addc_u32 s74, s1, -1
	s_add_i32 s75, 0, 0x10000
	s_cmp_eq_u32 s73, s50
	s_cselect_b32 s77, s39, s74
	s_cselect_b32 s76, s41, s51
	s_cselect_b32 s51, s82, s85
	s_cselect_b32 s50, s83, s84
	s_add_i32 s74, 0, 0x14000
	v_add_u32_e32 v142, s75, v184
	v_add_u32_e32 v168, s74, v184
	ds_read_b128 v[130:133], v142
	ds_read_b128 v[134:137], v142 offset:1024
	ds_read_b128 v[138:141], v142 offset:2048
	ds_read_b128 v[142:145], v142 offset:3072
	ds_read_b128 v[146:149], v168
	ds_read_b128 v[150:153], v168 offset:1024
	ds_read_b128 v[164:167], v168 offset:2048
	ds_read_b128 v[168:171], v168 offset:3072
	v_lshl_add_u64 v[180:181], s[0:1], 0, v[160:161]
	s_add_i32 m0, s11, 0xc000
	ds_read_b128 v[172:175], v185
	ds_read_b128 v[176:179], v185 offset:1024
	ds_read_b128 v[186:189], v185 offset:2048
	ds_read_b128 v[208:211], v185 offset:3072
	ds_read_b128 v[212:215], v185 offset:4096
	ds_read_b128 v[216:219], v185 offset:5120
	ds_read_b128 v[220:223], v185 offset:6144
	global_load_lds_dwordx4 v[180:181], off
	v_lshl_add_u64 v[180:181], s[0:1], 0, v[162:163]
	s_add_i32 m0, s11, 0xe000
	ds_read_b128 v[224:227], v185 offset:7168
	global_load_lds_dwordx4 v[180:181], off
	s_waitcnt vmcnt(8)
	s_waitcnt lgkmcnt(0)
	s_barrier
	s_waitcnt lgkmcnt(0)
	v_mfma_f32_16x16x32_bf16 v[122:125], v[130:133], v[172:175], v[122:125]
	v_mfma_f32_16x16x32_bf16 v[126:129], v[138:141], v[172:175], v[126:129]
	v_mfma_f32_16x16x32_bf16 v[110:113], v[130:133], v[186:189], v[110:113]
	v_mfma_f32_16x16x32_bf16 v[106:109], v[138:141], v[186:189], v[106:109]
	v_mfma_f32_16x16x32_bf16 v[94:97], v[130:133], v[212:215], v[94:97]
	v_mfma_f32_16x16x32_bf16 v[90:93], v[138:141], v[212:215], v[90:93]
	v_mfma_f32_16x16x32_bf16 v[78:81], v[130:133], v[220:223], v[78:81]
	v_mfma_f32_16x16x32_bf16 v[74:77], v[138:141], v[220:223], v[74:77]
	v_mfma_f32_16x16x32_bf16 v[122:125], v[134:137], v[176:179], v[122:125]
	v_mfma_f32_16x16x32_bf16 v[126:129], v[142:145], v[176:179], v[126:129]
	v_mfma_f32_16x16x32_bf16 v[110:113], v[134:137], v[208:211], v[110:113]
	v_mfma_f32_16x16x32_bf16 v[106:109], v[142:145], v[208:211], v[106:109]
	v_mfma_f32_16x16x32_bf16 v[94:97], v[134:137], v[216:219], v[94:97]
	v_mfma_f32_16x16x32_bf16 v[90:93], v[142:145], v[216:219], v[90:93]
	v_mfma_f32_16x16x32_bf16 v[78:81], v[134:137], v[224:227], v[78:81]
	v_mfma_f32_16x16x32_bf16 v[74:77], v[142:145], v[224:227], v[74:77]
	v_mfma_f32_16x16x32_bf16 v[118:121], v[146:149], v[172:175], v[118:121]
	v_mfma_f32_16x16x32_bf16 v[114:117], v[164:167], v[172:175], v[114:117]
	v_mfma_f32_16x16x32_bf16 v[102:105], v[146:149], v[186:189], v[102:105]
	v_mfma_f32_16x16x32_bf16 v[98:101], v[164:167], v[186:189], v[98:101]
	v_mfma_f32_16x16x32_bf16 v[86:89], v[146:149], v[212:215], v[86:89]
	v_mfma_f32_16x16x32_bf16 v[82:85], v[164:167], v[212:215], v[82:85]
	v_mfma_f32_16x16x32_bf16 v[70:73], v[146:149], v[220:223], v[70:73]
	v_mfma_f32_16x16x32_bf16 v[66:69], v[164:167], v[220:223], v[66:69]
	v_mfma_f32_16x16x32_bf16 v[118:121], v[150:153], v[176:179], v[118:121]
	v_mfma_f32_16x16x32_bf16 v[114:117], v[168:171], v[176:179], v[114:117]
	v_mfma_f32_16x16x32_bf16 v[102:105], v[150:153], v[208:211], v[102:105]
	v_mfma_f32_16x16x32_bf16 v[98:101], v[168:171], v[208:211], v[98:101]
	v_mfma_f32_16x16x32_bf16 v[86:89], v[150:153], v[216:219], v[86:89]
	v_mfma_f32_16x16x32_bf16 v[82:85], v[168:171], v[216:219], v[82:85]
	v_mfma_f32_16x16x32_bf16 v[70:73], v[150:153], v[224:227], v[70:73]
	v_mfma_f32_16x16x32_bf16 v[66:69], v[168:171], v[224:227], v[66:69]
	s_barrier
	s_add_i32 s75, s75, s7
	v_lshl_add_u64 v[180:181], s[50:51], 0, v[0:1]
	s_mov_b32 m0, s75
	ds_read_b128 v[172:175], v185 offset:16384
	ds_read_b128 v[176:179], v185 offset:17408
	ds_read_b128 v[186:189], v185 offset:18432
	ds_read_b128 v[208:211], v185 offset:19456
	ds_read_b128 v[212:215], v185 offset:20480
	global_load_lds_dwordx4 v[180:181], off
	s_add_i32 m0, s75, 0x2000
	s_add_u32 vcc_lo, s50, 0x40000
	v_lshl_add_u64 v[190:191], s[50:51], 0, v[154:155]
	s_addc_u32 vcc_hi, s51, 0
	s_add_i32 s74, s74, s7
	global_load_lds_dwordx4 v[190:191], off
	v_lshl_add_u64 v[228:229], vcc, 0, v[0:1]
	s_mov_b32 m0, s74
	v_lshl_add_u64 v[230:231], s[76:77], 0, v[156:157]
	global_load_lds_dwordx4 v[228:229], off
	v_lshl_add_u64 v[228:229], vcc, 0, v[154:155]
	s_add_i32 m0, s74, 0x2000
	ds_read_b128 v[216:219], v185 offset:21504
	global_load_lds_dwordx4 v[228:229], off
	v_lshl_add_u64 v[228:229], s[76:77], 0, v[158:159]
	s_mov_b32 m0, s11
	ds_read_b128 v[220:223], v185 offset:22528
	global_load_lds_dwordx4 v[228:229], off
	s_mov_b32 m0, s12
	ds_read_b128 v[224:227], v185 offset:23552
	global_load_lds_dwordx4 v[230:231], off
	s_waitcnt vmcnt(8)
	s_waitcnt lgkmcnt(0)
	s_barrier
; #define PG8_STAGE(bufoff, gbase, voff) do { _Pragma("unroll") for (int _i = 0; _i < 2; ++_i) \
;         __builtin_amdgcn_global_load_lds((const unsigned*)((const char*)(gbase) + (voff)[_i]), (LAS unsigned*)(lds + (bufoff) + ldsw + _i * 8192), 16, 0, 0); } while (0)
; #define PG8_LDA(dst, b, h) do { _Pragma("unroll") for (int m = 0; m < 4; ++m) _Pragma("unroll") for (int k = 0; k < 2; ++k) dst[m][k] = *(const LAS bf16x8*)(lds + PG8_SA(b, h) + aoff + m * 2048 + k * 1024); } while (0)
; #define PG8_LDB(dst, b, h) do { _Pragma("unroll") for (int n = 0; n < 2; ++n) _Pragma("unroll") for (int k = 0; k < 2; ++k) dst[n][k] = *(const LAS bf16x8*)(lds + PG8_SB(b, h) + boff + n * 2048 + k * 1024); } while (0)
; #define PG8_MMA(ai, bj, At, Bt) do { __builtin_amdgcn_s_setprio(1); _Pragma("unroll") for (int m = 0; m < 4; ++m) _Pragma("unroll") for (int n = 0; n < 2; ++n) _Pragma("unroll") for (int k = 0; k < 2; ++k) \
;         acc[ai][bj][m][n] = __builtin_amdgcn_mfma_f32_16x16x32_bf16(Bt[n][k], At[m][k], acc[ai][bj][m][n], 0, 0, 0); __builtin_amdgcn_s_setprio(0); } while (0)
; #define PG8_WAIT_V(n) asm volatile("s_waitcnt vmcnt(" #n ")" ::: "memory")
; #define PG8_WAIT_L(n) asm volatile("s_waitcnt lgkmcnt(" #n ")" ::: "memory")
; #define PG8_BAR __builtin_amdgcn_s_barrier()
; #define PG8_SCHED __builtin_amdgcn_sched_barrier(0)
; template <class Epi, class Sched>
; __device__ __forceinline__ void gemm_phase(LAS unsigned char* lds, const Gemm g, const Sched& S, const Epi& E) {
;     ...
;             PG8_WAIT_V(8); PG8_WAIT_L(0); PG8_BAR; PG8_MMA(1, 0, At, B0); PG8_MMA(1, 1, At, B1); PG8_BAR; PG8_SCHED;
;             PG8_LDB(B0, 1, 0); PG8_LDB(B1, 1, 1); PG8_SCHED; PG8_LDA(At, 1, 0); PG8_STAGE(PG8_SA(0, 1), a2 + hsA, voffA);
;             PG8_WAIT_V(8); PG8_WAIT_L(0); PG8_BAR; PG8_MMA(0, 0, At, B0); PG8_MMA(0, 1, At, B1); PG8_BAR; PG8_SCHED;
	s_waitcnt lgkmcnt(0)
	v_mfma_f32_16x16x32_bf16 v[62:65], v[130:133], v[172:175], v[62:65]
	v_mfma_f32_16x16x32_bf16 v[58:61], v[138:141], v[172:175], v[58:61]
	v_mfma_f32_16x16x32_bf16 v[46:49], v[130:133], v[186:189], v[46:49]
	v_mfma_f32_16x16x32_bf16 v[42:45], v[138:141], v[186:189], v[42:45]
	v_mfma_f32_16x16x32_bf16 v[30:33], v[130:133], v[212:215], v[30:33]
	v_mfma_f32_16x16x32_bf16 v[26:29], v[138:141], v[212:215], v[26:29]
	v_mfma_f32_16x16x32_bf16 v[14:17], v[130:133], v[220:223], v[14:17]
	v_mfma_f32_16x16x32_bf16 v[10:13], v[138:141], v[220:223], v[10:13]
	v_mfma_f32_16x16x32_bf16 v[62:65], v[134:137], v[176:179], v[62:65]
	v_mfma_f32_16x16x32_bf16 v[58:61], v[142:145], v[176:179], v[58:61]
	v_mfma_f32_16x16x32_bf16 v[46:49], v[134:137], v[208:211], v[46:49]
	v_mfma_f32_16x16x32_bf16 v[42:45], v[142:145], v[208:211], v[42:45]
	v_mfma_f32_16x16x32_bf16 v[30:33], v[134:137], v[216:219], v[30:33]
	v_mfma_f32_16x16x32_bf16 v[26:29], v[142:145], v[216:219], v[26:29]
	v_mfma_f32_16x16x32_bf16 v[14:17], v[134:137], v[224:227], v[14:17]
	v_mfma_f32_16x16x32_bf16 v[10:13], v[142:145], v[224:227], v[10:13]
	v_mfma_f32_16x16x32_bf16 v[54:57], v[146:149], v[172:175], v[54:57]
	v_mfma_f32_16x16x32_bf16 v[50:53], v[164:167], v[172:175], v[50:53]
	v_mfma_f32_16x16x32_bf16 v[38:41], v[146:149], v[186:189], v[38:41]
	v_mfma_f32_16x16x32_bf16 v[34:37], v[164:167], v[186:189], v[34:37]
	v_mfma_f32_16x16x32_bf16 v[22:25], v[146:149], v[212:215], v[22:25]
	v_mfma_f32_16x16x32_bf16 v[18:21], v[164:167], v[212:215], v[18:21]
	v_mfma_f32_16x16x32_bf16 v[6:9], v[146:149], v[220:223], v[6:9]
	v_mfma_f32_16x16x32_bf16 v[2:5], v[164:167], v[220:223], v[2:5]
	v_mfma_f32_16x16x32_bf16 v[54:57], v[150:153], v[176:179], v[54:57]
	v_mfma_f32_16x16x32_bf16 v[50:53], v[168:171], v[176:179], v[50:53]
	v_mfma_f32_16x16x32_bf16 v[38:41], v[150:153], v[208:211], v[38:41]
	v_mfma_f32_16x16x32_bf16 v[34:37], v[168:171], v[208:211], v[34:37]
	v_mfma_f32_16x16x32_bf16 v[22:25], v[150:153], v[216:219], v[22:25]
	v_mfma_f32_16x16x32_bf16 v[18:21], v[168:171], v[216:219], v[18:21]
	v_mfma_f32_16x16x32_bf16 v[6:9], v[150:153], v[224:227], v[6:9]
	v_mfma_f32_16x16x32_bf16 v[2:5], v[168:171], v[224:227], v[2:5]
	s_barrier
	s_add_i32 s74, 0, 0x18000
	s_add_i32 s75, 0, 0x1c000
	v_add_u32_e32 v142, s74, v184
	v_add_u32_e32 v168, s75, v184
	ds_read_b128 v[130:133], v142
	ds_read_b128 v[134:137], v142 offset:1024
	ds_read_b128 v[138:141], v142 offset:2048
	ds_read_b128 v[142:145], v142 offset:3072
	ds_read_b128 v[146:149], v168
	ds_read_b128 v[150:153], v168 offset:1024
	ds_read_b128 v[164:167], v168 offset:2048
	ds_read_b128 v[168:171], v168 offset:3072
	s_add_u32 s76, s76, 0x40000
	s_addc_u32 s77, s77, 0
	s_mov_b32 m0, s16
	v_lshl_add_u64 v[232:233], s[76:77], 0, v[158:159]
	ds_read_b128 v[172:175], v185 offset:32768
	ds_read_b128 v[176:179], v185 offset:33792
	ds_read_b128 v[186:189], v185 offset:34816
	ds_read_b128 v[208:211], v185 offset:35840
	ds_read_b128 v[212:215], v185 offset:36864
	ds_read_b128 v[216:219], v185 offset:37888
	ds_read_b128 v[220:223], v185 offset:38912
	global_load_lds_dwordx4 v[232:233], off
	v_lshl_add_u64 v[232:233], s[76:77], 0, v[156:157]
	s_mov_b32 m0, s24
	ds_read_b128 v[224:227], v185 offset:39936
	global_load_lds_dwordx4 v[232:233], off
	s_waitcnt vmcnt(8)
	s_waitcnt lgkmcnt(0)
	s_barrier
	s_waitcnt lgkmcnt(0)
	v_mfma_f32_16x16x32_bf16 v[122:125], v[130:133], v[172:175], v[122:125]
	v_mfma_f32_16x16x32_bf16 v[126:129], v[138:141], v[172:175], v[126:129]
	v_mfma_f32_16x16x32_bf16 v[110:113], v[130:133], v[186:189], v[110:113]
	v_mfma_f32_16x16x32_bf16 v[106:109], v[138:141], v[186:189], v[106:109]
	v_mfma_f32_16x16x32_bf16 v[94:97], v[130:133], v[212:215], v[94:97]
	v_mfma_f32_16x16x32_bf16 v[90:93], v[138:141], v[212:215], v[90:93]
	v_mfma_f32_16x16x32_bf16 v[78:81], v[130:133], v[220:223], v[78:81]
	v_mfma_f32_16x16x32_bf16 v[74:77], v[138:141], v[220:223], v[74:77]
	v_mfma_f32_16x16x32_bf16 v[122:125], v[134:137], v[176:179], v[122:125]
	v_mfma_f32_16x16x32_bf16 v[126:129], v[142:145], v[176:179], v[126:129]
	v_mfma_f32_16x16x32_bf16 v[110:113], v[134:137], v[208:211], v[110:113]
	v_mfma_f32_16x16x32_bf16 v[106:109], v[142:145], v[208:211], v[106:109]
	v_mfma_f32_16x16x32_bf16 v[94:97], v[134:137], v[216:219], v[94:97]
	v_mfma_f32_16x16x32_bf16 v[90:93], v[142:145], v[216:219], v[90:93]
	v_mfma_f32_16x16x32_bf16 v[78:81], v[134:137], v[224:227], v[78:81]
	v_mfma_f32_16x16x32_bf16 v[74:77], v[142:145], v[224:227], v[74:77]
	v_mfma_f32_16x16x32_bf16 v[118:121], v[146:149], v[172:175], v[118:121]
	v_mfma_f32_16x16x32_bf16 v[114:117], v[164:167], v[172:175], v[114:117]
	v_mfma_f32_16x16x32_bf16 v[102:105], v[146:149], v[186:189], v[102:105]
	v_mfma_f32_16x16x32_bf16 v[98:101], v[164:167], v[186:189], v[98:101]
	v_mfma_f32_16x16x32_bf16 v[86:89], v[146:149], v[212:215], v[86:89]
	v_mfma_f32_16x16x32_bf16 v[82:85], v[164:167], v[212:215], v[82:85]
	v_mfma_f32_16x16x32_bf16 v[70:73], v[146:149], v[220:223], v[70:73]
	v_mfma_f32_16x16x32_bf16 v[66:69], v[164:167], v[220:223], v[66:69]
	v_mfma_f32_16x16x32_bf16 v[118:121], v[150:153], v[176:179], v[118:121]
	v_mfma_f32_16x16x32_bf16 v[114:117], v[168:171], v[176:179], v[114:117]
	v_mfma_f32_16x16x32_bf16 v[102:105], v[150:153], v[208:211], v[102:105]
	v_mfma_f32_16x16x32_bf16 v[98:101], v[168:171], v[208:211], v[98:101]
	v_mfma_f32_16x16x32_bf16 v[86:89], v[150:153], v[216:219], v[86:89]
	v_mfma_f32_16x16x32_bf16 v[82:85], v[168:171], v[216:219], v[82:85]
	v_mfma_f32_16x16x32_bf16 v[70:73], v[150:153], v[224:227], v[70:73]
	v_mfma_f32_16x16x32_bf16 v[66:69], v[168:171], v[224:227], v[66:69]
	s_barrier
; #define PG8_STAGE(bufoff, gbase, voff) do { _Pragma("unroll") for (int _i = 0; _i < 2; ++_i) \
;         __builtin_amdgcn_global_load_lds((const unsigned*)((const char*)(gbase) + (voff)[_i]), (LAS unsigned*)(lds + (bufoff) + ldsw + _i * 8192), 16, 0, 0); } while (0)
; #define PG8_LDA(dst, b, h) do { _Pragma("unroll") for (int m = 0; m < 4; ++m) _Pragma("unroll") for (int k = 0; k < 2; ++k) dst[m][k] = *(const LAS bf16x8*)(lds + PG8_SA(b, h) + aoff + m * 2048 + k * 1024); } while (0)
; #define PG8_MMA(ai, bj, At, Bt) do { __builtin_amdgcn_s_setprio(1); _Pragma("unroll") for (int m = 0; m < 4; ++m) _Pragma("unroll") for (int n = 0; n < 2; ++n) _Pragma("unroll") for (int k = 0; k < 2; ++k) \
;         acc[ai][bj][m][n] = __builtin_amdgcn_mfma_f32_16x16x32_bf16(Bt[n][k], At[m][k], acc[ai][bj][m][n], 0, 0, 0); __builtin_amdgcn_s_setprio(0); } while (0)
; #define PG8_WAIT_V(n) asm volatile("s_waitcnt vmcnt(" #n ")" ::: "memory")
; #define PG8_WAIT_L(n) asm volatile("s_waitcnt lgkmcnt(" #n ")" ::: "memory")
; #define PG8_BAR __builtin_amdgcn_s_barrier()
; #define PG8_SCHED __builtin_amdgcn_sched_barrier(0)
; template <class Epi, class Sched>
; __device__ __forceinline__ void gemm_phase(LAS unsigned char* lds, const Gemm g, const Sched& S, const Epi& E) {
;     ...
;             PG8_LDA(At, 1, 1); PG8_STAGE(PG8_SB(1, 0), b3, voffB); PG8_STAGE(PG8_SB(1, 1), b3 + hsB, voffB); PG8_STAGE(PG8_SA(1, 0), a3, voffA);
;             PG8_WAIT_V(8); PG8_WAIT_L(0); PG8_BAR; PG8_MMA(1, 0, At, B0); PG8_MMA(1, 1, At, B1); PG8_BAR; PG8_SCHED;
;         }
	s_add_i32 s74, s74, s7
	v_lshl_add_u64 v[180:181], v[180:181], 0, s[18:19]
	s_mov_b32 m0, s74
	ds_read_b128 v[172:175], v185 offset:49152
	ds_read_b128 v[176:179], v185 offset:50176
	ds_read_b128 v[186:189], v185 offset:51200
	ds_read_b128 v[208:211], v185 offset:52224
	global_load_lds_dwordx4 v[180:181], off
	s_add_i32 m0, s74, 0x2000
	s_add_u32 s50, s50, 0x40080
	v_lshl_add_u64 v[180:181], v[190:191], 0, s[18:19]
	s_addc_u32 s51, s51, 0
	s_add_i32 s74, s75, s7
	global_load_lds_dwordx4 v[180:181], off
	v_lshl_add_u64 v[180:181], s[50:51], 0, v[0:1]
	s_mov_b32 m0, s74
	ds_read_b128 v[212:215], v185 offset:53248
	global_load_lds_dwordx4 v[180:181], off
	v_lshl_add_u64 v[180:181], s[50:51], 0, v[154:155]
	s_add_i32 m0, s74, 0x2000
	ds_read_b128 v[216:219], v185 offset:54272
	global_load_lds_dwordx4 v[180:181], off
	v_lshl_add_u64 v[180:181], v[228:229], 0, s[18:19]
	s_mov_b32 m0, s57
	ds_read_b128 v[220:223], v185 offset:55296
	global_load_lds_dwordx4 v[180:181], off
	v_lshl_add_u64 v[180:181], v[230:231], 0, s[18:19]
	s_mov_b32 m0, s64
	ds_read_b128 v[224:227], v185 offset:56320
	global_load_lds_dwordx4 v[180:181], off
	s_waitcnt vmcnt(8)
	s_waitcnt lgkmcnt(0)
	s_barrier
	s_waitcnt lgkmcnt(0)
	v_mfma_f32_16x16x32_bf16 v[62:65], v[130:133], v[172:175], v[62:65]
	v_mfma_f32_16x16x32_bf16 v[58:61], v[138:141], v[172:175], v[58:61]
	v_mfma_f32_16x16x32_bf16 v[46:49], v[130:133], v[186:189], v[46:49]
	v_mfma_f32_16x16x32_bf16 v[42:45], v[138:141], v[186:189], v[42:45]
	v_mfma_f32_16x16x32_bf16 v[30:33], v[130:133], v[212:215], v[30:33]
	v_mfma_f32_16x16x32_bf16 v[26:29], v[138:141], v[212:215], v[26:29]
	v_mfma_f32_16x16x32_bf16 v[14:17], v[130:133], v[220:223], v[14:17]
	v_mfma_f32_16x16x32_bf16 v[10:13], v[138:141], v[220:223], v[10:13]
	v_mfma_f32_16x16x32_bf16 v[62:65], v[134:137], v[176:179], v[62:65]
	v_mfma_f32_16x16x32_bf16 v[58:61], v[142:145], v[176:179], v[58:61]
	v_mfma_f32_16x16x32_bf16 v[46:49], v[134:137], v[208:211], v[46:49]
	v_mfma_f32_16x16x32_bf16 v[42:45], v[142:145], v[208:211], v[42:45]
	v_mfma_f32_16x16x32_bf16 v[30:33], v[134:137], v[216:219], v[30:33]
	v_mfma_f32_16x16x32_bf16 v[26:29], v[142:145], v[216:219], v[26:29]
	v_mfma_f32_16x16x32_bf16 v[14:17], v[134:137], v[224:227], v[14:17]
	v_mfma_f32_16x16x32_bf16 v[10:13], v[142:145], v[224:227], v[10:13]
	v_mfma_f32_16x16x32_bf16 v[54:57], v[146:149], v[172:175], v[54:57]
	v_mfma_f32_16x16x32_bf16 v[50:53], v[164:167], v[172:175], v[50:53]
	v_mfma_f32_16x16x32_bf16 v[38:41], v[146:149], v[186:189], v[38:41]
	v_mfma_f32_16x16x32_bf16 v[34:37], v[164:167], v[186:189], v[34:37]
	v_mfma_f32_16x16x32_bf16 v[22:25], v[146:149], v[212:215], v[22:25]
	v_mfma_f32_16x16x32_bf16 v[18:21], v[164:167], v[212:215], v[18:21]
	v_mfma_f32_16x16x32_bf16 v[6:9], v[146:149], v[220:223], v[6:9]
	v_mfma_f32_16x16x32_bf16 v[2:5], v[164:167], v[220:223], v[2:5]
	v_mfma_f32_16x16x32_bf16 v[54:57], v[150:153], v[176:179], v[54:57]
	v_mfma_f32_16x16x32_bf16 v[50:53], v[168:171], v[176:179], v[50:53]
	v_mfma_f32_16x16x32_bf16 v[38:41], v[150:153], v[208:211], v[38:41]
	v_mfma_f32_16x16x32_bf16 v[34:37], v[168:171], v[208:211], v[34:37]
	v_mfma_f32_16x16x32_bf16 v[22:25], v[150:153], v[216:219], v[22:25]
	v_mfma_f32_16x16x32_bf16 v[18:21], v[168:171], v[216:219], v[18:21]
	v_mfma_f32_16x16x32_bf16 v[6:9], v[150:153], v[224:227], v[6:9]
	v_mfma_f32_16x16x32_bf16 v[2:5], v[168:171], v[224:227], v[2:5]
	s_barrier
	s_add_u32 s0, s0, 0x100
	s_addc_u32 s1, s1, 0
	s_add_u32 s84, s84, 0x100
	s_addc_u32 s85, s85, 0
	s_cmp_ge_i32 s96, s30
	s_mov_b32 s50, s96
	s_cbranch_scc0 .LBB0_912
	s_setprio 0
	v_readlane_b32 s82, v254, 45
	v_readlane_b32 s83, v254, 46
	v_readlane_b32 s96, v250, 43
